# peerq K-loops (gemm_tile1) also replaced by the hand-written LDS-DMA loop with rotated K start; all 10 GEMM K-loops now hand-written
# speedup vs baseline: 1.0368x; 1.0099x over previous
.LBB0_187:
	s_lshl_b32 s28, s67, 7
	s_ashr_i32 s29, s28, 31
	s_lshl_b64 s[26:27], s[28:29], 10
	s_lshl_b64 s[6:7], s[28:29], 11
	s_add_u32 s6, s23, s6
	s_addc_u32 s7, s33, s7
	s_ashr_i32 s25, s24, 31
	s_lshl_b64 s[8:9], s[24:25], 18
	s_add_u32 s8, s56, s8
	s_addc_u32 s9, s57, s9
	v_and_b32_e32 v200, 15, v0
	v_bfe_u32 v201, v0, 4, 2
	v_and_b32_e32 v161, 7, v200
	v_xor_b32_e32 v201, v201, v161
	v_lshlrev_b32_e32 v201, 4, v201
	v_lshl_or_b32 v201, v200, 7, v201
	v_bfe_u32 v200, v0, 7, 1
	v_lshl_or_b32 v130, v200, 13, v201
	v_bfe_u32 v200, v0, 6, 1
	v_lshl_or_b32 v194, v200, 13, v201
	v_or_b32_e32 v194, 0x4000, v194
	v_xor_b32_e32 v161, 64, v130
	v_xor_b32_e32 v195, 64, v194
	v_bfe_u32 v200, v0, 3, 3
	v_and_b32_e32 v201, 7, v0
	v_xor_b32_e32 v201, v201, v200
	v_lshlrev_b32_e32 v201, 4, v201
	v_lshl_or_b32 v201, v200, 11, v201
	v_lshrrev_b32_e32 v200, 6, v0
	v_and_b32_e32 v200, 3, v200
	v_lshl_or_b32 v196, v200, 16, v201
	v_add_u32_e32 v197, 0x3c00, v196
	v_add_u32_e32 v198, 0x7800, v196
	v_add_u32_e32 v199, 0xb400, v196
	v_lshlrev_b32_e32 v200, 12, v200
	s_nop 0
	v_readfirstlane_b32 s14, v200
	s_add_u32 s14, s14, 32
	v_mov_b32_e32 v94, 0
	v_mov_b32_e32 v95, 0
	v_mov_b32_e32 v96, 0
	v_mov_b32_e32 v97, 0
	v_mov_b32_e32 v90, 0
	v_mov_b32_e32 v91, 0
	v_mov_b32_e32 v92, 0
	v_mov_b32_e32 v93, 0
	v_mov_b32_e32 v86, 0
	v_mov_b32_e32 v87, 0
	v_mov_b32_e32 v88, 0
	v_mov_b32_e32 v89, 0
	v_mov_b32_e32 v82, 0
	v_mov_b32_e32 v83, 0
	v_mov_b32_e32 v84, 0
	v_mov_b32_e32 v85, 0
	v_mov_b32_e32 v74, 0
	v_mov_b32_e32 v75, 0
	v_mov_b32_e32 v76, 0
	v_mov_b32_e32 v77, 0
	v_mov_b32_e32 v70, 0
	v_mov_b32_e32 v71, 0
	v_mov_b32_e32 v72, 0
	v_mov_b32_e32 v73, 0
	v_mov_b32_e32 v66, 0
	v_mov_b32_e32 v67, 0
	v_mov_b32_e32 v68, 0
	v_mov_b32_e32 v69, 0
	v_mov_b32_e32 v62, 0
	v_mov_b32_e32 v63, 0
	v_mov_b32_e32 v64, 0
	v_mov_b32_e32 v65, 0
	v_mov_b32_e32 v54, 0
	v_mov_b32_e32 v55, 0
	v_mov_b32_e32 v56, 0
	v_mov_b32_e32 v57, 0
	v_mov_b32_e32 v34, 0
	v_mov_b32_e32 v35, 0
	v_mov_b32_e32 v36, 0
	v_mov_b32_e32 v37, 0
	v_mov_b32_e32 v18, 0
	v_mov_b32_e32 v19, 0
	v_mov_b32_e32 v20, 0
	v_mov_b32_e32 v21, 0
	v_mov_b32_e32 v14, 0
	v_mov_b32_e32 v15, 0
	v_mov_b32_e32 v16, 0
	v_mov_b32_e32 v17, 0
	v_mov_b32_e32 v10, 0
	v_mov_b32_e32 v11, 0
	v_mov_b32_e32 v12, 0
	v_mov_b32_e32 v13, 0
	v_mov_b32_e32 v6, 0
	v_mov_b32_e32 v7, 0
	v_mov_b32_e32 v8, 0
	v_mov_b32_e32 v9, 0
	v_mov_b32_e32 v2, 0
	v_mov_b32_e32 v3, 0
	v_mov_b32_e32 v4, 0
	v_mov_b32_e32 v5, 0
	v_mov_b32_e32 v78, 0
	v_mov_b32_e32 v79, 0
	v_mov_b32_e32 v80, 0
	v_mov_b32_e32 v81, 0
	v_mov_b32_e32 v98, 0
	v_mov_b32_e32 v99, 0
	v_mov_b32_e32 v100, 0
	v_mov_b32_e32 v101, 0
	v_mov_b32_e32 v102, 0
	v_mov_b32_e32 v103, 0
	v_mov_b32_e32 v104, 0
	v_mov_b32_e32 v105, 0
	v_mov_b32_e32 v106, 0
	v_mov_b32_e32 v107, 0
	v_mov_b32_e32 v108, 0
	v_mov_b32_e32 v109, 0
	v_mov_b32_e32 v110, 0
	v_mov_b32_e32 v111, 0
	v_mov_b32_e32 v112, 0
	v_mov_b32_e32 v113, 0
	v_mov_b32_e32 v114, 0
	v_mov_b32_e32 v115, 0
	v_mov_b32_e32 v116, 0
	v_mov_b32_e32 v117, 0
	v_mov_b32_e32 v118, 0
	v_mov_b32_e32 v119, 0
	v_mov_b32_e32 v120, 0
	v_mov_b32_e32 v121, 0
	v_mov_b32_e32 v122, 0
	v_mov_b32_e32 v123, 0
	v_mov_b32_e32 v124, 0
	v_mov_b32_e32 v125, 0
	v_mov_b32_e32 v126, 0
	v_mov_b32_e32 v127, 0
	v_mov_b32_e32 v128, 0
	v_mov_b32_e32 v129, 0
	s_waitcnt lgkmcnt(0)
	s_barrier
	v_readlane_b32 s98, v255, 16
	s_lshr_b32 s98, s98, 3
	s_and_b32 s98, s98, 3
	s_lshl_b32 s98, s98, 2
	s_lshl_b32 s99, s98, 7
	s_add_u32 s6, s6, s99
	s_addc_u32 s7, s7, 0
	s_add_u32 s8, s8, s99
	s_addc_u32 s9, s9, 0
	s_add_u32 m0, s14, 0
	s_nop 0
	global_load_lds_dwordx4 v196, s[6:7] offset:0
	global_load_lds_dwordx4 v197, s[6:7] offset:1024
	global_load_lds_dwordx4 v198, s[6:7] offset:2048
	global_load_lds_dwordx4 v199, s[6:7] offset:3072
	s_add_u32 m0, s14, 16384
	s_nop 0
	global_load_lds_dwordx4 v196, s[8:9] offset:0
	global_load_lds_dwordx4 v197, s[8:9] offset:1024
	global_load_lds_dwordx4 v198, s[8:9] offset:2048
	global_load_lds_dwordx4 v199, s[8:9] offset:3072
	s_add_u32 s98, s98, 1
	s_and_b32 s98, s98, 15
	s_cmp_eq_u32 s98, 0
	s_cselect_b32 s99, 0x800, 0
	s_add_u32 s6, s6, 0x80
	s_addc_u32 s7, s7, 0
	s_sub_u32 s6, s6, s99
	s_subb_u32 s7, s7, 0
	s_add_u32 s8, s8, 0x80
	s_addc_u32 s9, s9, 0
	s_sub_u32 s8, s8, s99
	s_subb_u32 s9, s9, 0
	s_mov_b32 s25, 0
	s_waitcnt vmcnt(0)
.Lk_g1l0_loop:
	s_barrier
	s_add_u32 m0, s14, 32768
	v_mfma_f32_16x16x32_bf16 v[94:97], v[98:101], v[114:117], v[94:97]
	ds_read_b128 v[22:25], v130 offset:32
	global_load_lds_dwordx4 v196, s[6:7] offset:0
	v_mfma_f32_16x16x32_bf16 v[90:93], v[98:101], v[118:121], v[90:93]
	ds_read_b128 v[42:45], v194 offset:32
	global_load_lds_dwordx4 v197, s[6:7] offset:1024
	v_mfma_f32_16x16x32_bf16 v[86:89], v[98:101], v[122:125], v[86:89]
	ds_read_b128 v[46:49], v194 offset:2080
	global_load_lds_dwordx4 v198, s[6:7] offset:2048
	v_mfma_f32_16x16x32_bf16 v[82:85], v[98:101], v[126:129], v[82:85]
	ds_read_b128 v[26:29], v130 offset:2080
	global_load_lds_dwordx4 v199, s[6:7] offset:3072
	s_add_u32 m0, s14, 49152
	v_mfma_f32_16x16x32_bf16 v[74:77], v[102:105], v[114:117], v[74:77]
	ds_read_b128 v[50:53], v194 offset:4128
	global_load_lds_dwordx4 v196, s[8:9] offset:0
	v_mfma_f32_16x16x32_bf16 v[70:73], v[102:105], v[118:121], v[70:73]
	ds_read_b128 v[58:61], v194 offset:6176
	global_load_lds_dwordx4 v197, s[8:9] offset:1024
	v_mfma_f32_16x16x32_bf16 v[66:69], v[102:105], v[122:125], v[66:69]
	ds_read_b128 v[30:33], v130 offset:4128
	global_load_lds_dwordx4 v198, s[8:9] offset:2048
	v_mfma_f32_16x16x32_bf16 v[62:65], v[102:105], v[126:129], v[62:65]
	ds_read_b128 v[38:41], v130 offset:6176
	global_load_lds_dwordx4 v199, s[8:9] offset:3072
	v_mfma_f32_16x16x32_bf16 v[54:57], v[106:109], v[114:117], v[54:57]
	v_mfma_f32_16x16x32_bf16 v[34:37], v[106:109], v[118:121], v[34:37]
	v_mfma_f32_16x16x32_bf16 v[18:21], v[106:109], v[122:125], v[18:21]
	v_mfma_f32_16x16x32_bf16 v[14:17], v[106:109], v[126:129], v[14:17]
	v_mfma_f32_16x16x32_bf16 v[10:13], v[110:113], v[114:117], v[10:13]
	v_mfma_f32_16x16x32_bf16 v[6:9], v[110:113], v[118:121], v[6:9]
	v_mfma_f32_16x16x32_bf16 v[2:5], v[110:113], v[122:125], v[2:5]
	v_mfma_f32_16x16x32_bf16 v[78:81], v[110:113], v[126:129], v[78:81]
	s_add_u32 s98, s98, 1
	s_and_b32 s98, s98, 15
	s_cmp_eq_u32 s98, 0
	s_cselect_b32 s99, 0x800, 0
	s_add_u32 s6, s6, 0x80
	s_addc_u32 s7, s7, 0
	s_sub_u32 s6, s6, s99
	s_subb_u32 s7, s7, 0
	s_add_u32 s8, s8, 0x80
	s_addc_u32 s9, s9, 0
	s_sub_u32 s8, s8, s99
	s_subb_u32 s9, s9, 0
	s_waitcnt lgkmcnt(0)
	v_mfma_f32_16x16x32_bf16 v[94:97], v[22:25], v[42:45], v[94:97]
	ds_read_b128 v[98:101], v161 offset:32
	v_mfma_f32_16x16x32_bf16 v[90:93], v[22:25], v[46:49], v[90:93]
	ds_read_b128 v[114:117], v195 offset:32
	v_mfma_f32_16x16x32_bf16 v[86:89], v[22:25], v[50:53], v[86:89]
	ds_read_b128 v[118:121], v195 offset:2080
	v_mfma_f32_16x16x32_bf16 v[82:85], v[22:25], v[58:61], v[82:85]
	ds_read_b128 v[102:105], v161 offset:2080
	v_mfma_f32_16x16x32_bf16 v[74:77], v[26:29], v[42:45], v[74:77]
	ds_read_b128 v[122:125], v195 offset:4128
	v_mfma_f32_16x16x32_bf16 v[70:73], v[26:29], v[46:49], v[70:73]
	ds_read_b128 v[126:129], v195 offset:6176
	v_mfma_f32_16x16x32_bf16 v[66:69], v[26:29], v[50:53], v[66:69]
	ds_read_b128 v[106:109], v161 offset:4128
	v_mfma_f32_16x16x32_bf16 v[62:65], v[26:29], v[58:61], v[62:65]
	ds_read_b128 v[110:113], v161 offset:6176
	v_mfma_f32_16x16x32_bf16 v[54:57], v[30:33], v[42:45], v[54:57]
	v_mfma_f32_16x16x32_bf16 v[34:37], v[30:33], v[46:49], v[34:37]
	v_mfma_f32_16x16x32_bf16 v[18:21], v[30:33], v[50:53], v[18:21]
	v_mfma_f32_16x16x32_bf16 v[14:17], v[30:33], v[58:61], v[14:17]
	v_mfma_f32_16x16x32_bf16 v[10:13], v[38:41], v[42:45], v[10:13]
	v_mfma_f32_16x16x32_bf16 v[6:9], v[38:41], v[46:49], v[6:9]
	v_mfma_f32_16x16x32_bf16 v[2:5], v[38:41], v[50:53], v[2:5]
	v_mfma_f32_16x16x32_bf16 v[78:81], v[38:41], v[58:61], v[78:81]
	s_waitcnt lgkmcnt(0)
	s_waitcnt vmcnt(0)
	s_barrier
	s_add_u32 m0, s14, 0
	v_mfma_f32_16x16x32_bf16 v[94:97], v[98:101], v[114:117], v[94:97]
	ds_read_b128 v[22:25], v130 offset:32800
	global_load_lds_dwordx4 v196, s[6:7] offset:0
	v_mfma_f32_16x16x32_bf16 v[90:93], v[98:101], v[118:121], v[90:93]
	ds_read_b128 v[42:45], v194 offset:32800
	global_load_lds_dwordx4 v197, s[6:7] offset:1024
	v_mfma_f32_16x16x32_bf16 v[86:89], v[98:101], v[122:125], v[86:89]
	ds_read_b128 v[46:49], v194 offset:34848
	global_load_lds_dwordx4 v198, s[6:7] offset:2048
	v_mfma_f32_16x16x32_bf16 v[82:85], v[98:101], v[126:129], v[82:85]
	ds_read_b128 v[26:29], v130 offset:34848
	global_load_lds_dwordx4 v199, s[6:7] offset:3072
	s_add_u32 m0, s14, 16384
	v_mfma_f32_16x16x32_bf16 v[74:77], v[102:105], v[114:117], v[74:77]
	ds_read_b128 v[50:53], v194 offset:36896
	global_load_lds_dwordx4 v196, s[8:9] offset:0
	v_mfma_f32_16x16x32_bf16 v[70:73], v[102:105], v[118:121], v[70:73]
	ds_read_b128 v[58:61], v194 offset:38944
	global_load_lds_dwordx4 v197, s[8:9] offset:1024
	v_mfma_f32_16x16x32_bf16 v[66:69], v[102:105], v[122:125], v[66:69]
	ds_read_b128 v[30:33], v130 offset:36896
	global_load_lds_dwordx4 v198, s[8:9] offset:2048
	v_mfma_f32_16x16x32_bf16 v[62:65], v[102:105], v[126:129], v[62:65]
	ds_read_b128 v[38:41], v130 offset:38944
	global_load_lds_dwordx4 v199, s[8:9] offset:3072
	v_mfma_f32_16x16x32_bf16 v[54:57], v[106:109], v[114:117], v[54:57]
	v_mfma_f32_16x16x32_bf16 v[34:37], v[106:109], v[118:121], v[34:37]
	v_mfma_f32_16x16x32_bf16 v[18:21], v[106:109], v[122:125], v[18:21]
	v_mfma_f32_16x16x32_bf16 v[14:17], v[106:109], v[126:129], v[14:17]
	v_mfma_f32_16x16x32_bf16 v[10:13], v[110:113], v[114:117], v[10:13]
	v_mfma_f32_16x16x32_bf16 v[6:9], v[110:113], v[118:121], v[6:9]
	v_mfma_f32_16x16x32_bf16 v[2:5], v[110:113], v[122:125], v[2:5]
	v_mfma_f32_16x16x32_bf16 v[78:81], v[110:113], v[126:129], v[78:81]
	s_add_u32 s98, s98, 1
	s_and_b32 s98, s98, 15
	s_cmp_eq_u32 s98, 0
	s_cselect_b32 s99, 0x800, 0
	s_add_u32 s6, s6, 0x80
	s_addc_u32 s7, s7, 0
	s_sub_u32 s6, s6, s99
	s_subb_u32 s7, s7, 0
	s_add_u32 s8, s8, 0x80
	s_addc_u32 s9, s9, 0
	s_sub_u32 s8, s8, s99
	s_subb_u32 s9, s9, 0
	s_waitcnt lgkmcnt(0)
	v_mfma_f32_16x16x32_bf16 v[94:97], v[22:25], v[42:45], v[94:97]
	ds_read_b128 v[98:101], v161 offset:32800
	v_mfma_f32_16x16x32_bf16 v[90:93], v[22:25], v[46:49], v[90:93]
	ds_read_b128 v[114:117], v195 offset:32800
	v_mfma_f32_16x16x32_bf16 v[86:89], v[22:25], v[50:53], v[86:89]
	ds_read_b128 v[118:121], v195 offset:34848
	v_mfma_f32_16x16x32_bf16 v[82:85], v[22:25], v[58:61], v[82:85]
	ds_read_b128 v[102:105], v161 offset:34848
	v_mfma_f32_16x16x32_bf16 v[74:77], v[26:29], v[42:45], v[74:77]
	ds_read_b128 v[122:125], v195 offset:36896
	v_mfma_f32_16x16x32_bf16 v[70:73], v[26:29], v[46:49], v[70:73]
	ds_read_b128 v[126:129], v195 offset:38944
	v_mfma_f32_16x16x32_bf16 v[66:69], v[26:29], v[50:53], v[66:69]
	ds_read_b128 v[106:109], v161 offset:36896
	v_mfma_f32_16x16x32_bf16 v[62:65], v[26:29], v[58:61], v[62:65]
	ds_read_b128 v[110:113], v161 offset:38944
	v_mfma_f32_16x16x32_bf16 v[54:57], v[30:33], v[42:45], v[54:57]
	v_mfma_f32_16x16x32_bf16 v[34:37], v[30:33], v[46:49], v[34:37]
	v_mfma_f32_16x16x32_bf16 v[18:21], v[30:33], v[50:53], v[18:21]
	v_mfma_f32_16x16x32_bf16 v[14:17], v[30:33], v[58:61], v[14:17]
	v_mfma_f32_16x16x32_bf16 v[10:13], v[38:41], v[42:45], v[10:13]
	v_mfma_f32_16x16x32_bf16 v[6:9], v[38:41], v[46:49], v[6:9]
	v_mfma_f32_16x16x32_bf16 v[2:5], v[38:41], v[50:53], v[2:5]
	v_mfma_f32_16x16x32_bf16 v[78:81], v[38:41], v[58:61], v[78:81]
	s_waitcnt lgkmcnt(0)
	s_waitcnt vmcnt(0)
	s_add_u32 s25, s25, 1
	s_cmp_lt_u32 s25, 7
	s_cbranch_scc1 .Lk_g1l0_loop
	s_barrier
	s_add_u32 m0, s14, 32768
	v_mfma_f32_16x16x32_bf16 v[94:97], v[98:101], v[114:117], v[94:97]
	ds_read_b128 v[22:25], v130 offset:32
	global_load_lds_dwordx4 v196, s[6:7] offset:0
	v_mfma_f32_16x16x32_bf16 v[90:93], v[98:101], v[118:121], v[90:93]
	ds_read_b128 v[42:45], v194 offset:32
	global_load_lds_dwordx4 v197, s[6:7] offset:1024
	v_mfma_f32_16x16x32_bf16 v[86:89], v[98:101], v[122:125], v[86:89]
	ds_read_b128 v[46:49], v194 offset:2080
	global_load_lds_dwordx4 v198, s[6:7] offset:2048
	v_mfma_f32_16x16x32_bf16 v[82:85], v[98:101], v[126:129], v[82:85]
	ds_read_b128 v[26:29], v130 offset:2080
	global_load_lds_dwordx4 v199, s[6:7] offset:3072
	s_add_u32 m0, s14, 49152
	v_mfma_f32_16x16x32_bf16 v[74:77], v[102:105], v[114:117], v[74:77]
	ds_read_b128 v[50:53], v194 offset:4128
	global_load_lds_dwordx4 v196, s[8:9] offset:0
	v_mfma_f32_16x16x32_bf16 v[70:73], v[102:105], v[118:121], v[70:73]
	ds_read_b128 v[58:61], v194 offset:6176
	global_load_lds_dwordx4 v197, s[8:9] offset:1024
	v_mfma_f32_16x16x32_bf16 v[66:69], v[102:105], v[122:125], v[66:69]
	ds_read_b128 v[30:33], v130 offset:4128
	global_load_lds_dwordx4 v198, s[8:9] offset:2048
	v_mfma_f32_16x16x32_bf16 v[62:65], v[102:105], v[126:129], v[62:65]
	ds_read_b128 v[38:41], v130 offset:6176
	global_load_lds_dwordx4 v199, s[8:9] offset:3072
	v_mfma_f32_16x16x32_bf16 v[54:57], v[106:109], v[114:117], v[54:57]
	v_mfma_f32_16x16x32_bf16 v[34:37], v[106:109], v[118:121], v[34:37]
	v_mfma_f32_16x16x32_bf16 v[18:21], v[106:109], v[122:125], v[18:21]
	v_mfma_f32_16x16x32_bf16 v[14:17], v[106:109], v[126:129], v[14:17]
	v_mfma_f32_16x16x32_bf16 v[10:13], v[110:113], v[114:117], v[10:13]
	v_mfma_f32_16x16x32_bf16 v[6:9], v[110:113], v[118:121], v[6:9]
	v_mfma_f32_16x16x32_bf16 v[2:5], v[110:113], v[122:125], v[2:5]
	v_mfma_f32_16x16x32_bf16 v[78:81], v[110:113], v[126:129], v[78:81]
	s_add_u32 s98, s98, 1
	s_and_b32 s98, s98, 15
	s_cmp_eq_u32 s98, 0
	s_cselect_b32 s99, 0x800, 0
	s_add_u32 s6, s6, 0x80
	s_addc_u32 s7, s7, 0
	s_sub_u32 s6, s6, s99
	s_subb_u32 s7, s7, 0
	s_add_u32 s8, s8, 0x80
	s_addc_u32 s9, s9, 0
	s_sub_u32 s8, s8, s99
	s_subb_u32 s9, s9, 0
	s_waitcnt lgkmcnt(0)
	v_mfma_f32_16x16x32_bf16 v[94:97], v[22:25], v[42:45], v[94:97]
	ds_read_b128 v[98:101], v161 offset:32
	v_mfma_f32_16x16x32_bf16 v[90:93], v[22:25], v[46:49], v[90:93]
	ds_read_b128 v[114:117], v195 offset:32
	v_mfma_f32_16x16x32_bf16 v[86:89], v[22:25], v[50:53], v[86:89]
	ds_read_b128 v[118:121], v195 offset:2080
	v_mfma_f32_16x16x32_bf16 v[82:85], v[22:25], v[58:61], v[82:85]
	ds_read_b128 v[102:105], v161 offset:2080
	v_mfma_f32_16x16x32_bf16 v[74:77], v[26:29], v[42:45], v[74:77]
	ds_read_b128 v[122:125], v195 offset:4128
	v_mfma_f32_16x16x32_bf16 v[70:73], v[26:29], v[46:49], v[70:73]
	ds_read_b128 v[126:129], v195 offset:6176
	v_mfma_f32_16x16x32_bf16 v[66:69], v[26:29], v[50:53], v[66:69]
	ds_read_b128 v[106:109], v161 offset:4128
	v_mfma_f32_16x16x32_bf16 v[62:65], v[26:29], v[58:61], v[62:65]
	ds_read_b128 v[110:113], v161 offset:6176
	v_mfma_f32_16x16x32_bf16 v[54:57], v[30:33], v[42:45], v[54:57]
	v_mfma_f32_16x16x32_bf16 v[34:37], v[30:33], v[46:49], v[34:37]
	v_mfma_f32_16x16x32_bf16 v[18:21], v[30:33], v[50:53], v[18:21]
	v_mfma_f32_16x16x32_bf16 v[14:17], v[30:33], v[58:61], v[14:17]
	v_mfma_f32_16x16x32_bf16 v[10:13], v[38:41], v[42:45], v[10:13]
	v_mfma_f32_16x16x32_bf16 v[6:9], v[38:41], v[46:49], v[6:9]
	v_mfma_f32_16x16x32_bf16 v[2:5], v[38:41], v[50:53], v[2:5]
	v_mfma_f32_16x16x32_bf16 v[78:81], v[38:41], v[58:61], v[78:81]
	s_waitcnt lgkmcnt(0)
	s_waitcnt vmcnt(0)
	s_barrier
	v_mfma_f32_16x16x32_bf16 v[94:97], v[98:101], v[114:117], v[94:97]
	ds_read_b128 v[22:25], v130 offset:32800
	v_mfma_f32_16x16x32_bf16 v[90:93], v[98:101], v[118:121], v[90:93]
	ds_read_b128 v[42:45], v194 offset:32800
	v_mfma_f32_16x16x32_bf16 v[86:89], v[98:101], v[122:125], v[86:89]
	ds_read_b128 v[46:49], v194 offset:34848
	v_mfma_f32_16x16x32_bf16 v[82:85], v[98:101], v[126:129], v[82:85]
	ds_read_b128 v[26:29], v130 offset:34848
	v_mfma_f32_16x16x32_bf16 v[74:77], v[102:105], v[114:117], v[74:77]
	ds_read_b128 v[50:53], v194 offset:36896
	v_mfma_f32_16x16x32_bf16 v[70:73], v[102:105], v[118:121], v[70:73]
	ds_read_b128 v[58:61], v194 offset:38944
	v_mfma_f32_16x16x32_bf16 v[66:69], v[102:105], v[122:125], v[66:69]
	ds_read_b128 v[30:33], v130 offset:36896
	v_mfma_f32_16x16x32_bf16 v[62:65], v[102:105], v[126:129], v[62:65]
	ds_read_b128 v[38:41], v130 offset:38944
	v_mfma_f32_16x16x32_bf16 v[54:57], v[106:109], v[114:117], v[54:57]
	v_mfma_f32_16x16x32_bf16 v[34:37], v[106:109], v[118:121], v[34:37]
	v_mfma_f32_16x16x32_bf16 v[18:21], v[106:109], v[122:125], v[18:21]
	v_mfma_f32_16x16x32_bf16 v[14:17], v[106:109], v[126:129], v[14:17]
	v_mfma_f32_16x16x32_bf16 v[10:13], v[110:113], v[114:117], v[10:13]
	v_mfma_f32_16x16x32_bf16 v[6:9], v[110:113], v[118:121], v[6:9]
	v_mfma_f32_16x16x32_bf16 v[2:5], v[110:113], v[122:125], v[2:5]
	v_mfma_f32_16x16x32_bf16 v[78:81], v[110:113], v[126:129], v[78:81]
	s_waitcnt lgkmcnt(0)
	v_mfma_f32_16x16x32_bf16 v[94:97], v[22:25], v[42:45], v[94:97]
	ds_read_b128 v[98:101], v161 offset:32800
	v_mfma_f32_16x16x32_bf16 v[90:93], v[22:25], v[46:49], v[90:93]
	ds_read_b128 v[114:117], v195 offset:32800
	v_mfma_f32_16x16x32_bf16 v[86:89], v[22:25], v[50:53], v[86:89]
	ds_read_b128 v[118:121], v195 offset:34848
	v_mfma_f32_16x16x32_bf16 v[82:85], v[22:25], v[58:61], v[82:85]
	ds_read_b128 v[102:105], v161 offset:34848
	v_mfma_f32_16x16x32_bf16 v[74:77], v[26:29], v[42:45], v[74:77]
	ds_read_b128 v[122:125], v195 offset:36896
	v_mfma_f32_16x16x32_bf16 v[70:73], v[26:29], v[46:49], v[70:73]
	ds_read_b128 v[126:129], v195 offset:38944
	v_mfma_f32_16x16x32_bf16 v[66:69], v[26:29], v[50:53], v[66:69]
	ds_read_b128 v[106:109], v161 offset:36896
	v_mfma_f32_16x16x32_bf16 v[62:65], v[26:29], v[58:61], v[62:65]
	ds_read_b128 v[110:113], v161 offset:38944
	v_mfma_f32_16x16x32_bf16 v[54:57], v[30:33], v[42:45], v[54:57]
	v_mfma_f32_16x16x32_bf16 v[34:37], v[30:33], v[46:49], v[34:37]
	v_mfma_f32_16x16x32_bf16 v[18:21], v[30:33], v[50:53], v[18:21]
	v_mfma_f32_16x16x32_bf16 v[14:17], v[30:33], v[58:61], v[14:17]
	v_mfma_f32_16x16x32_bf16 v[10:13], v[38:41], v[42:45], v[10:13]
	v_mfma_f32_16x16x32_bf16 v[6:9], v[38:41], v[46:49], v[6:9]
	v_mfma_f32_16x16x32_bf16 v[2:5], v[38:41], v[50:53], v[2:5]
	v_mfma_f32_16x16x32_bf16 v[78:81], v[38:41], v[58:61], v[78:81]
	s_waitcnt lgkmcnt(0)
	v_mfma_f32_16x16x32_bf16 v[94:97], v[98:101], v[114:117], v[94:97]
	v_mfma_f32_16x16x32_bf16 v[90:93], v[98:101], v[118:121], v[90:93]
	v_mfma_f32_16x16x32_bf16 v[86:89], v[98:101], v[122:125], v[86:89]
	v_mfma_f32_16x16x32_bf16 v[82:85], v[98:101], v[126:129], v[82:85]
	v_mfma_f32_16x16x32_bf16 v[74:77], v[102:105], v[114:117], v[74:77]
	v_mfma_f32_16x16x32_bf16 v[70:73], v[102:105], v[118:121], v[70:73]
	v_mfma_f32_16x16x32_bf16 v[66:69], v[102:105], v[122:125], v[66:69]
	v_mfma_f32_16x16x32_bf16 v[62:65], v[102:105], v[126:129], v[62:65]
	v_mfma_f32_16x16x32_bf16 v[54:57], v[106:109], v[114:117], v[54:57]
	v_mfma_f32_16x16x32_bf16 v[34:37], v[106:109], v[118:121], v[34:37]
	v_mfma_f32_16x16x32_bf16 v[18:21], v[106:109], v[122:125], v[18:21]
	v_mfma_f32_16x16x32_bf16 v[14:17], v[106:109], v[126:129], v[14:17]
	v_mfma_f32_16x16x32_bf16 v[10:13], v[110:113], v[114:117], v[10:13]
	v_mfma_f32_16x16x32_bf16 v[6:9], v[110:113], v[118:121], v[6:9]
	v_mfma_f32_16x16x32_bf16 v[2:5], v[110:113], v[122:125], v[2:5]
	v_mfma_f32_16x16x32_bf16 v[78:81], v[110:113], v[126:129], v[78:81]
	s_waitcnt vmcnt(7)
	v_add_u32_e32 v22, 0x400, v168
	s_barrier
	ds_write2_b32 v168, v94, v90 offset1:16
	ds_write2_b32 v168, v95, v91 offset0:132 offset1:148
	ds_write2_b32 v22, v96, v92 offset0:8 offset1:24
	ds_write2_b32 v22, v97, v93 offset0:140 offset1:156
	ds_write2_b32 v168, v86, v82 offset0:32 offset1:48
	ds_write2_b32 v168, v87, v83 offset0:164 offset1:180
	ds_write2_b32 v22, v88, v84 offset0:40 offset1:56
	ds_write2_b32 v22, v89, v85 offset0:172 offset1:188
	v_add_u32_e32 v22, 0x2000, v168
	v_add_u32_e32 v23, 0x2400, v168
	s_cmp_gt_i32 s67, 63
	ds_write2_b32 v22, v74, v70 offset0:64 offset1:80
	ds_write2_b32 v22, v75, v71 offset0:196 offset1:212
	ds_write2_b32 v23, v76, v72 offset0:72 offset1:88
	ds_write2_b32 v23, v77, v73 offset0:204 offset1:220
	ds_write2_b32 v22, v66, v62 offset0:96 offset1:112
	ds_write2_b32 v22, v67, v63 offset0:228 offset1:244
	ds_write2_b32 v23, v68, v64 offset0:104 offset1:120
	ds_write2_b32 v23, v69, v65 offset0:236 offset1:252
	v_add_u32_e32 v22, 0x4000, v168
	v_add_u32_e32 v23, 0x4400, v168
	v_add_u32_e32 v24, 0x4800, v168
	s_cselect_b64 s[34:35], -1, 0
	s_cmp_lt_i32 s67, 64
	ds_write2_b32 v22, v54, v34 offset0:128 offset1:144
	ds_write2_b32 v23, v55, v35 offset0:4 offset1:20
	ds_write2_b32 v23, v56, v36 offset0:136 offset1:152
	ds_write2_b32 v24, v57, v37 offset0:12 offset1:28
	ds_write2_b32 v22, v18, v14 offset0:160 offset1:176
	ds_write2_b32 v23, v19, v15 offset0:36 offset1:52
	ds_write2_b32 v23, v20, v16 offset0:168 offset1:184
	ds_write2_b32 v24, v21, v17 offset0:44 offset1:60
	v_add_u32_e32 v14, 0x6000, v168
	s_cselect_b64 s[46:47], -1, 0
	s_add_i32 s6, s28, 0xffffe000
	ds_write2_b32 v14, v10, v6 offset0:192 offset1:208
	v_add_u32_e32 v6, 0x6400, v168
	s_lshr_b32 s68, s6, 10
	s_ashr_i32 s30, s67, 1
	s_and_b32 s69, s28, 0x380
	s_and_b32 s25, s28, 0x80
	ds_write2_b32 v6, v11, v7 offset0:68 offset1:84
	ds_write2_b32 v6, v12, v8 offset0:200 offset1:216
	v_add_u32_e32 v7, 0x6800, v168
	v_add_u32_e32 v162, s28, v165
	s_cmp_gt_i32 s24, 9
	s_mov_b64 s[6:7], -1
	ds_write2_b32 v7, v13, v9 offset0:76 offset1:92
	ds_write2_b32 v14, v2, v78 offset0:224 offset1:240
	ds_write2_b32 v6, v3, v79 offset0:100 offset1:116
	ds_write2_b32 v6, v4, v80 offset0:232 offset1:248
	ds_write2_b32 v7, v5, v81 offset0:108 offset1:124
	s_waitcnt lgkmcnt(0)
	s_barrier
	s_cbranch_scc0 .LBB0_239
	s_cmp_gt_u32 s24, 11
	s_cbranch_scc0 .LBB0_224
	s_cmp_lg_u32 s24, 36
	s_cbranch_scc0 .LBB0_219
	s_sub_i32 s6, s24, 20
	s_cmp_gt_u32 s6, 7
	s_mov_b64 s[6:7], -1
	s_cbranch_scc0 .LBB0_215
	s_cmp_lt_u32 s24, 16
	s_cselect_b64 s[48:49], -1, 0
	s_cmp_gt_u32 s24, 15
	s_mov_b64 s[54:55], -1
	s_cbranch_scc0 .LBB0_202
	s_cmp_gt_u32 s24, 19
	s_cbranch_scc0 .LBB0_199
	s_mov_b64 s[50:51], -1
	s_cmp_gt_u32 s24, 35
	s_mov_b64 s[8:9], -1
	s_cbranch_scc0 .LBB0_197
	s_lshl_b64 s[6:7], s[28:29], 12
	s_add_u32 s6, s42, s6
	s_addc_u32 s7, s43, s7
	s_mov_b64 s[8:9], 0

.LBB0_552:
	s_and_b32 s34, s33, 0xff
	s_mul_i32 s4, s34, 0xab
	s_lshr_b32 s47, s4, 11
	s_mul_i32 s4, s47, 12
	s_sub_i32 s4, s33, s4
	s_and_b32 s4, s4, 0xff
	s_lshl_b32 s4, s4, 10
	s_or_b32 s48, s4, s15
	s_lshl_b32 s35, s48, 10
	s_lshl_b32 s4, s48, 11
	s_add_u32 s10, s16, s4
	s_addc_u32 s11, s17, 0
	s_lshl_b32 s46, s47, 17
	s_lshl_b32 s4, s47, 18
	s_add_u32 s12, s18, s4
	s_addc_u32 s13, s19, 0
	v_and_b32_e32 v164, 15, v0
	v_bfe_u32 v165, v0, 4, 2
	v_and_b32_e32 v111, 7, v164
	v_xor_b32_e32 v165, v165, v111
	v_lshlrev_b32_e32 v165, 4, v165
	v_lshl_or_b32 v165, v164, 7, v165
	v_bfe_u32 v164, v0, 7, 1
	v_lshl_or_b32 v100, v164, 13, v165
	v_bfe_u32 v164, v0, 6, 1
	v_lshl_or_b32 v158, v164, 13, v165
	v_or_b32_e32 v158, 0x4000, v158
	v_xor_b32_e32 v111, 64, v100
	v_xor_b32_e32 v159, 64, v158
	v_bfe_u32 v164, v0, 3, 3
	v_and_b32_e32 v165, 7, v0
	v_xor_b32_e32 v165, v165, v164
	v_lshlrev_b32_e32 v165, 4, v165
	v_lshl_or_b32 v165, v164, 11, v165
	v_lshrrev_b32_e32 v164, 6, v0
	v_and_b32_e32 v164, 3, v164
	v_lshl_or_b32 v160, v164, 16, v165
	v_add_u32_e32 v161, 0x3c00, v160
	v_add_u32_e32 v162, 0x7800, v160
	v_add_u32_e32 v163, 0xb400, v160
	v_lshlrev_b32_e32 v164, 12, v164
	s_nop 0
	v_readfirstlane_b32 s50, v164
	s_add_u32 s50, s50, 32
	v_mov_b32_e32 v94, 0
	v_mov_b32_e32 v95, 0
	v_mov_b32_e32 v96, 0
	v_mov_b32_e32 v97, 0
	v_mov_b32_e32 v90, 0
	v_mov_b32_e32 v91, 0
	v_mov_b32_e32 v92, 0
	v_mov_b32_e32 v93, 0
	v_mov_b32_e32 v82, 0
	v_mov_b32_e32 v83, 0
	v_mov_b32_e32 v84, 0
	v_mov_b32_e32 v85, 0
	v_mov_b32_e32 v78, 0
	v_mov_b32_e32 v79, 0
	v_mov_b32_e32 v80, 0
	v_mov_b32_e32 v81, 0
	v_mov_b32_e32 v74, 0
	v_mov_b32_e32 v75, 0
	v_mov_b32_e32 v76, 0
	v_mov_b32_e32 v77, 0
	v_mov_b32_e32 v70, 0
	v_mov_b32_e32 v71, 0
	v_mov_b32_e32 v72, 0
	v_mov_b32_e32 v73, 0
	v_mov_b32_e32 v66, 0
	v_mov_b32_e32 v67, 0
	v_mov_b32_e32 v68, 0
	v_mov_b32_e32 v69, 0
	v_mov_b32_e32 v58, 0
	v_mov_b32_e32 v59, 0
	v_mov_b32_e32 v60, 0
	v_mov_b32_e32 v61, 0
	v_mov_b32_e32 v26, 0
	v_mov_b32_e32 v27, 0
	v_mov_b32_e32 v28, 0
	v_mov_b32_e32 v29, 0
	v_mov_b32_e32 v22, 0
	v_mov_b32_e32 v23, 0
	v_mov_b32_e32 v24, 0
	v_mov_b32_e32 v25, 0
	v_mov_b32_e32 v18, 0
	v_mov_b32_e32 v19, 0
	v_mov_b32_e32 v20, 0
	v_mov_b32_e32 v21, 0
	v_mov_b32_e32 v14, 0
	v_mov_b32_e32 v15, 0
	v_mov_b32_e32 v16, 0
	v_mov_b32_e32 v17, 0
	v_mov_b32_e32 v10, 0
	v_mov_b32_e32 v11, 0
	v_mov_b32_e32 v12, 0
	v_mov_b32_e32 v13, 0
	v_mov_b32_e32 v6, 0
	v_mov_b32_e32 v7, 0
	v_mov_b32_e32 v8, 0
	v_mov_b32_e32 v9, 0
	v_mov_b32_e32 v2, 0
	v_mov_b32_e32 v3, 0
	v_mov_b32_e32 v4, 0
	v_mov_b32_e32 v5, 0
	v_mov_b32_e32 v86, 0
	v_mov_b32_e32 v87, 0
	v_mov_b32_e32 v88, 0
	v_mov_b32_e32 v89, 0
	v_mov_b32_e32 v114, 0
	v_mov_b32_e32 v115, 0
	v_mov_b32_e32 v116, 0
	v_mov_b32_e32 v117, 0
	v_mov_b32_e32 v118, 0
	v_mov_b32_e32 v119, 0
	v_mov_b32_e32 v120, 0
	v_mov_b32_e32 v121, 0
	v_mov_b32_e32 v122, 0
	v_mov_b32_e32 v123, 0
	v_mov_b32_e32 v124, 0
	v_mov_b32_e32 v125, 0
	v_mov_b32_e32 v138, 0
	v_mov_b32_e32 v139, 0
	v_mov_b32_e32 v140, 0
	v_mov_b32_e32 v141, 0
	v_mov_b32_e32 v142, 0
	v_mov_b32_e32 v143, 0
	v_mov_b32_e32 v144, 0
	v_mov_b32_e32 v145, 0
	v_mov_b32_e32 v146, 0
	v_mov_b32_e32 v147, 0
	v_mov_b32_e32 v148, 0
	v_mov_b32_e32 v149, 0
	v_mov_b32_e32 v150, 0
	v_mov_b32_e32 v151, 0
	v_mov_b32_e32 v152, 0
	v_mov_b32_e32 v153, 0
	v_mov_b32_e32 v154, 0
	v_mov_b32_e32 v155, 0
	v_mov_b32_e32 v156, 0
	v_mov_b32_e32 v157, 0
	s_waitcnt lgkmcnt(0)
	s_barrier
	v_readlane_b32 s98, v255, 16
	s_lshr_b32 s98, s98, 3
	s_and_b32 s98, s98, 3
	s_lshl_b32 s98, s98, 2
	s_lshl_b32 s99, s98, 7
	s_add_u32 s10, s10, s99
	s_addc_u32 s11, s11, 0
	s_add_u32 s12, s12, s99
	s_addc_u32 s13, s13, 0
	s_add_u32 m0, s50, 0
	s_nop 0
	global_load_lds_dwordx4 v160, s[10:11] offset:0
	global_load_lds_dwordx4 v161, s[10:11] offset:1024
	global_load_lds_dwordx4 v162, s[10:11] offset:2048
	global_load_lds_dwordx4 v163, s[10:11] offset:3072
	s_add_u32 m0, s50, 16384
	s_nop 0
	global_load_lds_dwordx4 v160, s[12:13] offset:0
	global_load_lds_dwordx4 v161, s[12:13] offset:1024
	global_load_lds_dwordx4 v162, s[12:13] offset:2048
	global_load_lds_dwordx4 v163, s[12:13] offset:3072
	s_add_u32 s98, s98, 1
	s_and_b32 s98, s98, 15
	s_cmp_eq_u32 s98, 0
	s_cselect_b32 s99, 0x800, 0
	s_add_u32 s10, s10, 0x80
	s_addc_u32 s11, s11, 0
	s_sub_u32 s10, s10, s99
	s_subb_u32 s11, s11, 0
	s_add_u32 s12, s12, 0x80
	s_addc_u32 s13, s13, 0
	s_sub_u32 s12, s12, s99
	s_subb_u32 s13, s13, 0
	s_mov_b32 s49, 0
	s_waitcnt vmcnt(0)
.Lk_aol0a_loop:
	s_barrier
	s_add_u32 m0, s50, 32768
	v_mfma_f32_16x16x32_bf16 v[94:97], v[114:117], v[142:145], v[94:97]
	ds_read_b128 v[30:33], v100 offset:32
	global_load_lds_dwordx4 v160, s[10:11] offset:0
	v_mfma_f32_16x16x32_bf16 v[90:93], v[114:117], v[146:149], v[90:93]
	ds_read_b128 v[46:49], v158 offset:32
	global_load_lds_dwordx4 v161, s[10:11] offset:1024
	v_mfma_f32_16x16x32_bf16 v[82:85], v[114:117], v[150:153], v[82:85]
	ds_read_b128 v[50:53], v158 offset:2080
	global_load_lds_dwordx4 v162, s[10:11] offset:2048
	v_mfma_f32_16x16x32_bf16 v[78:81], v[114:117], v[154:157], v[78:81]
	ds_read_b128 v[34:37], v100 offset:2080
	global_load_lds_dwordx4 v163, s[10:11] offset:3072
	s_add_u32 m0, s50, 49152
	v_mfma_f32_16x16x32_bf16 v[74:77], v[118:121], v[142:145], v[74:77]
	ds_read_b128 v[54:57], v158 offset:4128
	global_load_lds_dwordx4 v160, s[12:13] offset:0
	v_mfma_f32_16x16x32_bf16 v[70:73], v[118:121], v[146:149], v[70:73]
	ds_read_b128 v[62:65], v158 offset:6176
	global_load_lds_dwordx4 v161, s[12:13] offset:1024
	v_mfma_f32_16x16x32_bf16 v[66:69], v[118:121], v[150:153], v[66:69]
	ds_read_b128 v[38:41], v100 offset:4128
	global_load_lds_dwordx4 v162, s[12:13] offset:2048
	v_mfma_f32_16x16x32_bf16 v[58:61], v[118:121], v[154:157], v[58:61]
	ds_read_b128 v[42:45], v100 offset:6176
	global_load_lds_dwordx4 v163, s[12:13] offset:3072
	v_mfma_f32_16x16x32_bf16 v[26:29], v[122:125], v[142:145], v[26:29]
	v_mfma_f32_16x16x32_bf16 v[22:25], v[122:125], v[146:149], v[22:25]
	v_mfma_f32_16x16x32_bf16 v[18:21], v[122:125], v[150:153], v[18:21]
	v_mfma_f32_16x16x32_bf16 v[14:17], v[122:125], v[154:157], v[14:17]
	v_mfma_f32_16x16x32_bf16 v[10:13], v[138:141], v[142:145], v[10:13]
	v_mfma_f32_16x16x32_bf16 v[6:9], v[138:141], v[146:149], v[6:9]
	v_mfma_f32_16x16x32_bf16 v[2:5], v[138:141], v[150:153], v[2:5]
	v_mfma_f32_16x16x32_bf16 v[86:89], v[138:141], v[154:157], v[86:89]
	s_add_u32 s98, s98, 1
	s_and_b32 s98, s98, 15
	s_cmp_eq_u32 s98, 0
	s_cselect_b32 s99, 0x800, 0
	s_add_u32 s10, s10, 0x80
	s_addc_u32 s11, s11, 0
	s_sub_u32 s10, s10, s99
	s_subb_u32 s11, s11, 0
	s_add_u32 s12, s12, 0x80
	s_addc_u32 s13, s13, 0
	s_sub_u32 s12, s12, s99
	s_subb_u32 s13, s13, 0
	s_waitcnt lgkmcnt(0)
	v_mfma_f32_16x16x32_bf16 v[94:97], v[30:33], v[46:49], v[94:97]
	ds_read_b128 v[114:117], v111 offset:32
	v_mfma_f32_16x16x32_bf16 v[90:93], v[30:33], v[50:53], v[90:93]
	ds_read_b128 v[142:145], v159 offset:32
	v_mfma_f32_16x16x32_bf16 v[82:85], v[30:33], v[54:57], v[82:85]
	ds_read_b128 v[146:149], v159 offset:2080
	v_mfma_f32_16x16x32_bf16 v[78:81], v[30:33], v[62:65], v[78:81]
	ds_read_b128 v[118:121], v111 offset:2080
	v_mfma_f32_16x16x32_bf16 v[74:77], v[34:37], v[46:49], v[74:77]
	ds_read_b128 v[150:153], v159 offset:4128
	v_mfma_f32_16x16x32_bf16 v[70:73], v[34:37], v[50:53], v[70:73]
	ds_read_b128 v[154:157], v159 offset:6176
	v_mfma_f32_16x16x32_bf16 v[66:69], v[34:37], v[54:57], v[66:69]
	ds_read_b128 v[122:125], v111 offset:4128
	v_mfma_f32_16x16x32_bf16 v[58:61], v[34:37], v[62:65], v[58:61]
	ds_read_b128 v[138:141], v111 offset:6176
	v_mfma_f32_16x16x32_bf16 v[26:29], v[38:41], v[46:49], v[26:29]
	v_mfma_f32_16x16x32_bf16 v[22:25], v[38:41], v[50:53], v[22:25]
	v_mfma_f32_16x16x32_bf16 v[18:21], v[38:41], v[54:57], v[18:21]
	v_mfma_f32_16x16x32_bf16 v[14:17], v[38:41], v[62:65], v[14:17]
	v_mfma_f32_16x16x32_bf16 v[10:13], v[42:45], v[46:49], v[10:13]
	v_mfma_f32_16x16x32_bf16 v[6:9], v[42:45], v[50:53], v[6:9]
	v_mfma_f32_16x16x32_bf16 v[2:5], v[42:45], v[54:57], v[2:5]
	v_mfma_f32_16x16x32_bf16 v[86:89], v[42:45], v[62:65], v[86:89]
	s_waitcnt lgkmcnt(0)
	s_waitcnt vmcnt(0)
	s_barrier
	s_add_u32 m0, s50, 0
	v_mfma_f32_16x16x32_bf16 v[94:97], v[114:117], v[142:145], v[94:97]
	ds_read_b128 v[30:33], v100 offset:32800
	global_load_lds_dwordx4 v160, s[10:11] offset:0
	v_mfma_f32_16x16x32_bf16 v[90:93], v[114:117], v[146:149], v[90:93]
	ds_read_b128 v[46:49], v158 offset:32800
	global_load_lds_dwordx4 v161, s[10:11] offset:1024
	v_mfma_f32_16x16x32_bf16 v[82:85], v[114:117], v[150:153], v[82:85]
	ds_read_b128 v[50:53], v158 offset:34848
	global_load_lds_dwordx4 v162, s[10:11] offset:2048
	v_mfma_f32_16x16x32_bf16 v[78:81], v[114:117], v[154:157], v[78:81]
	ds_read_b128 v[34:37], v100 offset:34848
	global_load_lds_dwordx4 v163, s[10:11] offset:3072
	s_add_u32 m0, s50, 16384
	v_mfma_f32_16x16x32_bf16 v[74:77], v[118:121], v[142:145], v[74:77]
	ds_read_b128 v[54:57], v158 offset:36896
	global_load_lds_dwordx4 v160, s[12:13] offset:0
	v_mfma_f32_16x16x32_bf16 v[70:73], v[118:121], v[146:149], v[70:73]
	ds_read_b128 v[62:65], v158 offset:38944
	global_load_lds_dwordx4 v161, s[12:13] offset:1024
	v_mfma_f32_16x16x32_bf16 v[66:69], v[118:121], v[150:153], v[66:69]
	ds_read_b128 v[38:41], v100 offset:36896
	global_load_lds_dwordx4 v162, s[12:13] offset:2048
	v_mfma_f32_16x16x32_bf16 v[58:61], v[118:121], v[154:157], v[58:61]
	ds_read_b128 v[42:45], v100 offset:38944
	global_load_lds_dwordx4 v163, s[12:13] offset:3072
	v_mfma_f32_16x16x32_bf16 v[26:29], v[122:125], v[142:145], v[26:29]
	v_mfma_f32_16x16x32_bf16 v[22:25], v[122:125], v[146:149], v[22:25]
	v_mfma_f32_16x16x32_bf16 v[18:21], v[122:125], v[150:153], v[18:21]
	v_mfma_f32_16x16x32_bf16 v[14:17], v[122:125], v[154:157], v[14:17]
	v_mfma_f32_16x16x32_bf16 v[10:13], v[138:141], v[142:145], v[10:13]
	v_mfma_f32_16x16x32_bf16 v[6:9], v[138:141], v[146:149], v[6:9]
	v_mfma_f32_16x16x32_bf16 v[2:5], v[138:141], v[150:153], v[2:5]
	v_mfma_f32_16x16x32_bf16 v[86:89], v[138:141], v[154:157], v[86:89]
	s_add_u32 s98, s98, 1
	s_and_b32 s98, s98, 15
	s_cmp_eq_u32 s98, 0
	s_cselect_b32 s99, 0x800, 0
	s_add_u32 s10, s10, 0x80
	s_addc_u32 s11, s11, 0
	s_sub_u32 s10, s10, s99
	s_subb_u32 s11, s11, 0
	s_add_u32 s12, s12, 0x80
	s_addc_u32 s13, s13, 0
	s_sub_u32 s12, s12, s99
	s_subb_u32 s13, s13, 0
	s_waitcnt lgkmcnt(0)
	v_mfma_f32_16x16x32_bf16 v[94:97], v[30:33], v[46:49], v[94:97]
	ds_read_b128 v[114:117], v111 offset:32800
	v_mfma_f32_16x16x32_bf16 v[90:93], v[30:33], v[50:53], v[90:93]
	ds_read_b128 v[142:145], v159 offset:32800
	v_mfma_f32_16x16x32_bf16 v[82:85], v[30:33], v[54:57], v[82:85]
	ds_read_b128 v[146:149], v159 offset:34848
	v_mfma_f32_16x16x32_bf16 v[78:81], v[30:33], v[62:65], v[78:81]
	ds_read_b128 v[118:121], v111 offset:34848
	v_mfma_f32_16x16x32_bf16 v[74:77], v[34:37], v[46:49], v[74:77]
	ds_read_b128 v[150:153], v159 offset:36896
	v_mfma_f32_16x16x32_bf16 v[70:73], v[34:37], v[50:53], v[70:73]
	ds_read_b128 v[154:157], v159 offset:38944
	v_mfma_f32_16x16x32_bf16 v[66:69], v[34:37], v[54:57], v[66:69]
	ds_read_b128 v[122:125], v111 offset:36896
	v_mfma_f32_16x16x32_bf16 v[58:61], v[34:37], v[62:65], v[58:61]
	ds_read_b128 v[138:141], v111 offset:38944
	v_mfma_f32_16x16x32_bf16 v[26:29], v[38:41], v[46:49], v[26:29]
	v_mfma_f32_16x16x32_bf16 v[22:25], v[38:41], v[50:53], v[22:25]
	v_mfma_f32_16x16x32_bf16 v[18:21], v[38:41], v[54:57], v[18:21]
	v_mfma_f32_16x16x32_bf16 v[14:17], v[38:41], v[62:65], v[14:17]
	v_mfma_f32_16x16x32_bf16 v[10:13], v[42:45], v[46:49], v[10:13]
	v_mfma_f32_16x16x32_bf16 v[6:9], v[42:45], v[50:53], v[6:9]
	v_mfma_f32_16x16x32_bf16 v[2:5], v[42:45], v[54:57], v[2:5]
	v_mfma_f32_16x16x32_bf16 v[86:89], v[42:45], v[62:65], v[86:89]
	s_waitcnt lgkmcnt(0)
	s_waitcnt vmcnt(0)
	s_add_u32 s49, s49, 1
	s_cmp_lt_u32 s49, 7
	s_cbranch_scc1 .Lk_aol0a_loop
	s_barrier
	s_add_u32 m0, s50, 32768
	v_mfma_f32_16x16x32_bf16 v[94:97], v[114:117], v[142:145], v[94:97]
	ds_read_b128 v[30:33], v100 offset:32
	global_load_lds_dwordx4 v160, s[10:11] offset:0
	v_mfma_f32_16x16x32_bf16 v[90:93], v[114:117], v[146:149], v[90:93]
	ds_read_b128 v[46:49], v158 offset:32
	global_load_lds_dwordx4 v161, s[10:11] offset:1024
	v_mfma_f32_16x16x32_bf16 v[82:85], v[114:117], v[150:153], v[82:85]
	ds_read_b128 v[50:53], v158 offset:2080
	global_load_lds_dwordx4 v162, s[10:11] offset:2048
	v_mfma_f32_16x16x32_bf16 v[78:81], v[114:117], v[154:157], v[78:81]
	ds_read_b128 v[34:37], v100 offset:2080
	global_load_lds_dwordx4 v163, s[10:11] offset:3072
	s_add_u32 m0, s50, 49152
	v_mfma_f32_16x16x32_bf16 v[74:77], v[118:121], v[142:145], v[74:77]
	ds_read_b128 v[54:57], v158 offset:4128
	global_load_lds_dwordx4 v160, s[12:13] offset:0
	v_mfma_f32_16x16x32_bf16 v[70:73], v[118:121], v[146:149], v[70:73]
	ds_read_b128 v[62:65], v158 offset:6176
	global_load_lds_dwordx4 v161, s[12:13] offset:1024
	v_mfma_f32_16x16x32_bf16 v[66:69], v[118:121], v[150:153], v[66:69]
	ds_read_b128 v[38:41], v100 offset:4128
	global_load_lds_dwordx4 v162, s[12:13] offset:2048
	v_mfma_f32_16x16x32_bf16 v[58:61], v[118:121], v[154:157], v[58:61]
	ds_read_b128 v[42:45], v100 offset:6176
	global_load_lds_dwordx4 v163, s[12:13] offset:3072
	v_mfma_f32_16x16x32_bf16 v[26:29], v[122:125], v[142:145], v[26:29]
	v_mfma_f32_16x16x32_bf16 v[22:25], v[122:125], v[146:149], v[22:25]
	v_mfma_f32_16x16x32_bf16 v[18:21], v[122:125], v[150:153], v[18:21]
	v_mfma_f32_16x16x32_bf16 v[14:17], v[122:125], v[154:157], v[14:17]
	v_mfma_f32_16x16x32_bf16 v[10:13], v[138:141], v[142:145], v[10:13]
	v_mfma_f32_16x16x32_bf16 v[6:9], v[138:141], v[146:149], v[6:9]
	v_mfma_f32_16x16x32_bf16 v[2:5], v[138:141], v[150:153], v[2:5]
	v_mfma_f32_16x16x32_bf16 v[86:89], v[138:141], v[154:157], v[86:89]
	s_add_u32 s98, s98, 1
	s_and_b32 s98, s98, 15
	s_cmp_eq_u32 s98, 0
	s_cselect_b32 s99, 0x800, 0
	s_add_u32 s10, s10, 0x80
	s_addc_u32 s11, s11, 0
	s_sub_u32 s10, s10, s99
	s_subb_u32 s11, s11, 0
	s_add_u32 s12, s12, 0x80
	s_addc_u32 s13, s13, 0
	s_sub_u32 s12, s12, s99
	s_subb_u32 s13, s13, 0
	s_waitcnt lgkmcnt(0)
	v_mfma_f32_16x16x32_bf16 v[94:97], v[30:33], v[46:49], v[94:97]
	ds_read_b128 v[114:117], v111 offset:32
	v_mfma_f32_16x16x32_bf16 v[90:93], v[30:33], v[50:53], v[90:93]
	ds_read_b128 v[142:145], v159 offset:32
	v_mfma_f32_16x16x32_bf16 v[82:85], v[30:33], v[54:57], v[82:85]
	ds_read_b128 v[146:149], v159 offset:2080
	v_mfma_f32_16x16x32_bf16 v[78:81], v[30:33], v[62:65], v[78:81]
	ds_read_b128 v[118:121], v111 offset:2080
	v_mfma_f32_16x16x32_bf16 v[74:77], v[34:37], v[46:49], v[74:77]
	ds_read_b128 v[150:153], v159 offset:4128
	v_mfma_f32_16x16x32_bf16 v[70:73], v[34:37], v[50:53], v[70:73]
	ds_read_b128 v[154:157], v159 offset:6176
	v_mfma_f32_16x16x32_bf16 v[66:69], v[34:37], v[54:57], v[66:69]
	ds_read_b128 v[122:125], v111 offset:4128
	v_mfma_f32_16x16x32_bf16 v[58:61], v[34:37], v[62:65], v[58:61]
	ds_read_b128 v[138:141], v111 offset:6176
	v_mfma_f32_16x16x32_bf16 v[26:29], v[38:41], v[46:49], v[26:29]
	v_mfma_f32_16x16x32_bf16 v[22:25], v[38:41], v[50:53], v[22:25]
	v_mfma_f32_16x16x32_bf16 v[18:21], v[38:41], v[54:57], v[18:21]
	v_mfma_f32_16x16x32_bf16 v[14:17], v[38:41], v[62:65], v[14:17]
	v_mfma_f32_16x16x32_bf16 v[10:13], v[42:45], v[46:49], v[10:13]
	v_mfma_f32_16x16x32_bf16 v[6:9], v[42:45], v[50:53], v[6:9]
	v_mfma_f32_16x16x32_bf16 v[2:5], v[42:45], v[54:57], v[2:5]
	v_mfma_f32_16x16x32_bf16 v[86:89], v[42:45], v[62:65], v[86:89]
	s_waitcnt lgkmcnt(0)
	s_waitcnt vmcnt(0)
	s_barrier
	v_mfma_f32_16x16x32_bf16 v[94:97], v[114:117], v[142:145], v[94:97]
	ds_read_b128 v[30:33], v100 offset:32800
	v_mfma_f32_16x16x32_bf16 v[90:93], v[114:117], v[146:149], v[90:93]
	ds_read_b128 v[46:49], v158 offset:32800
	v_mfma_f32_16x16x32_bf16 v[82:85], v[114:117], v[150:153], v[82:85]
	ds_read_b128 v[50:53], v158 offset:34848
	v_mfma_f32_16x16x32_bf16 v[78:81], v[114:117], v[154:157], v[78:81]
	ds_read_b128 v[34:37], v100 offset:34848
	v_mfma_f32_16x16x32_bf16 v[74:77], v[118:121], v[142:145], v[74:77]
	ds_read_b128 v[54:57], v158 offset:36896
	v_mfma_f32_16x16x32_bf16 v[70:73], v[118:121], v[146:149], v[70:73]
	ds_read_b128 v[62:65], v158 offset:38944
	v_mfma_f32_16x16x32_bf16 v[66:69], v[118:121], v[150:153], v[66:69]
	ds_read_b128 v[38:41], v100 offset:36896
	v_mfma_f32_16x16x32_bf16 v[58:61], v[118:121], v[154:157], v[58:61]
	ds_read_b128 v[42:45], v100 offset:38944
	v_mfma_f32_16x16x32_bf16 v[26:29], v[122:125], v[142:145], v[26:29]
	v_mfma_f32_16x16x32_bf16 v[22:25], v[122:125], v[146:149], v[22:25]
	v_mfma_f32_16x16x32_bf16 v[18:21], v[122:125], v[150:153], v[18:21]
	v_mfma_f32_16x16x32_bf16 v[14:17], v[122:125], v[154:157], v[14:17]
	v_mfma_f32_16x16x32_bf16 v[10:13], v[138:141], v[142:145], v[10:13]
	v_mfma_f32_16x16x32_bf16 v[6:9], v[138:141], v[146:149], v[6:9]
	v_mfma_f32_16x16x32_bf16 v[2:5], v[138:141], v[150:153], v[2:5]
	v_mfma_f32_16x16x32_bf16 v[86:89], v[138:141], v[154:157], v[86:89]
	s_waitcnt lgkmcnt(0)
	v_mfma_f32_16x16x32_bf16 v[94:97], v[30:33], v[46:49], v[94:97]
	ds_read_b128 v[114:117], v111 offset:32800
	v_mfma_f32_16x16x32_bf16 v[90:93], v[30:33], v[50:53], v[90:93]
	ds_read_b128 v[142:145], v159 offset:32800
	v_mfma_f32_16x16x32_bf16 v[82:85], v[30:33], v[54:57], v[82:85]
	ds_read_b128 v[146:149], v159 offset:34848
	v_mfma_f32_16x16x32_bf16 v[78:81], v[30:33], v[62:65], v[78:81]
	ds_read_b128 v[118:121], v111 offset:34848
	v_mfma_f32_16x16x32_bf16 v[74:77], v[34:37], v[46:49], v[74:77]
	ds_read_b128 v[150:153], v159 offset:36896
	v_mfma_f32_16x16x32_bf16 v[70:73], v[34:37], v[50:53], v[70:73]
	ds_read_b128 v[154:157], v159 offset:38944
	v_mfma_f32_16x16x32_bf16 v[66:69], v[34:37], v[54:57], v[66:69]
	ds_read_b128 v[122:125], v111 offset:36896
	v_mfma_f32_16x16x32_bf16 v[58:61], v[34:37], v[62:65], v[58:61]
	ds_read_b128 v[138:141], v111 offset:38944
	v_mfma_f32_16x16x32_bf16 v[26:29], v[38:41], v[46:49], v[26:29]
	v_mfma_f32_16x16x32_bf16 v[22:25], v[38:41], v[50:53], v[22:25]
	v_mfma_f32_16x16x32_bf16 v[18:21], v[38:41], v[54:57], v[18:21]
	v_mfma_f32_16x16x32_bf16 v[14:17], v[38:41], v[62:65], v[14:17]
	v_mfma_f32_16x16x32_bf16 v[10:13], v[42:45], v[46:49], v[10:13]
	v_mfma_f32_16x16x32_bf16 v[6:9], v[42:45], v[50:53], v[6:9]
	v_mfma_f32_16x16x32_bf16 v[2:5], v[42:45], v[54:57], v[2:5]
	v_mfma_f32_16x16x32_bf16 v[86:89], v[42:45], v[62:65], v[86:89]
	s_waitcnt lgkmcnt(0)
	v_mfma_f32_16x16x32_bf16 v[94:97], v[114:117], v[142:145], v[94:97]
	v_mfma_f32_16x16x32_bf16 v[90:93], v[114:117], v[146:149], v[90:93]
	v_mfma_f32_16x16x32_bf16 v[82:85], v[114:117], v[150:153], v[82:85]
	v_mfma_f32_16x16x32_bf16 v[78:81], v[114:117], v[154:157], v[78:81]
	v_mfma_f32_16x16x32_bf16 v[74:77], v[118:121], v[142:145], v[74:77]
	v_mfma_f32_16x16x32_bf16 v[70:73], v[118:121], v[146:149], v[70:73]
	v_mfma_f32_16x16x32_bf16 v[66:69], v[118:121], v[150:153], v[66:69]
	v_mfma_f32_16x16x32_bf16 v[58:61], v[118:121], v[154:157], v[58:61]
	v_mfma_f32_16x16x32_bf16 v[26:29], v[122:125], v[142:145], v[26:29]
	v_mfma_f32_16x16x32_bf16 v[22:25], v[122:125], v[146:149], v[22:25]
	v_mfma_f32_16x16x32_bf16 v[18:21], v[122:125], v[150:153], v[18:21]
	v_mfma_f32_16x16x32_bf16 v[14:17], v[122:125], v[154:157], v[14:17]
	v_mfma_f32_16x16x32_bf16 v[10:13], v[138:141], v[142:145], v[10:13]
	v_mfma_f32_16x16x32_bf16 v[6:9], v[138:141], v[146:149], v[6:9]
	v_mfma_f32_16x16x32_bf16 v[2:5], v[138:141], v[150:153], v[2:5]
	v_mfma_f32_16x16x32_bf16 v[86:89], v[138:141], v[154:157], v[86:89]
	s_mul_i32 s4, s31, s25
	s_add_i32 s4, s4, s30
	s_and_b32 s4, s4, 0xff
	s_waitcnt vmcnt(7)
	v_lshl_or_b32 v30, s4, 10, v132
	s_mul_hi_u32 s4, s4, 0x15555556
	s_mulk_i32 s4, 0xd000
	v_add_u32_e32 v30, s4, v30
	s_lshl_b32 s4, s47, 8
	v_add_u32_e32 v138, 0x400, v129
	v_add_u32_e32 v139, 0x2000, v129
	v_add_u32_e32 v140, 0x2400, v129
	v_add_u32_e32 v141, 0x4000, v129
	v_add_u32_e32 v142, 0x4400, v129
	v_add_u32_e32 v143, 0x4800, v129
	v_add_u32_e32 v144, 0x6000, v129
	v_add_u32_e32 v145, 0x6400, v129
	v_add_u32_e32 v146, 0x6800, v129
	v_lshl_add_u64 v[114:115], v[102:103], 0, s[4:5]
	v_cmp_gt_u32_e32 vcc, s29, v30
	s_barrier
	ds_write2_b32 v129, v94, v90 offset1:16
	ds_write2_b32 v129, v95, v91 offset0:132 offset1:148
	ds_write2_b32 v138, v96, v92 offset0:8 offset1:24
	ds_write2_b32 v138, v97, v93 offset0:140 offset1:156
	ds_write2_b32 v129, v82, v78 offset0:32 offset1:48
	ds_write2_b32 v129, v83, v79 offset0:164 offset1:180
	ds_write2_b32 v138, v84, v80 offset0:40 offset1:56
	ds_write2_b32 v138, v85, v81 offset0:172 offset1:188
	ds_write2_b32 v139, v74, v70 offset0:64 offset1:80
	ds_write2_b32 v139, v75, v71 offset0:196 offset1:212
	ds_write2_b32 v140, v76, v72 offset0:72 offset1:88
	ds_write2_b32 v140, v77, v73 offset0:204 offset1:220
	ds_write2_b32 v139, v66, v58 offset0:96 offset1:112
	ds_write2_b32 v139, v67, v59 offset0:228 offset1:244
	ds_write2_b32 v140, v68, v60 offset0:104 offset1:120
	ds_write2_b32 v140, v69, v61 offset0:236 offset1:252
	ds_write2_b32 v141, v26, v22 offset0:128 offset1:144
	ds_write2_b32 v142, v27, v23 offset0:4 offset1:20
	ds_write2_b32 v142, v28, v24 offset0:136 offset1:152
	ds_write2_b32 v143, v29, v25 offset0:12 offset1:28
	ds_write2_b32 v141, v18, v14 offset0:160 offset1:176
	ds_write2_b32 v142, v19, v15 offset0:36 offset1:52
	ds_write2_b32 v142, v20, v16 offset0:168 offset1:184
	ds_write2_b32 v143, v21, v17 offset0:44 offset1:60
	ds_write2_b32 v144, v10, v6 offset0:192 offset1:208
	ds_write2_b32 v145, v11, v7 offset0:68 offset1:84
	ds_write2_b32 v145, v12, v8 offset0:200 offset1:216
	ds_write2_b32 v146, v13, v9 offset0:76 offset1:92
	ds_write2_b32 v144, v2, v86 offset0:224 offset1:240
	ds_write2_b32 v145, v3, v87 offset0:100 offset1:116
	ds_write2_b32 v145, v4, v88 offset0:232 offset1:248
	ds_write2_b32 v146, v5, v89 offset0:108 offset1:124
	s_waitcnt lgkmcnt(0)
	s_barrier
	s_and_saveexec_b64 s[10:11], vcc
	s_xor_b64 s[10:11], exec, s[10:11]
	s_cbranch_execz .LBB0_557
	s_mov_b32 s4, s48
	s_mov_b32 s12, 1
	s_mov_b32 s13, 0
	s_mov_b32 s49, 8

.LBB0_560:
	s_or_b64 exec, exec, s[10:11]
	s_lshl_b32 s10, s47, 7
	s_lshl_b32 s4, s35, 1
	s_add_u32 s12, s21, s4
	s_addc_u32 s13, s22, 0
	s_lshl_b32 s4, s46, 1
	v_mov_b32_e32 v111, v101
	s_add_u32 s46, s23, s4
	s_addc_u32 s47, s24, 0
	s_waitcnt lgkmcnt(0)
	s_barrier
	ds_read2_b32 v[26:27], v129 offset1:16
	ds_read2_b32 v[148:149], v129 offset0:132 offset1:148
	ds_read2_b32 v[28:29], v138 offset0:8 offset1:24
	ds_read2_b32 v[150:151], v138 offset0:140 offset1:156
	ds_read2_b32 v[22:23], v129 offset0:32 offset1:48
	ds_read2_b32 v[152:153], v129 offset0:164 offset1:180
	ds_read2_b32 v[24:25], v138 offset0:40 offset1:56
	ds_read2_b32 v[154:155], v138 offset0:172 offset1:188
	ds_read2_b32 v[18:19], v139 offset0:64 offset1:80
	ds_read2_b32 v[156:157], v139 offset0:196 offset1:212
	ds_read2_b32 v[20:21], v140 offset0:72 offset1:88
	ds_read2_b32 v[158:159], v140 offset0:204 offset1:220
	ds_read2_b32 v[14:15], v139 offset0:96 offset1:112
	ds_read2_b32 v[160:161], v139 offset0:228 offset1:244
	ds_read2_b32 v[16:17], v140 offset0:104 offset1:120
	ds_read2_b32 v[162:163], v140 offset0:236 offset1:252
	ds_read2_b32 v[10:11], v141 offset0:128 offset1:144
	ds_read2_b32 v[164:165], v142 offset0:4 offset1:20
	ds_read2_b32 v[12:13], v142 offset0:136 offset1:152
	ds_read2_b32 v[166:167], v143 offset0:12 offset1:28
	ds_read2_b32 v[6:7], v141 offset0:160 offset1:176
	ds_read2_b32 v[168:169], v142 offset0:36 offset1:52
	ds_read2_b32 v[8:9], v142 offset0:168 offset1:184
	ds_read2_b32 v[170:171], v143 offset0:44 offset1:60
	ds_read2_b32 v[2:3], v144 offset0:192 offset1:208
	ds_read2_b32 v[172:173], v145 offset0:68 offset1:84
	ds_read2_b32 v[4:5], v145 offset0:200 offset1:216
	ds_read2_b32 v[174:175], v146 offset0:76 offset1:92
	ds_read2_b32 v[30:31], v144 offset0:224 offset1:240
	ds_read2_b32 v[176:177], v145 offset0:100 offset1:116
	ds_read2_b32 v[32:33], v145 offset0:232 offset1:248
	ds_read2_b32 v[180:181], v146 offset0:108 offset1:124
	s_waitcnt lgkmcnt(0)
	s_barrier
	v_mov_b32_e32 v94, v31
	v_mov_b32_e32 v95, v177
	v_mov_b32_e32 v96, v33
	v_mov_b32_e32 v97, v181
	v_mov_b32_e32 v31, v176
	v_mov_b32_e32 v33, v180
	v_mov_b32_e32 v66, v3
	v_mov_b32_e32 v67, v173
	v_mov_b32_e32 v68, v5
	v_mov_b32_e32 v69, v175
	v_mov_b32_e32 v3, v172
	v_mov_b32_e32 v5, v174
	v_mov_b32_e32 v70, v7
	v_mov_b32_e32 v71, v169
	v_mov_b32_e32 v72, v9
	v_mov_b32_e32 v73, v171
	v_mov_b32_e32 v7, v168
	v_mov_b32_e32 v9, v170
	v_mov_b32_e32 v74, v11
	v_mov_b32_e32 v75, v165
	v_mov_b32_e32 v76, v13
	v_mov_b32_e32 v77, v167
	v_mov_b32_e32 v11, v164
	v_mov_b32_e32 v13, v166
	v_mov_b32_e32 v78, v15
	v_mov_b32_e32 v79, v161
	v_mov_b32_e32 v80, v17
	v_mov_b32_e32 v81, v163
	v_mov_b32_e32 v15, v160
	v_mov_b32_e32 v17, v162
	v_mov_b32_e32 v82, v19
	v_mov_b32_e32 v83, v157
	v_mov_b32_e32 v84, v21
	v_mov_b32_e32 v85, v159
	v_mov_b32_e32 v19, v156
	v_mov_b32_e32 v21, v158
	v_mov_b32_e32 v86, v23
	v_mov_b32_e32 v87, v153
	v_mov_b32_e32 v88, v25
	v_mov_b32_e32 v89, v155
	v_mov_b32_e32 v23, v152
	v_mov_b32_e32 v25, v154
	v_mov_b32_e32 v90, v27
	v_mov_b32_e32 v91, v149
	v_mov_b32_e32 v92, v29
	v_mov_b32_e32 v93, v151
	v_mov_b32_e32 v27, v148
	v_mov_b32_e32 v29, v150
	s_waitcnt lgkmcnt(0)
	s_barrier
	v_and_b32_e32 v174, 15, v0
	v_bfe_u32 v175, v0, 4, 2
	v_and_b32_e32 v111, 7, v174
	v_xor_b32_e32 v175, v175, v111
	v_lshlrev_b32_e32 v175, 4, v175
	v_lshl_or_b32 v175, v174, 7, v175
	v_bfe_u32 v174, v0, 7, 1
	v_lshl_or_b32 v100, v174, 13, v175
	v_bfe_u32 v174, v0, 6, 1
	v_lshl_or_b32 v168, v174, 13, v175
	v_or_b32_e32 v168, 0x4000, v168
	v_xor_b32_e32 v111, 64, v100
	v_xor_b32_e32 v169, 64, v168
	v_bfe_u32 v174, v0, 3, 3
	v_and_b32_e32 v175, 7, v0
	v_xor_b32_e32 v175, v175, v174
	v_lshlrev_b32_e32 v175, 4, v175
	v_lshl_or_b32 v175, v174, 11, v175
	v_lshrrev_b32_e32 v174, 6, v0
	v_and_b32_e32 v174, 3, v174
	v_lshl_or_b32 v170, v174, 16, v175
	v_add_u32_e32 v171, 0x3c00, v170
	v_add_u32_e32 v172, 0x7800, v170
	v_add_u32_e32 v173, 0xb400, v170
	v_lshlrev_b32_e32 v174, 12, v174
	s_nop 0
	v_readfirstlane_b32 s4, v174
	s_add_u32 s4, s4, 32
	v_mov_b32_e32 v116, 0
	v_mov_b32_e32 v117, 0
	v_mov_b32_e32 v118, 0
	v_mov_b32_e32 v119, 0
	v_mov_b32_e32 v120, 0
	v_mov_b32_e32 v121, 0
	v_mov_b32_e32 v122, 0
	v_mov_b32_e32 v123, 0
	v_mov_b32_e32 v124, 0
	v_mov_b32_e32 v125, 0
	v_mov_b32_e32 v126, 0
	v_mov_b32_e32 v127, 0
	v_mov_b32_e32 v148, 0
	v_mov_b32_e32 v149, 0
	v_mov_b32_e32 v150, 0
	v_mov_b32_e32 v151, 0
	v_mov_b32_e32 v152, 0
	v_mov_b32_e32 v153, 0
	v_mov_b32_e32 v154, 0
	v_mov_b32_e32 v155, 0
	v_mov_b32_e32 v156, 0
	v_mov_b32_e32 v157, 0
	v_mov_b32_e32 v158, 0
	v_mov_b32_e32 v159, 0
	v_mov_b32_e32 v160, 0
	v_mov_b32_e32 v161, 0
	v_mov_b32_e32 v162, 0
	v_mov_b32_e32 v163, 0
	v_mov_b32_e32 v164, 0
	v_mov_b32_e32 v165, 0
	v_mov_b32_e32 v166, 0
	v_mov_b32_e32 v167, 0
	s_waitcnt lgkmcnt(0)
	s_barrier
	v_readlane_b32 s98, v255, 16
	s_lshr_b32 s98, s98, 3
	s_and_b32 s98, s98, 3
	s_lshl_b32 s98, s98, 2
	s_lshl_b32 s99, s98, 7
	s_add_u32 s12, s12, s99
	s_addc_u32 s13, s13, 0
	s_add_u32 s46, s46, s99
	s_addc_u32 s47, s47, 0
	s_add_u32 m0, s4, 0
	s_nop 0
	global_load_lds_dwordx4 v170, s[12:13] offset:0
	global_load_lds_dwordx4 v171, s[12:13] offset:1024
	global_load_lds_dwordx4 v172, s[12:13] offset:2048
	global_load_lds_dwordx4 v173, s[12:13] offset:3072
	s_add_u32 m0, s4, 16384
	s_nop 0
	global_load_lds_dwordx4 v170, s[46:47] offset:0
	global_load_lds_dwordx4 v171, s[46:47] offset:1024
	global_load_lds_dwordx4 v172, s[46:47] offset:2048
	global_load_lds_dwordx4 v173, s[46:47] offset:3072
	s_add_u32 s98, s98, 1
	s_and_b32 s98, s98, 15
	s_cmp_eq_u32 s98, 0
	s_cselect_b32 s99, 0x800, 0
	s_add_u32 s12, s12, 0x80
	s_addc_u32 s13, s13, 0
	s_sub_u32 s12, s12, s99
	s_subb_u32 s13, s13, 0
	s_add_u32 s46, s46, 0x80
	s_addc_u32 s47, s47, 0
	s_sub_u32 s46, s46, s99
	s_subb_u32 s47, s47, 0
	s_mov_b32 s11, 0
	s_waitcnt vmcnt(0)
.Lk_aol0b_loop:
	s_barrier
	s_add_u32 m0, s4, 32768
	v_mfma_f32_16x16x32_bf16 v[26:29], v[116:119], v[152:155], v[26:29]
	ds_read_b128 v[34:37], v100 offset:32
	global_load_lds_dwordx4 v170, s[12:13] offset:0
	v_mfma_f32_16x16x32_bf16 v[90:93], v[116:119], v[156:159], v[90:93]
	ds_read_b128 v[50:53], v168 offset:32
	global_load_lds_dwordx4 v171, s[12:13] offset:1024
	v_mfma_f32_16x16x32_bf16 v[22:25], v[116:119], v[160:163], v[22:25]
	ds_read_b128 v[54:57], v168 offset:2080
	global_load_lds_dwordx4 v172, s[12:13] offset:2048
	v_mfma_f32_16x16x32_bf16 v[86:89], v[116:119], v[164:167], v[86:89]
	ds_read_b128 v[38:41], v100 offset:2080
	global_load_lds_dwordx4 v173, s[12:13] offset:3072
	s_add_u32 m0, s4, 49152
	v_mfma_f32_16x16x32_bf16 v[18:21], v[120:123], v[152:155], v[18:21]
	ds_read_b128 v[58:61], v168 offset:4128
	global_load_lds_dwordx4 v170, s[46:47] offset:0
	v_mfma_f32_16x16x32_bf16 v[82:85], v[120:123], v[156:159], v[82:85]
	ds_read_b128 v[62:65], v168 offset:6176
	global_load_lds_dwordx4 v171, s[46:47] offset:1024
	v_mfma_f32_16x16x32_bf16 v[14:17], v[120:123], v[160:163], v[14:17]
	ds_read_b128 v[42:45], v100 offset:4128
	global_load_lds_dwordx4 v172, s[46:47] offset:2048
	v_mfma_f32_16x16x32_bf16 v[78:81], v[120:123], v[164:167], v[78:81]
	ds_read_b128 v[46:49], v100 offset:6176
	global_load_lds_dwordx4 v173, s[46:47] offset:3072
	v_mfma_f32_16x16x32_bf16 v[10:13], v[124:127], v[152:155], v[10:13]
	v_mfma_f32_16x16x32_bf16 v[74:77], v[124:127], v[156:159], v[74:77]
	v_mfma_f32_16x16x32_bf16 v[6:9], v[124:127], v[160:163], v[6:9]
	v_mfma_f32_16x16x32_bf16 v[70:73], v[124:127], v[164:167], v[70:73]
	v_mfma_f32_16x16x32_bf16 v[2:5], v[148:151], v[152:155], v[2:5]
	v_mfma_f32_16x16x32_bf16 v[66:69], v[148:151], v[156:159], v[66:69]
	v_mfma_f32_16x16x32_bf16 v[30:33], v[148:151], v[160:163], v[30:33]
	v_mfma_f32_16x16x32_bf16 v[94:97], v[148:151], v[164:167], v[94:97]
	s_add_u32 s98, s98, 1
	s_and_b32 s98, s98, 15
	s_cmp_eq_u32 s98, 0
	s_cselect_b32 s99, 0x800, 0
	s_add_u32 s12, s12, 0x80
	s_addc_u32 s13, s13, 0
	s_sub_u32 s12, s12, s99
	s_subb_u32 s13, s13, 0
	s_add_u32 s46, s46, 0x80
	s_addc_u32 s47, s47, 0
	s_sub_u32 s46, s46, s99
	s_subb_u32 s47, s47, 0
	s_waitcnt lgkmcnt(0)
	v_mfma_f32_16x16x32_bf16 v[26:29], v[34:37], v[50:53], v[26:29]
	ds_read_b128 v[116:119], v111 offset:32
	v_mfma_f32_16x16x32_bf16 v[90:93], v[34:37], v[54:57], v[90:93]
	ds_read_b128 v[152:155], v169 offset:32
	v_mfma_f32_16x16x32_bf16 v[22:25], v[34:37], v[58:61], v[22:25]
	ds_read_b128 v[156:159], v169 offset:2080
	v_mfma_f32_16x16x32_bf16 v[86:89], v[34:37], v[62:65], v[86:89]
	ds_read_b128 v[120:123], v111 offset:2080
	v_mfma_f32_16x16x32_bf16 v[18:21], v[38:41], v[50:53], v[18:21]
	ds_read_b128 v[160:163], v169 offset:4128
	v_mfma_f32_16x16x32_bf16 v[82:85], v[38:41], v[54:57], v[82:85]
	ds_read_b128 v[164:167], v169 offset:6176
	v_mfma_f32_16x16x32_bf16 v[14:17], v[38:41], v[58:61], v[14:17]
	ds_read_b128 v[124:127], v111 offset:4128
	v_mfma_f32_16x16x32_bf16 v[78:81], v[38:41], v[62:65], v[78:81]
	ds_read_b128 v[148:151], v111 offset:6176
	v_mfma_f32_16x16x32_bf16 v[10:13], v[42:45], v[50:53], v[10:13]
	v_mfma_f32_16x16x32_bf16 v[74:77], v[42:45], v[54:57], v[74:77]
	v_mfma_f32_16x16x32_bf16 v[6:9], v[42:45], v[58:61], v[6:9]
	v_mfma_f32_16x16x32_bf16 v[70:73], v[42:45], v[62:65], v[70:73]
	v_mfma_f32_16x16x32_bf16 v[2:5], v[46:49], v[50:53], v[2:5]
	v_mfma_f32_16x16x32_bf16 v[66:69], v[46:49], v[54:57], v[66:69]
	v_mfma_f32_16x16x32_bf16 v[30:33], v[46:49], v[58:61], v[30:33]
	v_mfma_f32_16x16x32_bf16 v[94:97], v[46:49], v[62:65], v[94:97]
	s_waitcnt lgkmcnt(0)
	s_waitcnt vmcnt(0)
	s_barrier
	s_add_u32 m0, s4, 0
	v_mfma_f32_16x16x32_bf16 v[26:29], v[116:119], v[152:155], v[26:29]
	ds_read_b128 v[34:37], v100 offset:32800
	global_load_lds_dwordx4 v170, s[12:13] offset:0
	v_mfma_f32_16x16x32_bf16 v[90:93], v[116:119], v[156:159], v[90:93]
	ds_read_b128 v[50:53], v168 offset:32800
	global_load_lds_dwordx4 v171, s[12:13] offset:1024
	v_mfma_f32_16x16x32_bf16 v[22:25], v[116:119], v[160:163], v[22:25]
	ds_read_b128 v[54:57], v168 offset:34848
	global_load_lds_dwordx4 v172, s[12:13] offset:2048
	v_mfma_f32_16x16x32_bf16 v[86:89], v[116:119], v[164:167], v[86:89]
	ds_read_b128 v[38:41], v100 offset:34848
	global_load_lds_dwordx4 v173, s[12:13] offset:3072
	s_add_u32 m0, s4, 16384
	v_mfma_f32_16x16x32_bf16 v[18:21], v[120:123], v[152:155], v[18:21]
	ds_read_b128 v[58:61], v168 offset:36896
	global_load_lds_dwordx4 v170, s[46:47] offset:0
	v_mfma_f32_16x16x32_bf16 v[82:85], v[120:123], v[156:159], v[82:85]
	ds_read_b128 v[62:65], v168 offset:38944
	global_load_lds_dwordx4 v171, s[46:47] offset:1024
	v_mfma_f32_16x16x32_bf16 v[14:17], v[120:123], v[160:163], v[14:17]
	ds_read_b128 v[42:45], v100 offset:36896
	global_load_lds_dwordx4 v172, s[46:47] offset:2048
	v_mfma_f32_16x16x32_bf16 v[78:81], v[120:123], v[164:167], v[78:81]
	ds_read_b128 v[46:49], v100 offset:38944
	global_load_lds_dwordx4 v173, s[46:47] offset:3072
	v_mfma_f32_16x16x32_bf16 v[10:13], v[124:127], v[152:155], v[10:13]
	v_mfma_f32_16x16x32_bf16 v[74:77], v[124:127], v[156:159], v[74:77]
	v_mfma_f32_16x16x32_bf16 v[6:9], v[124:127], v[160:163], v[6:9]
	v_mfma_f32_16x16x32_bf16 v[70:73], v[124:127], v[164:167], v[70:73]
	v_mfma_f32_16x16x32_bf16 v[2:5], v[148:151], v[152:155], v[2:5]
	v_mfma_f32_16x16x32_bf16 v[66:69], v[148:151], v[156:159], v[66:69]
	v_mfma_f32_16x16x32_bf16 v[30:33], v[148:151], v[160:163], v[30:33]
	v_mfma_f32_16x16x32_bf16 v[94:97], v[148:151], v[164:167], v[94:97]
	s_add_u32 s98, s98, 1
	s_and_b32 s98, s98, 15
	s_cmp_eq_u32 s98, 0
	s_cselect_b32 s99, 0x800, 0
	s_add_u32 s12, s12, 0x80
	s_addc_u32 s13, s13, 0
	s_sub_u32 s12, s12, s99
	s_subb_u32 s13, s13, 0
	s_add_u32 s46, s46, 0x80
	s_addc_u32 s47, s47, 0
	s_sub_u32 s46, s46, s99
	s_subb_u32 s47, s47, 0
	s_waitcnt lgkmcnt(0)
	v_mfma_f32_16x16x32_bf16 v[26:29], v[34:37], v[50:53], v[26:29]
	ds_read_b128 v[116:119], v111 offset:32800
	v_mfma_f32_16x16x32_bf16 v[90:93], v[34:37], v[54:57], v[90:93]
	ds_read_b128 v[152:155], v169 offset:32800
	v_mfma_f32_16x16x32_bf16 v[22:25], v[34:37], v[58:61], v[22:25]
	ds_read_b128 v[156:159], v169 offset:34848
	v_mfma_f32_16x16x32_bf16 v[86:89], v[34:37], v[62:65], v[86:89]
	ds_read_b128 v[120:123], v111 offset:34848
	v_mfma_f32_16x16x32_bf16 v[18:21], v[38:41], v[50:53], v[18:21]
	ds_read_b128 v[160:163], v169 offset:36896
	v_mfma_f32_16x16x32_bf16 v[82:85], v[38:41], v[54:57], v[82:85]
	ds_read_b128 v[164:167], v169 offset:38944
	v_mfma_f32_16x16x32_bf16 v[14:17], v[38:41], v[58:61], v[14:17]
	ds_read_b128 v[124:127], v111 offset:36896
	v_mfma_f32_16x16x32_bf16 v[78:81], v[38:41], v[62:65], v[78:81]
	ds_read_b128 v[148:151], v111 offset:38944
	v_mfma_f32_16x16x32_bf16 v[10:13], v[42:45], v[50:53], v[10:13]
	v_mfma_f32_16x16x32_bf16 v[74:77], v[42:45], v[54:57], v[74:77]
	v_mfma_f32_16x16x32_bf16 v[6:9], v[42:45], v[58:61], v[6:9]
	v_mfma_f32_16x16x32_bf16 v[70:73], v[42:45], v[62:65], v[70:73]
	v_mfma_f32_16x16x32_bf16 v[2:5], v[46:49], v[50:53], v[2:5]
	v_mfma_f32_16x16x32_bf16 v[66:69], v[46:49], v[54:57], v[66:69]
	v_mfma_f32_16x16x32_bf16 v[30:33], v[46:49], v[58:61], v[30:33]
	v_mfma_f32_16x16x32_bf16 v[94:97], v[46:49], v[62:65], v[94:97]
	s_waitcnt lgkmcnt(0)
	s_waitcnt vmcnt(0)
	s_add_u32 s11, s11, 1
	s_cmp_lt_u32 s11, 7
	s_cbranch_scc1 .Lk_aol0b_loop
	s_barrier
	s_add_u32 m0, s4, 32768
	v_mfma_f32_16x16x32_bf16 v[26:29], v[116:119], v[152:155], v[26:29]
	ds_read_b128 v[34:37], v100 offset:32
	global_load_lds_dwordx4 v170, s[12:13] offset:0
	v_mfma_f32_16x16x32_bf16 v[90:93], v[116:119], v[156:159], v[90:93]
	ds_read_b128 v[50:53], v168 offset:32
	global_load_lds_dwordx4 v171, s[12:13] offset:1024
	v_mfma_f32_16x16x32_bf16 v[22:25], v[116:119], v[160:163], v[22:25]
	ds_read_b128 v[54:57], v168 offset:2080
	global_load_lds_dwordx4 v172, s[12:13] offset:2048
	v_mfma_f32_16x16x32_bf16 v[86:89], v[116:119], v[164:167], v[86:89]
	ds_read_b128 v[38:41], v100 offset:2080
	global_load_lds_dwordx4 v173, s[12:13] offset:3072
	s_add_u32 m0, s4, 49152
	v_mfma_f32_16x16x32_bf16 v[18:21], v[120:123], v[152:155], v[18:21]
	ds_read_b128 v[58:61], v168 offset:4128
	global_load_lds_dwordx4 v170, s[46:47] offset:0
	v_mfma_f32_16x16x32_bf16 v[82:85], v[120:123], v[156:159], v[82:85]
	ds_read_b128 v[62:65], v168 offset:6176
	global_load_lds_dwordx4 v171, s[46:47] offset:1024
	v_mfma_f32_16x16x32_bf16 v[14:17], v[120:123], v[160:163], v[14:17]
	ds_read_b128 v[42:45], v100 offset:4128
	global_load_lds_dwordx4 v172, s[46:47] offset:2048
	v_mfma_f32_16x16x32_bf16 v[78:81], v[120:123], v[164:167], v[78:81]
	ds_read_b128 v[46:49], v100 offset:6176
	global_load_lds_dwordx4 v173, s[46:47] offset:3072
	v_mfma_f32_16x16x32_bf16 v[10:13], v[124:127], v[152:155], v[10:13]
	v_mfma_f32_16x16x32_bf16 v[74:77], v[124:127], v[156:159], v[74:77]
	v_mfma_f32_16x16x32_bf16 v[6:9], v[124:127], v[160:163], v[6:9]
	v_mfma_f32_16x16x32_bf16 v[70:73], v[124:127], v[164:167], v[70:73]
	v_mfma_f32_16x16x32_bf16 v[2:5], v[148:151], v[152:155], v[2:5]
	v_mfma_f32_16x16x32_bf16 v[66:69], v[148:151], v[156:159], v[66:69]
	v_mfma_f32_16x16x32_bf16 v[30:33], v[148:151], v[160:163], v[30:33]
	v_mfma_f32_16x16x32_bf16 v[94:97], v[148:151], v[164:167], v[94:97]
	s_add_u32 s98, s98, 1
	s_and_b32 s98, s98, 15
	s_cmp_eq_u32 s98, 0
	s_cselect_b32 s99, 0x800, 0
	s_add_u32 s12, s12, 0x80
	s_addc_u32 s13, s13, 0
	s_sub_u32 s12, s12, s99
	s_subb_u32 s13, s13, 0
	s_add_u32 s46, s46, 0x80
	s_addc_u32 s47, s47, 0
	s_sub_u32 s46, s46, s99
	s_subb_u32 s47, s47, 0
	s_waitcnt lgkmcnt(0)
	v_mfma_f32_16x16x32_bf16 v[26:29], v[34:37], v[50:53], v[26:29]
	ds_read_b128 v[116:119], v111 offset:32
	v_mfma_f32_16x16x32_bf16 v[90:93], v[34:37], v[54:57], v[90:93]
	ds_read_b128 v[152:155], v169 offset:32
	v_mfma_f32_16x16x32_bf16 v[22:25], v[34:37], v[58:61], v[22:25]
	ds_read_b128 v[156:159], v169 offset:2080
	v_mfma_f32_16x16x32_bf16 v[86:89], v[34:37], v[62:65], v[86:89]
	ds_read_b128 v[120:123], v111 offset:2080
	v_mfma_f32_16x16x32_bf16 v[18:21], v[38:41], v[50:53], v[18:21]
	ds_read_b128 v[160:163], v169 offset:4128
	v_mfma_f32_16x16x32_bf16 v[82:85], v[38:41], v[54:57], v[82:85]
	ds_read_b128 v[164:167], v169 offset:6176
	v_mfma_f32_16x16x32_bf16 v[14:17], v[38:41], v[58:61], v[14:17]
	ds_read_b128 v[124:127], v111 offset:4128
	v_mfma_f32_16x16x32_bf16 v[78:81], v[38:41], v[62:65], v[78:81]
	ds_read_b128 v[148:151], v111 offset:6176
	v_mfma_f32_16x16x32_bf16 v[10:13], v[42:45], v[50:53], v[10:13]
	v_mfma_f32_16x16x32_bf16 v[74:77], v[42:45], v[54:57], v[74:77]
	v_mfma_f32_16x16x32_bf16 v[6:9], v[42:45], v[58:61], v[6:9]
	v_mfma_f32_16x16x32_bf16 v[70:73], v[42:45], v[62:65], v[70:73]
	v_mfma_f32_16x16x32_bf16 v[2:5], v[46:49], v[50:53], v[2:5]
	v_mfma_f32_16x16x32_bf16 v[66:69], v[46:49], v[54:57], v[66:69]
	v_mfma_f32_16x16x32_bf16 v[30:33], v[46:49], v[58:61], v[30:33]
	v_mfma_f32_16x16x32_bf16 v[94:97], v[46:49], v[62:65], v[94:97]
	s_waitcnt lgkmcnt(0)
	s_waitcnt vmcnt(0)
	s_barrier
	v_mfma_f32_16x16x32_bf16 v[26:29], v[116:119], v[152:155], v[26:29]
	ds_read_b128 v[34:37], v100 offset:32800
	v_mfma_f32_16x16x32_bf16 v[90:93], v[116:119], v[156:159], v[90:93]
	ds_read_b128 v[50:53], v168 offset:32800
	v_mfma_f32_16x16x32_bf16 v[22:25], v[116:119], v[160:163], v[22:25]
	ds_read_b128 v[54:57], v168 offset:34848
	v_mfma_f32_16x16x32_bf16 v[86:89], v[116:119], v[164:167], v[86:89]
	ds_read_b128 v[38:41], v100 offset:34848
	v_mfma_f32_16x16x32_bf16 v[18:21], v[120:123], v[152:155], v[18:21]
	ds_read_b128 v[58:61], v168 offset:36896
	v_mfma_f32_16x16x32_bf16 v[82:85], v[120:123], v[156:159], v[82:85]
	ds_read_b128 v[62:65], v168 offset:38944
	v_mfma_f32_16x16x32_bf16 v[14:17], v[120:123], v[160:163], v[14:17]
	ds_read_b128 v[42:45], v100 offset:36896
	v_mfma_f32_16x16x32_bf16 v[78:81], v[120:123], v[164:167], v[78:81]
	ds_read_b128 v[46:49], v100 offset:38944
	v_mfma_f32_16x16x32_bf16 v[10:13], v[124:127], v[152:155], v[10:13]
	v_mfma_f32_16x16x32_bf16 v[74:77], v[124:127], v[156:159], v[74:77]
	v_mfma_f32_16x16x32_bf16 v[6:9], v[124:127], v[160:163], v[6:9]
	v_mfma_f32_16x16x32_bf16 v[70:73], v[124:127], v[164:167], v[70:73]
	v_mfma_f32_16x16x32_bf16 v[2:5], v[148:151], v[152:155], v[2:5]
	v_mfma_f32_16x16x32_bf16 v[66:69], v[148:151], v[156:159], v[66:69]
	v_mfma_f32_16x16x32_bf16 v[30:33], v[148:151], v[160:163], v[30:33]
	v_mfma_f32_16x16x32_bf16 v[94:97], v[148:151], v[164:167], v[94:97]
	s_waitcnt lgkmcnt(0)
	v_mfma_f32_16x16x32_bf16 v[26:29], v[34:37], v[50:53], v[26:29]
	ds_read_b128 v[116:119], v111 offset:32800
	v_mfma_f32_16x16x32_bf16 v[90:93], v[34:37], v[54:57], v[90:93]
	ds_read_b128 v[152:155], v169 offset:32800
	v_mfma_f32_16x16x32_bf16 v[22:25], v[34:37], v[58:61], v[22:25]
	ds_read_b128 v[156:159], v169 offset:34848
	v_mfma_f32_16x16x32_bf16 v[86:89], v[34:37], v[62:65], v[86:89]
	ds_read_b128 v[120:123], v111 offset:34848
	v_mfma_f32_16x16x32_bf16 v[18:21], v[38:41], v[50:53], v[18:21]
	ds_read_b128 v[160:163], v169 offset:36896
	v_mfma_f32_16x16x32_bf16 v[82:85], v[38:41], v[54:57], v[82:85]
	ds_read_b128 v[164:167], v169 offset:38944
	v_mfma_f32_16x16x32_bf16 v[14:17], v[38:41], v[58:61], v[14:17]
	ds_read_b128 v[124:127], v111 offset:36896
	v_mfma_f32_16x16x32_bf16 v[78:81], v[38:41], v[62:65], v[78:81]
	ds_read_b128 v[148:151], v111 offset:38944
	v_mfma_f32_16x16x32_bf16 v[10:13], v[42:45], v[50:53], v[10:13]
	v_mfma_f32_16x16x32_bf16 v[74:77], v[42:45], v[54:57], v[74:77]
	v_mfma_f32_16x16x32_bf16 v[6:9], v[42:45], v[58:61], v[6:9]
	v_mfma_f32_16x16x32_bf16 v[70:73], v[42:45], v[62:65], v[70:73]
	v_mfma_f32_16x16x32_bf16 v[2:5], v[46:49], v[50:53], v[2:5]
	v_mfma_f32_16x16x32_bf16 v[66:69], v[46:49], v[54:57], v[66:69]
	v_mfma_f32_16x16x32_bf16 v[30:33], v[46:49], v[58:61], v[30:33]
	v_mfma_f32_16x16x32_bf16 v[94:97], v[46:49], v[62:65], v[94:97]
	s_waitcnt lgkmcnt(0)
	v_mfma_f32_16x16x32_bf16 v[26:29], v[116:119], v[152:155], v[26:29]
	v_mfma_f32_16x16x32_bf16 v[90:93], v[116:119], v[156:159], v[90:93]
	v_mfma_f32_16x16x32_bf16 v[22:25], v[116:119], v[160:163], v[22:25]
	v_mfma_f32_16x16x32_bf16 v[86:89], v[116:119], v[164:167], v[86:89]
	v_mfma_f32_16x16x32_bf16 v[18:21], v[120:123], v[152:155], v[18:21]
	v_mfma_f32_16x16x32_bf16 v[82:85], v[120:123], v[156:159], v[82:85]
	v_mfma_f32_16x16x32_bf16 v[14:17], v[120:123], v[160:163], v[14:17]
	v_mfma_f32_16x16x32_bf16 v[78:81], v[120:123], v[164:167], v[78:81]
	v_mfma_f32_16x16x32_bf16 v[10:13], v[124:127], v[152:155], v[10:13]
	v_mfma_f32_16x16x32_bf16 v[74:77], v[124:127], v[156:159], v[74:77]
	v_mfma_f32_16x16x32_bf16 v[6:9], v[124:127], v[160:163], v[6:9]
	v_mfma_f32_16x16x32_bf16 v[70:73], v[124:127], v[164:167], v[70:73]
	v_mfma_f32_16x16x32_bf16 v[2:5], v[148:151], v[152:155], v[2:5]
	v_mfma_f32_16x16x32_bf16 v[66:69], v[148:151], v[156:159], v[66:69]
	v_mfma_f32_16x16x32_bf16 v[30:33], v[148:151], v[160:163], v[30:33]
	v_mfma_f32_16x16x32_bf16 v[94:97], v[148:151], v[164:167], v[94:97]
	s_lshl_b32 s4, s10, 1
	s_barrier
	ds_write2_b32 v129, v26, v90 offset1:16
	ds_write2_b32 v129, v27, v91 offset0:132 offset1:148
	ds_write2_b32 v138, v28, v92 offset0:8 offset1:24
	ds_write2_b32 v138, v29, v93 offset0:140 offset1:156
	ds_write2_b32 v129, v22, v86 offset0:32 offset1:48
	ds_write2_b32 v129, v23, v87 offset0:164 offset1:180
	ds_write2_b32 v138, v24, v88 offset0:40 offset1:56
	ds_write2_b32 v138, v25, v89 offset0:172 offset1:188
	ds_write2_b32 v139, v18, v82 offset0:64 offset1:80
	ds_write2_b32 v139, v19, v83 offset0:196 offset1:212
	ds_write2_b32 v140, v20, v84 offset0:72 offset1:88
	ds_write2_b32 v140, v21, v85 offset0:204 offset1:220
	ds_write2_b32 v139, v14, v78 offset0:96 offset1:112
	ds_write2_b32 v139, v15, v79 offset0:228 offset1:244
	ds_write2_b32 v140, v16, v80 offset0:104 offset1:120
	ds_write2_b32 v140, v17, v81 offset0:236 offset1:252
	ds_write2_b32 v141, v10, v74 offset0:128 offset1:144
	ds_write2_b32 v142, v11, v75 offset0:4 offset1:20
	ds_write2_b32 v142, v12, v76 offset0:136 offset1:152
	ds_write2_b32 v143, v13, v77 offset0:12 offset1:28
	ds_write2_b32 v141, v6, v70 offset0:160 offset1:176
	ds_write2_b32 v142, v7, v71 offset0:36 offset1:52
	ds_write2_b32 v142, v8, v72 offset0:168 offset1:184
	ds_write2_b32 v143, v9, v73 offset0:44 offset1:60
	ds_write2_b32 v144, v2, v66 offset0:192 offset1:208
	ds_write2_b32 v145, v3, v67 offset0:68 offset1:84
	ds_write2_b32 v145, v4, v68 offset0:200 offset1:216
	ds_write2_b32 v146, v5, v69 offset0:76 offset1:92
	ds_write2_b32 v144, v30, v94 offset0:224 offset1:240
	ds_write2_b32 v145, v31, v95 offset0:100 offset1:116
	ds_write2_b32 v145, v32, v96 offset0:232 offset1:248
	ds_write2_b32 v146, v33, v97 offset0:108 offset1:124
	v_lshl_add_u64 v[2:3], v[106:107], 0, s[4:5]
	s_lshl_b32 s4, s34, 10
	s_mul_hi_u32 s10, s34, 0x15555556
	v_or_b32_e32 v4, s4, v134
	s_mulk_i32 s10, 0x3000
	v_or_b32_e32 v5, s4, v132
	v_subrev_u32_e32 v4, s10, v4
	v_subrev_u32_e32 v100, s10, v5
	s_mov_b32 s4, 0
	s_waitcnt lgkmcnt(0)
	s_barrier

.LBB0_634:
	s_and_b32 s31, s30, 0xff
	s_mul_i32 s4, s31, 0xab
	s_lshr_b32 s33, s4, 11
	s_mul_i32 s4, s33, 12
	s_sub_i32 s4, s30, s4
	s_and_b32 s4, s4, 0xff
	s_lshl_b32 s4, s4, 21
	s_or_b32 s4, s4, s23
	s_add_u32 s14, s18, s4
	s_addc_u32 s15, s19, 0
	s_lshl_b32 s4, s33, 18
	s_add_u32 s16, s20, s4
	s_addc_u32 s17, s21, 0
	v_and_b32_e32 v162, 15, v0
	v_bfe_u32 v163, v0, 4, 2
	v_and_b32_e32 v109, 7, v162
	v_xor_b32_e32 v163, v163, v109
	v_lshlrev_b32_e32 v163, 4, v163
	v_lshl_or_b32 v163, v162, 7, v163
	v_bfe_u32 v162, v0, 7, 1
	v_lshl_or_b32 v100, v162, 13, v163
	v_bfe_u32 v162, v0, 6, 1
	v_lshl_or_b32 v156, v162, 13, v163
	v_or_b32_e32 v156, 0x4000, v156
	v_xor_b32_e32 v109, 64, v100
	v_xor_b32_e32 v157, 64, v156
	v_bfe_u32 v162, v0, 3, 3
	v_and_b32_e32 v163, 7, v0
	v_xor_b32_e32 v163, v163, v162
	v_lshlrev_b32_e32 v163, 4, v163
	v_lshl_or_b32 v163, v162, 11, v163
	v_lshrrev_b32_e32 v162, 6, v0
	v_and_b32_e32 v162, 3, v162
	v_lshl_or_b32 v158, v162, 16, v163
	v_add_u32_e32 v159, 0x3c00, v158
	v_add_u32_e32 v160, 0x7800, v158
	v_add_u32_e32 v161, 0xb400, v158
	v_lshlrev_b32_e32 v162, 12, v162
	s_nop 0
	v_readfirstlane_b32 s35, v162
	s_add_u32 s35, s35, 32
	v_mov_b32_e32 v94, 0
	v_mov_b32_e32 v95, 0
	v_mov_b32_e32 v96, 0
	v_mov_b32_e32 v97, 0
	v_mov_b32_e32 v90, 0
	v_mov_b32_e32 v91, 0
	v_mov_b32_e32 v92, 0
	v_mov_b32_e32 v93, 0
	v_mov_b32_e32 v82, 0
	v_mov_b32_e32 v83, 0
	v_mov_b32_e32 v84, 0
	v_mov_b32_e32 v85, 0
	v_mov_b32_e32 v78, 0
	v_mov_b32_e32 v79, 0
	v_mov_b32_e32 v80, 0
	v_mov_b32_e32 v81, 0
	v_mov_b32_e32 v74, 0
	v_mov_b32_e32 v75, 0
	v_mov_b32_e32 v76, 0
	v_mov_b32_e32 v77, 0
	v_mov_b32_e32 v70, 0
	v_mov_b32_e32 v71, 0
	v_mov_b32_e32 v72, 0
	v_mov_b32_e32 v73, 0
	v_mov_b32_e32 v66, 0
	v_mov_b32_e32 v67, 0
	v_mov_b32_e32 v68, 0
	v_mov_b32_e32 v69, 0
	v_mov_b32_e32 v62, 0
	v_mov_b32_e32 v63, 0
	v_mov_b32_e32 v64, 0
	v_mov_b32_e32 v65, 0
	v_mov_b32_e32 v34, 0
	v_mov_b32_e32 v35, 0
	v_mov_b32_e32 v36, 0
	v_mov_b32_e32 v37, 0
	v_mov_b32_e32 v26, 0
	v_mov_b32_e32 v27, 0
	v_mov_b32_e32 v28, 0
	v_mov_b32_e32 v29, 0
	v_mov_b32_e32 v18, 0
	v_mov_b32_e32 v19, 0
	v_mov_b32_e32 v20, 0
	v_mov_b32_e32 v21, 0
	v_mov_b32_e32 v14, 0
	v_mov_b32_e32 v15, 0
	v_mov_b32_e32 v16, 0
	v_mov_b32_e32 v17, 0
	v_mov_b32_e32 v10, 0
	v_mov_b32_e32 v11, 0
	v_mov_b32_e32 v12, 0
	v_mov_b32_e32 v13, 0
	v_mov_b32_e32 v6, 0
	v_mov_b32_e32 v7, 0
	v_mov_b32_e32 v8, 0
	v_mov_b32_e32 v9, 0
	v_mov_b32_e32 v2, 0
	v_mov_b32_e32 v3, 0
	v_mov_b32_e32 v4, 0
	v_mov_b32_e32 v5, 0
	v_mov_b32_e32 v86, 0
	v_mov_b32_e32 v87, 0
	v_mov_b32_e32 v88, 0
	v_mov_b32_e32 v89, 0
	v_mov_b32_e32 v110, 0
	v_mov_b32_e32 v111, 0
	v_mov_b32_e32 v112, 0
	v_mov_b32_e32 v113, 0
	v_mov_b32_e32 v114, 0
	v_mov_b32_e32 v115, 0
	v_mov_b32_e32 v116, 0
	v_mov_b32_e32 v117, 0
	v_mov_b32_e32 v118, 0
	v_mov_b32_e32 v119, 0
	v_mov_b32_e32 v120, 0
	v_mov_b32_e32 v121, 0
	v_mov_b32_e32 v136, 0
	v_mov_b32_e32 v137, 0
	v_mov_b32_e32 v138, 0
	v_mov_b32_e32 v139, 0
	v_mov_b32_e32 v140, 0
	v_mov_b32_e32 v141, 0
	v_mov_b32_e32 v142, 0
	v_mov_b32_e32 v143, 0
	v_mov_b32_e32 v144, 0
	v_mov_b32_e32 v145, 0
	v_mov_b32_e32 v146, 0
	v_mov_b32_e32 v147, 0
	v_mov_b32_e32 v148, 0
	v_mov_b32_e32 v149, 0
	v_mov_b32_e32 v150, 0
	v_mov_b32_e32 v151, 0
	v_mov_b32_e32 v152, 0
	v_mov_b32_e32 v153, 0
	v_mov_b32_e32 v154, 0
	v_mov_b32_e32 v155, 0
	s_waitcnt lgkmcnt(0)
	s_barrier
	v_readlane_b32 s98, v255, 16
	s_lshr_b32 s98, s98, 3
	s_and_b32 s98, s98, 3
	s_lshl_b32 s98, s98, 2
	s_lshl_b32 s99, s98, 7
	s_add_u32 s14, s14, s99
	s_addc_u32 s15, s15, 0
	s_add_u32 s16, s16, s99
	s_addc_u32 s17, s17, 0
	s_add_u32 m0, s35, 0
	s_nop 0
	global_load_lds_dwordx4 v158, s[14:15] offset:0
	global_load_lds_dwordx4 v159, s[14:15] offset:1024
	global_load_lds_dwordx4 v160, s[14:15] offset:2048
	global_load_lds_dwordx4 v161, s[14:15] offset:3072
	s_add_u32 m0, s35, 16384
	s_nop 0
	global_load_lds_dwordx4 v158, s[16:17] offset:0
	global_load_lds_dwordx4 v159, s[16:17] offset:1024
	global_load_lds_dwordx4 v160, s[16:17] offset:2048
	global_load_lds_dwordx4 v161, s[16:17] offset:3072
	s_add_u32 s98, s98, 1
	s_and_b32 s98, s98, 15
	s_cmp_eq_u32 s98, 0
	s_cselect_b32 s99, 0x800, 0
	s_add_u32 s14, s14, 0x80
	s_addc_u32 s15, s15, 0
	s_sub_u32 s14, s14, s99
	s_subb_u32 s15, s15, 0
	s_add_u32 s16, s16, 0x80
	s_addc_u32 s17, s17, 0
	s_sub_u32 s16, s16, s99
	s_subb_u32 s17, s17, 0
	s_mov_b32 s34, 0
	s_waitcnt vmcnt(0)
.Lk_outl0_loop:
	s_barrier
	s_add_u32 m0, s35, 32768
	v_mfma_f32_16x16x32_bf16 v[94:97], v[110:113], v[140:143], v[94:97]
	ds_read_b128 v[22:25], v100 offset:32
	global_load_lds_dwordx4 v158, s[14:15] offset:0
	v_mfma_f32_16x16x32_bf16 v[90:93], v[110:113], v[144:147], v[90:93]
	ds_read_b128 v[46:49], v156 offset:32
	global_load_lds_dwordx4 v159, s[14:15] offset:1024
	v_mfma_f32_16x16x32_bf16 v[82:85], v[110:113], v[148:151], v[82:85]
	ds_read_b128 v[50:53], v156 offset:2080
	global_load_lds_dwordx4 v160, s[14:15] offset:2048
	v_mfma_f32_16x16x32_bf16 v[78:81], v[110:113], v[152:155], v[78:81]
	ds_read_b128 v[30:33], v100 offset:2080
	global_load_lds_dwordx4 v161, s[14:15] offset:3072
	s_add_u32 m0, s35, 49152
	v_mfma_f32_16x16x32_bf16 v[74:77], v[114:117], v[140:143], v[74:77]
	ds_read_b128 v[54:57], v156 offset:4128
	global_load_lds_dwordx4 v158, s[16:17] offset:0
	v_mfma_f32_16x16x32_bf16 v[70:73], v[114:117], v[144:147], v[70:73]
	ds_read_b128 v[58:61], v156 offset:6176
	global_load_lds_dwordx4 v159, s[16:17] offset:1024
	v_mfma_f32_16x16x32_bf16 v[66:69], v[114:117], v[148:151], v[66:69]
	ds_read_b128 v[38:41], v100 offset:4128
	global_load_lds_dwordx4 v160, s[16:17] offset:2048
	v_mfma_f32_16x16x32_bf16 v[62:65], v[114:117], v[152:155], v[62:65]
	ds_read_b128 v[42:45], v100 offset:6176
	global_load_lds_dwordx4 v161, s[16:17] offset:3072
	v_mfma_f32_16x16x32_bf16 v[34:37], v[118:121], v[140:143], v[34:37]
	v_mfma_f32_16x16x32_bf16 v[26:29], v[118:121], v[144:147], v[26:29]
	v_mfma_f32_16x16x32_bf16 v[18:21], v[118:121], v[148:151], v[18:21]
	v_mfma_f32_16x16x32_bf16 v[14:17], v[118:121], v[152:155], v[14:17]
	v_mfma_f32_16x16x32_bf16 v[10:13], v[136:139], v[140:143], v[10:13]
	v_mfma_f32_16x16x32_bf16 v[6:9], v[136:139], v[144:147], v[6:9]
	v_mfma_f32_16x16x32_bf16 v[2:5], v[136:139], v[148:151], v[2:5]
	v_mfma_f32_16x16x32_bf16 v[86:89], v[136:139], v[152:155], v[86:89]
	s_add_u32 s98, s98, 1
	s_and_b32 s98, s98, 15
	s_cmp_eq_u32 s98, 0
	s_cselect_b32 s99, 0x800, 0
	s_add_u32 s14, s14, 0x80
	s_addc_u32 s15, s15, 0
	s_sub_u32 s14, s14, s99
	s_subb_u32 s15, s15, 0
	s_add_u32 s16, s16, 0x80
	s_addc_u32 s17, s17, 0
	s_sub_u32 s16, s16, s99
	s_subb_u32 s17, s17, 0
	s_waitcnt lgkmcnt(0)
	v_mfma_f32_16x16x32_bf16 v[94:97], v[22:25], v[46:49], v[94:97]
	ds_read_b128 v[110:113], v109 offset:32
	v_mfma_f32_16x16x32_bf16 v[90:93], v[22:25], v[50:53], v[90:93]
	ds_read_b128 v[140:143], v157 offset:32
	v_mfma_f32_16x16x32_bf16 v[82:85], v[22:25], v[54:57], v[82:85]
	ds_read_b128 v[144:147], v157 offset:2080
	v_mfma_f32_16x16x32_bf16 v[78:81], v[22:25], v[58:61], v[78:81]
	ds_read_b128 v[114:117], v109 offset:2080
	v_mfma_f32_16x16x32_bf16 v[74:77], v[30:33], v[46:49], v[74:77]
	ds_read_b128 v[148:151], v157 offset:4128
	v_mfma_f32_16x16x32_bf16 v[70:73], v[30:33], v[50:53], v[70:73]
	ds_read_b128 v[152:155], v157 offset:6176
	v_mfma_f32_16x16x32_bf16 v[66:69], v[30:33], v[54:57], v[66:69]
	ds_read_b128 v[118:121], v109 offset:4128
	v_mfma_f32_16x16x32_bf16 v[62:65], v[30:33], v[58:61], v[62:65]
	ds_read_b128 v[136:139], v109 offset:6176
	v_mfma_f32_16x16x32_bf16 v[34:37], v[38:41], v[46:49], v[34:37]
	v_mfma_f32_16x16x32_bf16 v[26:29], v[38:41], v[50:53], v[26:29]
	v_mfma_f32_16x16x32_bf16 v[18:21], v[38:41], v[54:57], v[18:21]
	v_mfma_f32_16x16x32_bf16 v[14:17], v[38:41], v[58:61], v[14:17]
	v_mfma_f32_16x16x32_bf16 v[10:13], v[42:45], v[46:49], v[10:13]
	v_mfma_f32_16x16x32_bf16 v[6:9], v[42:45], v[50:53], v[6:9]
	v_mfma_f32_16x16x32_bf16 v[2:5], v[42:45], v[54:57], v[2:5]
	v_mfma_f32_16x16x32_bf16 v[86:89], v[42:45], v[58:61], v[86:89]
	s_waitcnt lgkmcnt(0)
	s_waitcnt vmcnt(0)
	s_barrier
	s_add_u32 m0, s35, 0
	v_mfma_f32_16x16x32_bf16 v[94:97], v[110:113], v[140:143], v[94:97]
	ds_read_b128 v[22:25], v100 offset:32800
	global_load_lds_dwordx4 v158, s[14:15] offset:0
	v_mfma_f32_16x16x32_bf16 v[90:93], v[110:113], v[144:147], v[90:93]
	ds_read_b128 v[46:49], v156 offset:32800
	global_load_lds_dwordx4 v159, s[14:15] offset:1024
	v_mfma_f32_16x16x32_bf16 v[82:85], v[110:113], v[148:151], v[82:85]
	ds_read_b128 v[50:53], v156 offset:34848
	global_load_lds_dwordx4 v160, s[14:15] offset:2048
	v_mfma_f32_16x16x32_bf16 v[78:81], v[110:113], v[152:155], v[78:81]
	ds_read_b128 v[30:33], v100 offset:34848
	global_load_lds_dwordx4 v161, s[14:15] offset:3072
	s_add_u32 m0, s35, 16384
	v_mfma_f32_16x16x32_bf16 v[74:77], v[114:117], v[140:143], v[74:77]
	ds_read_b128 v[54:57], v156 offset:36896
	global_load_lds_dwordx4 v158, s[16:17] offset:0
	v_mfma_f32_16x16x32_bf16 v[70:73], v[114:117], v[144:147], v[70:73]
	ds_read_b128 v[58:61], v156 offset:38944
	global_load_lds_dwordx4 v159, s[16:17] offset:1024
	v_mfma_f32_16x16x32_bf16 v[66:69], v[114:117], v[148:151], v[66:69]
	ds_read_b128 v[38:41], v100 offset:36896
	global_load_lds_dwordx4 v160, s[16:17] offset:2048
	v_mfma_f32_16x16x32_bf16 v[62:65], v[114:117], v[152:155], v[62:65]
	ds_read_b128 v[42:45], v100 offset:38944
	global_load_lds_dwordx4 v161, s[16:17] offset:3072
	v_mfma_f32_16x16x32_bf16 v[34:37], v[118:121], v[140:143], v[34:37]
	v_mfma_f32_16x16x32_bf16 v[26:29], v[118:121], v[144:147], v[26:29]
	v_mfma_f32_16x16x32_bf16 v[18:21], v[118:121], v[148:151], v[18:21]
	v_mfma_f32_16x16x32_bf16 v[14:17], v[118:121], v[152:155], v[14:17]
	v_mfma_f32_16x16x32_bf16 v[10:13], v[136:139], v[140:143], v[10:13]
	v_mfma_f32_16x16x32_bf16 v[6:9], v[136:139], v[144:147], v[6:9]
	v_mfma_f32_16x16x32_bf16 v[2:5], v[136:139], v[148:151], v[2:5]
	v_mfma_f32_16x16x32_bf16 v[86:89], v[136:139], v[152:155], v[86:89]
	s_add_u32 s98, s98, 1
	s_and_b32 s98, s98, 15
	s_cmp_eq_u32 s98, 0
	s_cselect_b32 s99, 0x800, 0
	s_add_u32 s14, s14, 0x80
	s_addc_u32 s15, s15, 0
	s_sub_u32 s14, s14, s99
	s_subb_u32 s15, s15, 0
	s_add_u32 s16, s16, 0x80
	s_addc_u32 s17, s17, 0
	s_sub_u32 s16, s16, s99
	s_subb_u32 s17, s17, 0
	s_waitcnt lgkmcnt(0)
	v_mfma_f32_16x16x32_bf16 v[94:97], v[22:25], v[46:49], v[94:97]
	ds_read_b128 v[110:113], v109 offset:32800
	v_mfma_f32_16x16x32_bf16 v[90:93], v[22:25], v[50:53], v[90:93]
	ds_read_b128 v[140:143], v157 offset:32800
	v_mfma_f32_16x16x32_bf16 v[82:85], v[22:25], v[54:57], v[82:85]
	ds_read_b128 v[144:147], v157 offset:34848
	v_mfma_f32_16x16x32_bf16 v[78:81], v[22:25], v[58:61], v[78:81]
	ds_read_b128 v[114:117], v109 offset:34848
	v_mfma_f32_16x16x32_bf16 v[74:77], v[30:33], v[46:49], v[74:77]
	ds_read_b128 v[148:151], v157 offset:36896
	v_mfma_f32_16x16x32_bf16 v[70:73], v[30:33], v[50:53], v[70:73]
	ds_read_b128 v[152:155], v157 offset:38944
	v_mfma_f32_16x16x32_bf16 v[66:69], v[30:33], v[54:57], v[66:69]
	ds_read_b128 v[118:121], v109 offset:36896
	v_mfma_f32_16x16x32_bf16 v[62:65], v[30:33], v[58:61], v[62:65]
	ds_read_b128 v[136:139], v109 offset:38944
	v_mfma_f32_16x16x32_bf16 v[34:37], v[38:41], v[46:49], v[34:37]
	v_mfma_f32_16x16x32_bf16 v[26:29], v[38:41], v[50:53], v[26:29]
	v_mfma_f32_16x16x32_bf16 v[18:21], v[38:41], v[54:57], v[18:21]
	v_mfma_f32_16x16x32_bf16 v[14:17], v[38:41], v[58:61], v[14:17]
	v_mfma_f32_16x16x32_bf16 v[10:13], v[42:45], v[46:49], v[10:13]
	v_mfma_f32_16x16x32_bf16 v[6:9], v[42:45], v[50:53], v[6:9]
	v_mfma_f32_16x16x32_bf16 v[2:5], v[42:45], v[54:57], v[2:5]
	v_mfma_f32_16x16x32_bf16 v[86:89], v[42:45], v[58:61], v[86:89]
	s_waitcnt lgkmcnt(0)
	s_waitcnt vmcnt(0)
	s_add_u32 s34, s34, 1
	s_cmp_lt_u32 s34, 7
	s_cbranch_scc1 .Lk_outl0_loop
	s_barrier
	s_add_u32 m0, s35, 32768
	v_mfma_f32_16x16x32_bf16 v[94:97], v[110:113], v[140:143], v[94:97]
	ds_read_b128 v[22:25], v100 offset:32
	global_load_lds_dwordx4 v158, s[14:15] offset:0
	v_mfma_f32_16x16x32_bf16 v[90:93], v[110:113], v[144:147], v[90:93]
	ds_read_b128 v[46:49], v156 offset:32
	global_load_lds_dwordx4 v159, s[14:15] offset:1024
	v_mfma_f32_16x16x32_bf16 v[82:85], v[110:113], v[148:151], v[82:85]
	ds_read_b128 v[50:53], v156 offset:2080
	global_load_lds_dwordx4 v160, s[14:15] offset:2048
	v_mfma_f32_16x16x32_bf16 v[78:81], v[110:113], v[152:155], v[78:81]
	ds_read_b128 v[30:33], v100 offset:2080
	global_load_lds_dwordx4 v161, s[14:15] offset:3072
	s_add_u32 m0, s35, 49152
	v_mfma_f32_16x16x32_bf16 v[74:77], v[114:117], v[140:143], v[74:77]
	ds_read_b128 v[54:57], v156 offset:4128
	global_load_lds_dwordx4 v158, s[16:17] offset:0
	v_mfma_f32_16x16x32_bf16 v[70:73], v[114:117], v[144:147], v[70:73]
	ds_read_b128 v[58:61], v156 offset:6176
	global_load_lds_dwordx4 v159, s[16:17] offset:1024
	v_mfma_f32_16x16x32_bf16 v[66:69], v[114:117], v[148:151], v[66:69]
	ds_read_b128 v[38:41], v100 offset:4128
	global_load_lds_dwordx4 v160, s[16:17] offset:2048
	v_mfma_f32_16x16x32_bf16 v[62:65], v[114:117], v[152:155], v[62:65]
	ds_read_b128 v[42:45], v100 offset:6176
	global_load_lds_dwordx4 v161, s[16:17] offset:3072
	v_mfma_f32_16x16x32_bf16 v[34:37], v[118:121], v[140:143], v[34:37]
	v_mfma_f32_16x16x32_bf16 v[26:29], v[118:121], v[144:147], v[26:29]
	v_mfma_f32_16x16x32_bf16 v[18:21], v[118:121], v[148:151], v[18:21]
	v_mfma_f32_16x16x32_bf16 v[14:17], v[118:121], v[152:155], v[14:17]
	v_mfma_f32_16x16x32_bf16 v[10:13], v[136:139], v[140:143], v[10:13]
	v_mfma_f32_16x16x32_bf16 v[6:9], v[136:139], v[144:147], v[6:9]
	v_mfma_f32_16x16x32_bf16 v[2:5], v[136:139], v[148:151], v[2:5]
	v_mfma_f32_16x16x32_bf16 v[86:89], v[136:139], v[152:155], v[86:89]
	s_add_u32 s98, s98, 1
	s_and_b32 s98, s98, 15
	s_cmp_eq_u32 s98, 0
	s_cselect_b32 s99, 0x800, 0
	s_add_u32 s14, s14, 0x80
	s_addc_u32 s15, s15, 0
	s_sub_u32 s14, s14, s99
	s_subb_u32 s15, s15, 0
	s_add_u32 s16, s16, 0x80
	s_addc_u32 s17, s17, 0
	s_sub_u32 s16, s16, s99
	s_subb_u32 s17, s17, 0
	s_waitcnt lgkmcnt(0)
	v_mfma_f32_16x16x32_bf16 v[94:97], v[22:25], v[46:49], v[94:97]
	ds_read_b128 v[110:113], v109 offset:32
	v_mfma_f32_16x16x32_bf16 v[90:93], v[22:25], v[50:53], v[90:93]
	ds_read_b128 v[140:143], v157 offset:32
	v_mfma_f32_16x16x32_bf16 v[82:85], v[22:25], v[54:57], v[82:85]
	ds_read_b128 v[144:147], v157 offset:2080
	v_mfma_f32_16x16x32_bf16 v[78:81], v[22:25], v[58:61], v[78:81]
	ds_read_b128 v[114:117], v109 offset:2080
	v_mfma_f32_16x16x32_bf16 v[74:77], v[30:33], v[46:49], v[74:77]
	ds_read_b128 v[148:151], v157 offset:4128
	v_mfma_f32_16x16x32_bf16 v[70:73], v[30:33], v[50:53], v[70:73]
	ds_read_b128 v[152:155], v157 offset:6176
	v_mfma_f32_16x16x32_bf16 v[66:69], v[30:33], v[54:57], v[66:69]
	ds_read_b128 v[118:121], v109 offset:4128
	v_mfma_f32_16x16x32_bf16 v[62:65], v[30:33], v[58:61], v[62:65]
	ds_read_b128 v[136:139], v109 offset:6176
	v_mfma_f32_16x16x32_bf16 v[34:37], v[38:41], v[46:49], v[34:37]
	v_mfma_f32_16x16x32_bf16 v[26:29], v[38:41], v[50:53], v[26:29]
	v_mfma_f32_16x16x32_bf16 v[18:21], v[38:41], v[54:57], v[18:21]
	v_mfma_f32_16x16x32_bf16 v[14:17], v[38:41], v[58:61], v[14:17]
	v_mfma_f32_16x16x32_bf16 v[10:13], v[42:45], v[46:49], v[10:13]
	v_mfma_f32_16x16x32_bf16 v[6:9], v[42:45], v[50:53], v[6:9]
	v_mfma_f32_16x16x32_bf16 v[2:5], v[42:45], v[54:57], v[2:5]
	v_mfma_f32_16x16x32_bf16 v[86:89], v[42:45], v[58:61], v[86:89]
	s_waitcnt lgkmcnt(0)
	s_waitcnt vmcnt(0)
	s_barrier
	v_mfma_f32_16x16x32_bf16 v[94:97], v[110:113], v[140:143], v[94:97]
	ds_read_b128 v[22:25], v100 offset:32800
	v_mfma_f32_16x16x32_bf16 v[90:93], v[110:113], v[144:147], v[90:93]
	ds_read_b128 v[46:49], v156 offset:32800
	v_mfma_f32_16x16x32_bf16 v[82:85], v[110:113], v[148:151], v[82:85]
	ds_read_b128 v[50:53], v156 offset:34848
	v_mfma_f32_16x16x32_bf16 v[78:81], v[110:113], v[152:155], v[78:81]
	ds_read_b128 v[30:33], v100 offset:34848
	v_mfma_f32_16x16x32_bf16 v[74:77], v[114:117], v[140:143], v[74:77]
	ds_read_b128 v[54:57], v156 offset:36896
	v_mfma_f32_16x16x32_bf16 v[70:73], v[114:117], v[144:147], v[70:73]
	ds_read_b128 v[58:61], v156 offset:38944
	v_mfma_f32_16x16x32_bf16 v[66:69], v[114:117], v[148:151], v[66:69]
	ds_read_b128 v[38:41], v100 offset:36896
	v_mfma_f32_16x16x32_bf16 v[62:65], v[114:117], v[152:155], v[62:65]
	ds_read_b128 v[42:45], v100 offset:38944
	v_mfma_f32_16x16x32_bf16 v[34:37], v[118:121], v[140:143], v[34:37]
	v_mfma_f32_16x16x32_bf16 v[26:29], v[118:121], v[144:147], v[26:29]
	v_mfma_f32_16x16x32_bf16 v[18:21], v[118:121], v[148:151], v[18:21]
	v_mfma_f32_16x16x32_bf16 v[14:17], v[118:121], v[152:155], v[14:17]
	v_mfma_f32_16x16x32_bf16 v[10:13], v[136:139], v[140:143], v[10:13]
	v_mfma_f32_16x16x32_bf16 v[6:9], v[136:139], v[144:147], v[6:9]
	v_mfma_f32_16x16x32_bf16 v[2:5], v[136:139], v[148:151], v[2:5]
	v_mfma_f32_16x16x32_bf16 v[86:89], v[136:139], v[152:155], v[86:89]
	s_waitcnt lgkmcnt(0)
	v_mfma_f32_16x16x32_bf16 v[94:97], v[22:25], v[46:49], v[94:97]
	ds_read_b128 v[110:113], v109 offset:32800
	v_mfma_f32_16x16x32_bf16 v[90:93], v[22:25], v[50:53], v[90:93]
	ds_read_b128 v[140:143], v157 offset:32800
	v_mfma_f32_16x16x32_bf16 v[82:85], v[22:25], v[54:57], v[82:85]
	ds_read_b128 v[144:147], v157 offset:34848
	v_mfma_f32_16x16x32_bf16 v[78:81], v[22:25], v[58:61], v[78:81]
	ds_read_b128 v[114:117], v109 offset:34848
	v_mfma_f32_16x16x32_bf16 v[74:77], v[30:33], v[46:49], v[74:77]
	ds_read_b128 v[148:151], v157 offset:36896
	v_mfma_f32_16x16x32_bf16 v[70:73], v[30:33], v[50:53], v[70:73]
	ds_read_b128 v[152:155], v157 offset:38944
	v_mfma_f32_16x16x32_bf16 v[66:69], v[30:33], v[54:57], v[66:69]
	ds_read_b128 v[118:121], v109 offset:36896
	v_mfma_f32_16x16x32_bf16 v[62:65], v[30:33], v[58:61], v[62:65]
	ds_read_b128 v[136:139], v109 offset:38944
	v_mfma_f32_16x16x32_bf16 v[34:37], v[38:41], v[46:49], v[34:37]
	v_mfma_f32_16x16x32_bf16 v[26:29], v[38:41], v[50:53], v[26:29]
	v_mfma_f32_16x16x32_bf16 v[18:21], v[38:41], v[54:57], v[18:21]
	v_mfma_f32_16x16x32_bf16 v[14:17], v[38:41], v[58:61], v[14:17]
	v_mfma_f32_16x16x32_bf16 v[10:13], v[42:45], v[46:49], v[10:13]
	v_mfma_f32_16x16x32_bf16 v[6:9], v[42:45], v[50:53], v[6:9]
	v_mfma_f32_16x16x32_bf16 v[2:5], v[42:45], v[54:57], v[2:5]
	v_mfma_f32_16x16x32_bf16 v[86:89], v[42:45], v[58:61], v[86:89]
	s_waitcnt lgkmcnt(0)
	v_mfma_f32_16x16x32_bf16 v[94:97], v[110:113], v[140:143], v[94:97]
	v_mfma_f32_16x16x32_bf16 v[90:93], v[110:113], v[144:147], v[90:93]
	v_mfma_f32_16x16x32_bf16 v[82:85], v[110:113], v[148:151], v[82:85]
	v_mfma_f32_16x16x32_bf16 v[78:81], v[110:113], v[152:155], v[78:81]
	v_mfma_f32_16x16x32_bf16 v[74:77], v[114:117], v[140:143], v[74:77]
	v_mfma_f32_16x16x32_bf16 v[70:73], v[114:117], v[144:147], v[70:73]
	v_mfma_f32_16x16x32_bf16 v[66:69], v[114:117], v[148:151], v[66:69]
	v_mfma_f32_16x16x32_bf16 v[62:65], v[114:117], v[152:155], v[62:65]
	v_mfma_f32_16x16x32_bf16 v[34:37], v[118:121], v[140:143], v[34:37]
	v_mfma_f32_16x16x32_bf16 v[26:29], v[118:121], v[144:147], v[26:29]
	v_mfma_f32_16x16x32_bf16 v[18:21], v[118:121], v[148:151], v[18:21]
	v_mfma_f32_16x16x32_bf16 v[14:17], v[118:121], v[152:155], v[14:17]
	v_mfma_f32_16x16x32_bf16 v[10:13], v[136:139], v[140:143], v[10:13]
	v_mfma_f32_16x16x32_bf16 v[6:9], v[136:139], v[144:147], v[6:9]
	v_mfma_f32_16x16x32_bf16 v[2:5], v[136:139], v[148:151], v[2:5]
	v_mfma_f32_16x16x32_bf16 v[86:89], v[136:139], v[152:155], v[86:89]
	s_waitcnt vmcnt(7)
	v_add_u32_e32 v22, 0x400, v123
	s_barrier
	ds_write2_b32 v123, v94, v90 offset1:16
	ds_write2_b32 v123, v95, v91 offset0:132 offset1:148
	ds_write2_b32 v22, v96, v92 offset0:8 offset1:24
	ds_write2_b32 v22, v97, v93 offset0:140 offset1:156
	ds_write2_b32 v123, v82, v78 offset0:32 offset1:48
	ds_write2_b32 v123, v83, v79 offset0:164 offset1:180
	ds_write2_b32 v22, v84, v80 offset0:40 offset1:56
	ds_write2_b32 v22, v85, v81 offset0:172 offset1:188
	v_add_u32_e32 v22, 0x2000, v123
	v_add_u32_e32 v23, 0x2400, v123
	ds_write2_b32 v22, v74, v70 offset0:64 offset1:80
	ds_write2_b32 v22, v75, v71 offset0:196 offset1:212
	ds_write2_b32 v23, v76, v72 offset0:72 offset1:88
	ds_write2_b32 v23, v77, v73 offset0:204 offset1:220
	ds_write2_b32 v22, v66, v62 offset0:96 offset1:112
	ds_write2_b32 v22, v67, v63 offset0:228 offset1:244
	ds_write2_b32 v23, v68, v64 offset0:104 offset1:120
	ds_write2_b32 v23, v69, v65 offset0:236 offset1:252
	v_add_u32_e32 v22, 0x4000, v123
	v_add_u32_e32 v23, 0x4400, v123
	v_add_u32_e32 v24, 0x4800, v123
	ds_write2_b32 v22, v34, v26 offset0:128 offset1:144
	ds_write2_b32 v23, v35, v27 offset0:4 offset1:20
	ds_write2_b32 v23, v36, v28 offset0:136 offset1:152
	ds_write2_b32 v24, v37, v29 offset0:12 offset1:28
	ds_write2_b32 v22, v18, v14 offset0:160 offset1:176
	ds_write2_b32 v23, v19, v15 offset0:36 offset1:52
	ds_write2_b32 v23, v20, v16 offset0:168 offset1:184
	ds_write2_b32 v24, v21, v17 offset0:44 offset1:60
	v_add_u32_e32 v14, 0x6000, v123
	ds_write2_b32 v14, v10, v6 offset0:192 offset1:208
	v_add_u32_e32 v6, 0x6400, v123
	ds_write2_b32 v6, v11, v7 offset0:68 offset1:84
	ds_write2_b32 v6, v12, v8 offset0:200 offset1:216
	v_add_u32_e32 v7, 0x6800, v123
	s_lshl_b32 s4, s33, 9
	ds_write2_b32 v7, v13, v9 offset0:76 offset1:92
	ds_write2_b32 v14, v2, v86 offset0:224 offset1:240
	ds_write2_b32 v6, v3, v87 offset0:100 offset1:116
	ds_write2_b32 v6, v4, v88 offset0:232 offset1:248
	ds_write2_b32 v7, v5, v89 offset0:108 offset1:124
	v_lshl_add_u64 v[2:3], v[102:103], 0, s[4:5]
	v_lshl_add_u64 v[4:5], v[104:105], 0, s[4:5]
	s_lshl_b32 s4, s31, 10
	s_mul_hi_u32 s14, s31, 0x15555556
	s_lshl_b32 s15, s33, 7
	v_or_b32_e32 v6, s4, v125
	s_mulk_i32 s14, 0x3000
	v_or_b32_e32 v7, s4, v127
	v_or_b32_e32 v8, s4, v129
	v_or_b32_e32 v9, s4, v133
	v_subrev_u32_e32 v6, s14, v6
	v_subrev_u32_e32 v7, s14, v7
	v_subrev_u32_e32 v8, s14, v8
	v_subrev_u32_e32 v9, s14, v9
	s_mov_b32 s14, 0
	s_lshl_b32 s4, s15, 2
	v_mov_b32_e32 v10, v132
	v_mov_b32_e32 v11, v128
	v_mov_b32_e32 v12, v126
	v_mov_b32_e32 v13, v124
	s_waitcnt lgkmcnt(0)
	s_barrier

.LBB0_786:
	s_lshl_b32 s10, s48, 7
	s_xor_b64 s[46:47], s[50:51], -1
	s_or_b32 s50, s31, s10
	s_mov_b32 s51, s75
	s_lshl_b64 s[50:51], s[50:51], 11
	s_add_u32 s50, s54, s50
	s_addc_u32 s51, s55, s51
	s_waitcnt lgkmcnt(0)
	s_lshl_b32 s98, s30, 11
	s_add_u32 s98, s52, s98
	s_addc_u32 s99, s53, 0
	v_and_b32_e32 v222, 15, v0
	v_bfe_u32 v223, v0, 4, 2
	v_and_b32_e32 v141, 7, v222
	v_xor_b32_e32 v223, v223, v141
	v_lshlrev_b32_e32 v223, 4, v223
	v_lshl_or_b32 v223, v222, 7, v223
	v_bfe_u32 v222, v0, 7, 1
	v_lshl_or_b32 v140, v222, 13, v223
	v_bfe_u32 v222, v0, 6, 1
	v_lshl_or_b32 v216, v222, 13, v223
	v_or_b32_e32 v216, 0x4000, v216
	v_xor_b32_e32 v141, 64, v140
	v_xor_b32_e32 v217, 64, v216
	v_bfe_u32 v222, v0, 3, 3
	v_and_b32_e32 v223, 7, v0
	v_xor_b32_e32 v223, v223, v222
	v_lshlrev_b32_e32 v223, 4, v223
	v_lshl_or_b32 v223, v222, 11, v223
	v_lshrrev_b32_e32 v222, 6, v0
	v_and_b32_e32 v222, 3, v222
	v_lshl_or_b32 v218, v222, 16, v223
	v_add_u32_e32 v219, 0x3c00, v218
	v_add_u32_e32 v220, 0x7800, v218
	v_add_u32_e32 v221, 0xb400, v218
	v_lshlrev_b32_e32 v222, 12, v222
	s_nop 0
	v_readfirstlane_b32 s101, v222
	s_add_u32 s101, s101, 32
	v_mov_b32_e32 v86, 0
	v_mov_b32_e32 v87, 0
	v_mov_b32_e32 v88, 0
	v_mov_b32_e32 v89, 0
	v_mov_b32_e32 v82, 0
	v_mov_b32_e32 v83, 0
	v_mov_b32_e32 v84, 0
	v_mov_b32_e32 v85, 0
	v_mov_b32_e32 v78, 0
	v_mov_b32_e32 v79, 0
	v_mov_b32_e32 v80, 0
	v_mov_b32_e32 v81, 0
	v_mov_b32_e32 v74, 0
	v_mov_b32_e32 v75, 0
	v_mov_b32_e32 v76, 0
	v_mov_b32_e32 v77, 0
	v_mov_b32_e32 v70, 0
	v_mov_b32_e32 v71, 0
	v_mov_b32_e32 v72, 0
	v_mov_b32_e32 v73, 0
	v_mov_b32_e32 v90, 0
	v_mov_b32_e32 v91, 0
	v_mov_b32_e32 v92, 0
	v_mov_b32_e32 v93, 0
	v_mov_b32_e32 v94, 0
	v_mov_b32_e32 v95, 0
	v_mov_b32_e32 v96, 0
	v_mov_b32_e32 v97, 0
	v_mov_b32_e32 v6, 0
	v_mov_b32_e32 v7, 0
	v_mov_b32_e32 v8, 0
	v_mov_b32_e32 v9, 0
	v_mov_b32_e32 v2, 0
	v_mov_b32_e32 v3, 0
	v_mov_b32_e32 v4, 0
	v_mov_b32_e32 v5, 0
	v_mov_b32_e32 v10, 0
	v_mov_b32_e32 v11, 0
	v_mov_b32_e32 v12, 0
	v_mov_b32_e32 v13, 0
	v_mov_b32_e32 v14, 0
	v_mov_b32_e32 v15, 0
	v_mov_b32_e32 v16, 0
	v_mov_b32_e32 v17, 0
	v_mov_b32_e32 v26, 0
	v_mov_b32_e32 v27, 0
	v_mov_b32_e32 v28, 0
	v_mov_b32_e32 v29, 0
	v_mov_b32_e32 v34, 0
	v_mov_b32_e32 v35, 0
	v_mov_b32_e32 v36, 0
	v_mov_b32_e32 v37, 0
	v_mov_b32_e32 v30, 0
	v_mov_b32_e32 v31, 0
	v_mov_b32_e32 v32, 0
	v_mov_b32_e32 v33, 0
	v_mov_b32_e32 v22, 0
	v_mov_b32_e32 v23, 0
	v_mov_b32_e32 v24, 0
	v_mov_b32_e32 v25, 0
	v_mov_b32_e32 v18, 0
	v_mov_b32_e32 v19, 0
	v_mov_b32_e32 v20, 0
	v_mov_b32_e32 v21, 0
	v_mov_b32_e32 v136, 0
	v_mov_b32_e32 v137, 0
	v_mov_b32_e32 v138, 0
	v_mov_b32_e32 v139, 0
	v_mov_b32_e32 v188, 0
	v_mov_b32_e32 v189, 0
	v_mov_b32_e32 v190, 0
	v_mov_b32_e32 v191, 0
	v_mov_b32_e32 v192, 0
	v_mov_b32_e32 v193, 0
	v_mov_b32_e32 v194, 0
	v_mov_b32_e32 v195, 0
	v_mov_b32_e32 v196, 0
	v_mov_b32_e32 v197, 0
	v_mov_b32_e32 v198, 0
	v_mov_b32_e32 v199, 0
	v_mov_b32_e32 v200, 0
	v_mov_b32_e32 v201, 0
	v_mov_b32_e32 v202, 0
	v_mov_b32_e32 v203, 0
	v_mov_b32_e32 v204, 0
	v_mov_b32_e32 v205, 0
	v_mov_b32_e32 v206, 0
	v_mov_b32_e32 v207, 0
	v_mov_b32_e32 v208, 0
	v_mov_b32_e32 v209, 0
	v_mov_b32_e32 v210, 0
	v_mov_b32_e32 v211, 0
	v_mov_b32_e32 v212, 0
	v_mov_b32_e32 v213, 0
	v_mov_b32_e32 v214, 0
	v_mov_b32_e32 v215, 0
	s_waitcnt lgkmcnt(0)
	s_barrier
	v_readlane_b32 s49, v255, 16
	s_lshr_b32 s49, s49, 3
	s_and_b32 s49, s49, 3
	s_lshl_b32 s49, s49, 2
	s_lshl_b32 s10, s49, 7
	s_add_u32 s98, s98, s10
	s_addc_u32 s99, s99, 0
	s_add_u32 s50, s50, s10
	s_addc_u32 s51, s51, 0
	s_add_u32 m0, s101, 0
	s_nop 0
	global_load_lds_dwordx4 v218, s[98:99] offset:0
	global_load_lds_dwordx4 v219, s[98:99] offset:1024
	global_load_lds_dwordx4 v220, s[98:99] offset:2048
	global_load_lds_dwordx4 v221, s[98:99] offset:3072
	s_add_u32 m0, s101, 16384
	s_nop 0
	global_load_lds_dwordx4 v218, s[50:51] offset:0
	global_load_lds_dwordx4 v219, s[50:51] offset:1024
	global_load_lds_dwordx4 v220, s[50:51] offset:2048
	global_load_lds_dwordx4 v221, s[50:51] offset:3072
	s_add_u32 s49, s49, 1
	s_and_b32 s49, s49, 15
	s_cmp_eq_u32 s49, 0
	s_cselect_b32 s10, 0x800, 0
	s_add_u32 s98, s98, 0x80
	s_addc_u32 s99, s99, 0
	s_sub_u32 s98, s98, s10
	s_subb_u32 s99, s99, 0
	s_add_u32 s50, s50, 0x80
	s_addc_u32 s51, s51, 0
	s_sub_u32 s50, s50, s10
	s_subb_u32 s51, s51, 0
	s_mov_b32 s100, 0
	s_waitcnt vmcnt(0)
.Lk_pq0_loop:
	s_barrier
	s_add_u32 m0, s101, 32768
	v_mfma_f32_16x16x32_bf16 v[86:89], v[136:139], v[200:203], v[86:89]
	ds_read_b128 v[38:41], v140 offset:32
	global_load_lds_dwordx4 v218, s[98:99] offset:0
	v_mfma_f32_16x16x32_bf16 v[82:85], v[136:139], v[204:207], v[82:85]
	ds_read_b128 v[54:57], v216 offset:32
	global_load_lds_dwordx4 v219, s[98:99] offset:1024
	v_mfma_f32_16x16x32_bf16 v[78:81], v[136:139], v[208:211], v[78:81]
	ds_read_b128 v[58:61], v216 offset:2080
	global_load_lds_dwordx4 v220, s[98:99] offset:2048
	v_mfma_f32_16x16x32_bf16 v[74:77], v[136:139], v[212:215], v[74:77]
	ds_read_b128 v[42:45], v140 offset:2080
	global_load_lds_dwordx4 v221, s[98:99] offset:3072
	s_add_u32 m0, s101, 49152
	v_mfma_f32_16x16x32_bf16 v[70:73], v[188:191], v[200:203], v[70:73]
	ds_read_b128 v[62:65], v216 offset:4128
	global_load_lds_dwordx4 v218, s[50:51] offset:0
	v_mfma_f32_16x16x32_bf16 v[90:93], v[188:191], v[204:207], v[90:93]
	ds_read_b128 v[66:69], v216 offset:6176
	global_load_lds_dwordx4 v219, s[50:51] offset:1024
	v_mfma_f32_16x16x32_bf16 v[94:97], v[188:191], v[208:211], v[94:97]
	ds_read_b128 v[46:49], v140 offset:4128
	global_load_lds_dwordx4 v220, s[50:51] offset:2048
	v_mfma_f32_16x16x32_bf16 v[6:9], v[188:191], v[212:215], v[6:9]
	ds_read_b128 v[50:53], v140 offset:6176
	global_load_lds_dwordx4 v221, s[50:51] offset:3072
	v_mfma_f32_16x16x32_bf16 v[2:5], v[192:195], v[200:203], v[2:5]
	v_mfma_f32_16x16x32_bf16 v[10:13], v[192:195], v[204:207], v[10:13]
	v_mfma_f32_16x16x32_bf16 v[14:17], v[192:195], v[208:211], v[14:17]
	v_mfma_f32_16x16x32_bf16 v[26:29], v[192:195], v[212:215], v[26:29]
	v_mfma_f32_16x16x32_bf16 v[34:37], v[196:199], v[200:203], v[34:37]
	v_mfma_f32_16x16x32_bf16 v[30:33], v[196:199], v[204:207], v[30:33]
	v_mfma_f32_16x16x32_bf16 v[22:25], v[196:199], v[208:211], v[22:25]
	v_mfma_f32_16x16x32_bf16 v[18:21], v[196:199], v[212:215], v[18:21]
	s_add_u32 s49, s49, 1
	s_and_b32 s49, s49, 15
	s_cmp_eq_u32 s49, 0
	s_cselect_b32 s10, 0x800, 0
	s_add_u32 s98, s98, 0x80
	s_addc_u32 s99, s99, 0
	s_sub_u32 s98, s98, s10
	s_subb_u32 s99, s99, 0
	s_add_u32 s50, s50, 0x80
	s_addc_u32 s51, s51, 0
	s_sub_u32 s50, s50, s10
	s_subb_u32 s51, s51, 0
	s_waitcnt lgkmcnt(0)
	v_mfma_f32_16x16x32_bf16 v[86:89], v[38:41], v[54:57], v[86:89]
	ds_read_b128 v[136:139], v141 offset:32
	v_mfma_f32_16x16x32_bf16 v[82:85], v[38:41], v[58:61], v[82:85]
	ds_read_b128 v[200:203], v217 offset:32
	v_mfma_f32_16x16x32_bf16 v[78:81], v[38:41], v[62:65], v[78:81]
	ds_read_b128 v[204:207], v217 offset:2080
	v_mfma_f32_16x16x32_bf16 v[74:77], v[38:41], v[66:69], v[74:77]
	ds_read_b128 v[188:191], v141 offset:2080
	v_mfma_f32_16x16x32_bf16 v[70:73], v[42:45], v[54:57], v[70:73]
	ds_read_b128 v[208:211], v217 offset:4128
	v_mfma_f32_16x16x32_bf16 v[90:93], v[42:45], v[58:61], v[90:93]
	ds_read_b128 v[212:215], v217 offset:6176
	v_mfma_f32_16x16x32_bf16 v[94:97], v[42:45], v[62:65], v[94:97]
	ds_read_b128 v[192:195], v141 offset:4128
	v_mfma_f32_16x16x32_bf16 v[6:9], v[42:45], v[66:69], v[6:9]
	ds_read_b128 v[196:199], v141 offset:6176
	v_mfma_f32_16x16x32_bf16 v[2:5], v[46:49], v[54:57], v[2:5]
	v_mfma_f32_16x16x32_bf16 v[10:13], v[46:49], v[58:61], v[10:13]
	v_mfma_f32_16x16x32_bf16 v[14:17], v[46:49], v[62:65], v[14:17]
	v_mfma_f32_16x16x32_bf16 v[26:29], v[46:49], v[66:69], v[26:29]
	v_mfma_f32_16x16x32_bf16 v[34:37], v[50:53], v[54:57], v[34:37]
	v_mfma_f32_16x16x32_bf16 v[30:33], v[50:53], v[58:61], v[30:33]
	v_mfma_f32_16x16x32_bf16 v[22:25], v[50:53], v[62:65], v[22:25]
	v_mfma_f32_16x16x32_bf16 v[18:21], v[50:53], v[66:69], v[18:21]
	s_waitcnt lgkmcnt(0)
	s_waitcnt vmcnt(0)
	s_barrier
	s_add_u32 m0, s101, 0
	v_mfma_f32_16x16x32_bf16 v[86:89], v[136:139], v[200:203], v[86:89]
	ds_read_b128 v[38:41], v140 offset:32800
	global_load_lds_dwordx4 v218, s[98:99] offset:0
	v_mfma_f32_16x16x32_bf16 v[82:85], v[136:139], v[204:207], v[82:85]
	ds_read_b128 v[54:57], v216 offset:32800
	global_load_lds_dwordx4 v219, s[98:99] offset:1024
	v_mfma_f32_16x16x32_bf16 v[78:81], v[136:139], v[208:211], v[78:81]
	ds_read_b128 v[58:61], v216 offset:34848
	global_load_lds_dwordx4 v220, s[98:99] offset:2048
	v_mfma_f32_16x16x32_bf16 v[74:77], v[136:139], v[212:215], v[74:77]
	ds_read_b128 v[42:45], v140 offset:34848
	global_load_lds_dwordx4 v221, s[98:99] offset:3072
	s_add_u32 m0, s101, 16384
	v_mfma_f32_16x16x32_bf16 v[70:73], v[188:191], v[200:203], v[70:73]
	ds_read_b128 v[62:65], v216 offset:36896
	global_load_lds_dwordx4 v218, s[50:51] offset:0
	v_mfma_f32_16x16x32_bf16 v[90:93], v[188:191], v[204:207], v[90:93]
	ds_read_b128 v[66:69], v216 offset:38944
	global_load_lds_dwordx4 v219, s[50:51] offset:1024
	v_mfma_f32_16x16x32_bf16 v[94:97], v[188:191], v[208:211], v[94:97]
	ds_read_b128 v[46:49], v140 offset:36896
	global_load_lds_dwordx4 v220, s[50:51] offset:2048
	v_mfma_f32_16x16x32_bf16 v[6:9], v[188:191], v[212:215], v[6:9]
	ds_read_b128 v[50:53], v140 offset:38944
	global_load_lds_dwordx4 v221, s[50:51] offset:3072
	v_mfma_f32_16x16x32_bf16 v[2:5], v[192:195], v[200:203], v[2:5]
	v_mfma_f32_16x16x32_bf16 v[10:13], v[192:195], v[204:207], v[10:13]
	v_mfma_f32_16x16x32_bf16 v[14:17], v[192:195], v[208:211], v[14:17]
	v_mfma_f32_16x16x32_bf16 v[26:29], v[192:195], v[212:215], v[26:29]
	v_mfma_f32_16x16x32_bf16 v[34:37], v[196:199], v[200:203], v[34:37]
	v_mfma_f32_16x16x32_bf16 v[30:33], v[196:199], v[204:207], v[30:33]
	v_mfma_f32_16x16x32_bf16 v[22:25], v[196:199], v[208:211], v[22:25]
	v_mfma_f32_16x16x32_bf16 v[18:21], v[196:199], v[212:215], v[18:21]
	s_add_u32 s49, s49, 1
	s_and_b32 s49, s49, 15
	s_cmp_eq_u32 s49, 0
	s_cselect_b32 s10, 0x800, 0
	s_add_u32 s98, s98, 0x80
	s_addc_u32 s99, s99, 0
	s_sub_u32 s98, s98, s10
	s_subb_u32 s99, s99, 0
	s_add_u32 s50, s50, 0x80
	s_addc_u32 s51, s51, 0
	s_sub_u32 s50, s50, s10
	s_subb_u32 s51, s51, 0
	s_waitcnt lgkmcnt(0)
	v_mfma_f32_16x16x32_bf16 v[86:89], v[38:41], v[54:57], v[86:89]
	ds_read_b128 v[136:139], v141 offset:32800
	v_mfma_f32_16x16x32_bf16 v[82:85], v[38:41], v[58:61], v[82:85]
	ds_read_b128 v[200:203], v217 offset:32800
	v_mfma_f32_16x16x32_bf16 v[78:81], v[38:41], v[62:65], v[78:81]
	ds_read_b128 v[204:207], v217 offset:34848
	v_mfma_f32_16x16x32_bf16 v[74:77], v[38:41], v[66:69], v[74:77]
	ds_read_b128 v[188:191], v141 offset:34848
	v_mfma_f32_16x16x32_bf16 v[70:73], v[42:45], v[54:57], v[70:73]
	ds_read_b128 v[208:211], v217 offset:36896
	v_mfma_f32_16x16x32_bf16 v[90:93], v[42:45], v[58:61], v[90:93]
	ds_read_b128 v[212:215], v217 offset:38944
	v_mfma_f32_16x16x32_bf16 v[94:97], v[42:45], v[62:65], v[94:97]
	ds_read_b128 v[192:195], v141 offset:36896
	v_mfma_f32_16x16x32_bf16 v[6:9], v[42:45], v[66:69], v[6:9]
	ds_read_b128 v[196:199], v141 offset:38944
	v_mfma_f32_16x16x32_bf16 v[2:5], v[46:49], v[54:57], v[2:5]
	v_mfma_f32_16x16x32_bf16 v[10:13], v[46:49], v[58:61], v[10:13]
	v_mfma_f32_16x16x32_bf16 v[14:17], v[46:49], v[62:65], v[14:17]
	v_mfma_f32_16x16x32_bf16 v[26:29], v[46:49], v[66:69], v[26:29]
	v_mfma_f32_16x16x32_bf16 v[34:37], v[50:53], v[54:57], v[34:37]
	v_mfma_f32_16x16x32_bf16 v[30:33], v[50:53], v[58:61], v[30:33]
	v_mfma_f32_16x16x32_bf16 v[22:25], v[50:53], v[62:65], v[22:25]
	v_mfma_f32_16x16x32_bf16 v[18:21], v[50:53], v[66:69], v[18:21]
	s_waitcnt lgkmcnt(0)
	s_waitcnt vmcnt(0)
	s_add_u32 s100, s100, 1
	s_cmp_lt_u32 s100, 7
	s_cbranch_scc1 .Lk_pq0_loop
	s_barrier
	s_add_u32 m0, s101, 32768
	v_mfma_f32_16x16x32_bf16 v[86:89], v[136:139], v[200:203], v[86:89]
	ds_read_b128 v[38:41], v140 offset:32
	global_load_lds_dwordx4 v218, s[98:99] offset:0
	v_mfma_f32_16x16x32_bf16 v[82:85], v[136:139], v[204:207], v[82:85]
	ds_read_b128 v[54:57], v216 offset:32
	global_load_lds_dwordx4 v219, s[98:99] offset:1024
	v_mfma_f32_16x16x32_bf16 v[78:81], v[136:139], v[208:211], v[78:81]
	ds_read_b128 v[58:61], v216 offset:2080
	global_load_lds_dwordx4 v220, s[98:99] offset:2048
	v_mfma_f32_16x16x32_bf16 v[74:77], v[136:139], v[212:215], v[74:77]
	ds_read_b128 v[42:45], v140 offset:2080
	global_load_lds_dwordx4 v221, s[98:99] offset:3072
	s_add_u32 m0, s101, 49152
	v_mfma_f32_16x16x32_bf16 v[70:73], v[188:191], v[200:203], v[70:73]
	ds_read_b128 v[62:65], v216 offset:4128
	global_load_lds_dwordx4 v218, s[50:51] offset:0
	v_mfma_f32_16x16x32_bf16 v[90:93], v[188:191], v[204:207], v[90:93]
	ds_read_b128 v[66:69], v216 offset:6176
	global_load_lds_dwordx4 v219, s[50:51] offset:1024
	v_mfma_f32_16x16x32_bf16 v[94:97], v[188:191], v[208:211], v[94:97]
	ds_read_b128 v[46:49], v140 offset:4128
	global_load_lds_dwordx4 v220, s[50:51] offset:2048
	v_mfma_f32_16x16x32_bf16 v[6:9], v[188:191], v[212:215], v[6:9]
	ds_read_b128 v[50:53], v140 offset:6176
	global_load_lds_dwordx4 v221, s[50:51] offset:3072
	v_mfma_f32_16x16x32_bf16 v[2:5], v[192:195], v[200:203], v[2:5]
	v_mfma_f32_16x16x32_bf16 v[10:13], v[192:195], v[204:207], v[10:13]
	v_mfma_f32_16x16x32_bf16 v[14:17], v[192:195], v[208:211], v[14:17]
	v_mfma_f32_16x16x32_bf16 v[26:29], v[192:195], v[212:215], v[26:29]
	v_mfma_f32_16x16x32_bf16 v[34:37], v[196:199], v[200:203], v[34:37]
	v_mfma_f32_16x16x32_bf16 v[30:33], v[196:199], v[204:207], v[30:33]
	v_mfma_f32_16x16x32_bf16 v[22:25], v[196:199], v[208:211], v[22:25]
	v_mfma_f32_16x16x32_bf16 v[18:21], v[196:199], v[212:215], v[18:21]
	s_add_u32 s49, s49, 1
	s_and_b32 s49, s49, 15
	s_cmp_eq_u32 s49, 0
	s_cselect_b32 s10, 0x800, 0
	s_add_u32 s98, s98, 0x80
	s_addc_u32 s99, s99, 0
	s_sub_u32 s98, s98, s10
	s_subb_u32 s99, s99, 0
	s_add_u32 s50, s50, 0x80
	s_addc_u32 s51, s51, 0
	s_sub_u32 s50, s50, s10
	s_subb_u32 s51, s51, 0
	s_waitcnt lgkmcnt(0)
	v_mfma_f32_16x16x32_bf16 v[86:89], v[38:41], v[54:57], v[86:89]
	ds_read_b128 v[136:139], v141 offset:32
	v_mfma_f32_16x16x32_bf16 v[82:85], v[38:41], v[58:61], v[82:85]
	ds_read_b128 v[200:203], v217 offset:32
	v_mfma_f32_16x16x32_bf16 v[78:81], v[38:41], v[62:65], v[78:81]
	ds_read_b128 v[204:207], v217 offset:2080
	v_mfma_f32_16x16x32_bf16 v[74:77], v[38:41], v[66:69], v[74:77]
	ds_read_b128 v[188:191], v141 offset:2080
	v_mfma_f32_16x16x32_bf16 v[70:73], v[42:45], v[54:57], v[70:73]
	ds_read_b128 v[208:211], v217 offset:4128
	v_mfma_f32_16x16x32_bf16 v[90:93], v[42:45], v[58:61], v[90:93]
	ds_read_b128 v[212:215], v217 offset:6176
	v_mfma_f32_16x16x32_bf16 v[94:97], v[42:45], v[62:65], v[94:97]
	ds_read_b128 v[192:195], v141 offset:4128
	v_mfma_f32_16x16x32_bf16 v[6:9], v[42:45], v[66:69], v[6:9]
	ds_read_b128 v[196:199], v141 offset:6176
	v_mfma_f32_16x16x32_bf16 v[2:5], v[46:49], v[54:57], v[2:5]
	v_mfma_f32_16x16x32_bf16 v[10:13], v[46:49], v[58:61], v[10:13]
	v_mfma_f32_16x16x32_bf16 v[14:17], v[46:49], v[62:65], v[14:17]
	v_mfma_f32_16x16x32_bf16 v[26:29], v[46:49], v[66:69], v[26:29]
	v_mfma_f32_16x16x32_bf16 v[34:37], v[50:53], v[54:57], v[34:37]
	v_mfma_f32_16x16x32_bf16 v[30:33], v[50:53], v[58:61], v[30:33]
	v_mfma_f32_16x16x32_bf16 v[22:25], v[50:53], v[62:65], v[22:25]
	v_mfma_f32_16x16x32_bf16 v[18:21], v[50:53], v[66:69], v[18:21]
	s_waitcnt lgkmcnt(0)
	s_waitcnt vmcnt(0)
	s_barrier
	v_mfma_f32_16x16x32_bf16 v[86:89], v[136:139], v[200:203], v[86:89]
	ds_read_b128 v[38:41], v140 offset:32800
	v_mfma_f32_16x16x32_bf16 v[82:85], v[136:139], v[204:207], v[82:85]
	ds_read_b128 v[54:57], v216 offset:32800
	v_mfma_f32_16x16x32_bf16 v[78:81], v[136:139], v[208:211], v[78:81]
	ds_read_b128 v[58:61], v216 offset:34848
	v_mfma_f32_16x16x32_bf16 v[74:77], v[136:139], v[212:215], v[74:77]
	ds_read_b128 v[42:45], v140 offset:34848
	v_mfma_f32_16x16x32_bf16 v[70:73], v[188:191], v[200:203], v[70:73]
	ds_read_b128 v[62:65], v216 offset:36896
	v_mfma_f32_16x16x32_bf16 v[90:93], v[188:191], v[204:207], v[90:93]
	ds_read_b128 v[66:69], v216 offset:38944
	v_mfma_f32_16x16x32_bf16 v[94:97], v[188:191], v[208:211], v[94:97]
	ds_read_b128 v[46:49], v140 offset:36896
	v_mfma_f32_16x16x32_bf16 v[6:9], v[188:191], v[212:215], v[6:9]
	ds_read_b128 v[50:53], v140 offset:38944
	v_mfma_f32_16x16x32_bf16 v[2:5], v[192:195], v[200:203], v[2:5]
	v_mfma_f32_16x16x32_bf16 v[10:13], v[192:195], v[204:207], v[10:13]
	v_mfma_f32_16x16x32_bf16 v[14:17], v[192:195], v[208:211], v[14:17]
	v_mfma_f32_16x16x32_bf16 v[26:29], v[192:195], v[212:215], v[26:29]
	v_mfma_f32_16x16x32_bf16 v[34:37], v[196:199], v[200:203], v[34:37]
	v_mfma_f32_16x16x32_bf16 v[30:33], v[196:199], v[204:207], v[30:33]
	v_mfma_f32_16x16x32_bf16 v[22:25], v[196:199], v[208:211], v[22:25]
	v_mfma_f32_16x16x32_bf16 v[18:21], v[196:199], v[212:215], v[18:21]
	s_waitcnt lgkmcnt(0)
	v_mfma_f32_16x16x32_bf16 v[86:89], v[38:41], v[54:57], v[86:89]
	ds_read_b128 v[136:139], v141 offset:32800
	v_mfma_f32_16x16x32_bf16 v[82:85], v[38:41], v[58:61], v[82:85]
	ds_read_b128 v[200:203], v217 offset:32800
	v_mfma_f32_16x16x32_bf16 v[78:81], v[38:41], v[62:65], v[78:81]
	ds_read_b128 v[204:207], v217 offset:34848
	v_mfma_f32_16x16x32_bf16 v[74:77], v[38:41], v[66:69], v[74:77]
	ds_read_b128 v[188:191], v141 offset:34848
	v_mfma_f32_16x16x32_bf16 v[70:73], v[42:45], v[54:57], v[70:73]
	ds_read_b128 v[208:211], v217 offset:36896
	v_mfma_f32_16x16x32_bf16 v[90:93], v[42:45], v[58:61], v[90:93]
	ds_read_b128 v[212:215], v217 offset:38944
	v_mfma_f32_16x16x32_bf16 v[94:97], v[42:45], v[62:65], v[94:97]
	ds_read_b128 v[192:195], v141 offset:36896
	v_mfma_f32_16x16x32_bf16 v[6:9], v[42:45], v[66:69], v[6:9]
	ds_read_b128 v[196:199], v141 offset:38944
	v_mfma_f32_16x16x32_bf16 v[2:5], v[46:49], v[54:57], v[2:5]
	v_mfma_f32_16x16x32_bf16 v[10:13], v[46:49], v[58:61], v[10:13]
	v_mfma_f32_16x16x32_bf16 v[14:17], v[46:49], v[62:65], v[14:17]
	v_mfma_f32_16x16x32_bf16 v[26:29], v[46:49], v[66:69], v[26:29]
	v_mfma_f32_16x16x32_bf16 v[34:37], v[50:53], v[54:57], v[34:37]
	v_mfma_f32_16x16x32_bf16 v[30:33], v[50:53], v[58:61], v[30:33]
	v_mfma_f32_16x16x32_bf16 v[22:25], v[50:53], v[62:65], v[22:25]
	v_mfma_f32_16x16x32_bf16 v[18:21], v[50:53], v[66:69], v[18:21]
	s_waitcnt lgkmcnt(0)
	v_mfma_f32_16x16x32_bf16 v[86:89], v[136:139], v[200:203], v[86:89]
	v_mfma_f32_16x16x32_bf16 v[82:85], v[136:139], v[204:207], v[82:85]
	v_mfma_f32_16x16x32_bf16 v[78:81], v[136:139], v[208:211], v[78:81]
	v_mfma_f32_16x16x32_bf16 v[74:77], v[136:139], v[212:215], v[74:77]
	v_mfma_f32_16x16x32_bf16 v[70:73], v[188:191], v[200:203], v[70:73]
	v_mfma_f32_16x16x32_bf16 v[90:93], v[188:191], v[204:207], v[90:93]
	v_mfma_f32_16x16x32_bf16 v[94:97], v[188:191], v[208:211], v[94:97]
	v_mfma_f32_16x16x32_bf16 v[6:9], v[188:191], v[212:215], v[6:9]
	v_mfma_f32_16x16x32_bf16 v[2:5], v[192:195], v[200:203], v[2:5]
	v_mfma_f32_16x16x32_bf16 v[10:13], v[192:195], v[204:207], v[10:13]
	v_mfma_f32_16x16x32_bf16 v[14:17], v[192:195], v[208:211], v[14:17]
	v_mfma_f32_16x16x32_bf16 v[26:29], v[192:195], v[212:215], v[26:29]
	v_mfma_f32_16x16x32_bf16 v[34:37], v[196:199], v[200:203], v[34:37]
	v_mfma_f32_16x16x32_bf16 v[30:33], v[196:199], v[204:207], v[30:33]
	v_mfma_f32_16x16x32_bf16 v[22:25], v[196:199], v[208:211], v[22:25]
	v_mfma_f32_16x16x32_bf16 v[18:21], v[196:199], v[212:215], v[18:21]
	s_waitcnt vmcnt(1)
	v_cvt_pk_bf16_f32 v38, v86, s0
	s_barrier
	ds_write_b16 v147, v38
	v_cvt_pk_bf16_f32 v38, v87, s0
	ds_write_b16 v147, v38 offset:272
	v_cvt_pk_bf16_f32 v38, v88, s0
	ds_write_b16 v147, v38 offset:544
	v_cvt_pk_bf16_f32 v38, v89, s0
	ds_write_b16 v147, v38 offset:816
	v_cvt_pk_bf16_f32 v38, v82, s0
	ds_write_b16 v147, v38 offset:32
	v_cvt_pk_bf16_f32 v38, v83, s0
	ds_write_b16 v147, v38 offset:304
	v_cvt_pk_bf16_f32 v38, v84, s0
	ds_write_b16 v147, v38 offset:576
	v_cvt_pk_bf16_f32 v38, v85, s0
	ds_write_b16 v147, v38 offset:848
	v_cvt_pk_bf16_f32 v38, v78, s0
	ds_write_b16 v147, v38 offset:64
	v_cvt_pk_bf16_f32 v38, v79, s0
	ds_write_b16 v147, v38 offset:336
	v_cvt_pk_bf16_f32 v38, v80, s0
	ds_write_b16 v147, v38 offset:608
	v_cvt_pk_bf16_f32 v38, v81, s0
	ds_write_b16 v147, v38 offset:880
	v_cvt_pk_bf16_f32 v38, v74, s0
	ds_write_b16 v147, v38 offset:96
	v_cvt_pk_bf16_f32 v38, v75, s0
	ds_write_b16 v147, v38 offset:368
	v_cvt_pk_bf16_f32 v38, v76, s0
	ds_write_b16 v147, v38 offset:640
	v_cvt_pk_bf16_f32 v38, v77, s0
	ds_write_b16 v147, v38 offset:912
	v_cvt_pk_bf16_f32 v38, v70, s0
	ds_write_b16 v147, v38 offset:4352
	v_cvt_pk_bf16_f32 v38, v71, s0
	ds_write_b16 v147, v38 offset:4624
	v_cvt_pk_bf16_f32 v38, v72, s0
	ds_write_b16 v147, v38 offset:4896
	v_cvt_pk_bf16_f32 v38, v73, s0
	ds_write_b16 v147, v38 offset:5168
	v_cvt_pk_bf16_f32 v38, v90, s0
	ds_write_b16 v147, v38 offset:4384
	v_cvt_pk_bf16_f32 v38, v91, s0
	ds_write_b16 v147, v38 offset:4656
	v_cvt_pk_bf16_f32 v38, v92, s0
	ds_write_b16 v147, v38 offset:4928
	v_cvt_pk_bf16_f32 v38, v93, s0
	ds_write_b16 v147, v38 offset:5200
	v_cvt_pk_bf16_f32 v38, v94, s0
	ds_write_b16 v147, v38 offset:4416
	v_cvt_pk_bf16_f32 v38, v95, s0
	s_mov_b32 s49, s11
	ds_write_b16 v147, v38 offset:4688
	v_cvt_pk_bf16_f32 v38, v96, s0
	s_lshl_b64 s[50:51], s[48:49], 15
	ds_write_b16 v147, v38 offset:4960
	v_cvt_pk_bf16_f32 v38, v97, s0
	s_waitcnt vmcnt(0)
	v_lshl_add_u64 v[66:67], v[102:103], 0, s[50:51]
	ds_write_b16 v147, v38 offset:5232
	v_lshl_add_u64 v[38:39], v[66:67], 0, v[100:101]
	v_mov_b32_e32 v107, v101
	global_load_dwordx4 v[38:41], v[38:39], off
	v_lshl_add_u64 v[42:43], v[66:67], 0, v[106:107]
	v_mov_b32_e32 v109, v101
	global_load_dwordx4 v[42:45], v[42:43], off
	v_lshl_add_u64 v[46:47], v[66:67], 0, v[108:109]
	v_mov_b32_e32 v111, v101
	global_load_dwordx4 v[46:49], v[46:47], off
	v_lshl_add_u64 v[50:51], v[66:67], 0, v[110:111]
	v_mov_b32_e32 v113, v101
	global_load_dwordx4 v[50:53], v[50:51], off
	v_lshl_add_u64 v[54:55], v[66:67], 0, v[112:113]
	v_mov_b32_e32 v115, v101
	global_load_dwordx4 v[54:57], v[54:55], off
	v_lshl_add_u64 v[58:59], v[66:67], 0, v[114:115]
	v_mov_b32_e32 v117, v101
	global_load_dwordx4 v[58:61], v[58:59], off
	v_lshl_add_u64 v[62:63], v[66:67], 0, v[116:117]
	v_mov_b32_e32 v119, v101
	global_load_dwordx4 v[62:65], v[62:63], off
	v_lshl_add_u64 v[66:67], v[66:67], 0, v[118:119]
	global_load_dwordx4 v[66:69], v[66:67], off
	v_cvt_pk_bf16_f32 v2, v2, s0
	ds_write_b16 v147, v2 offset:8704
	v_cvt_pk_bf16_f32 v2, v3, s0
	ds_write_b16 v147, v2 offset:8976
	v_cvt_pk_bf16_f32 v2, v4, s0
	ds_write_b16 v147, v2 offset:9248
	v_cvt_pk_bf16_f32 v2, v5, s0
	ds_write_b16 v147, v2 offset:9520
	v_cvt_pk_bf16_f32 v2, v10, s0
	ds_write_b16 v147, v2 offset:8736
	v_cvt_pk_bf16_f32 v2, v11, s0
	ds_write_b16 v147, v2 offset:9008
	v_cvt_pk_bf16_f32 v2, v12, s0
	ds_write_b16 v147, v2 offset:9280
	v_cvt_pk_bf16_f32 v2, v13, s0
	ds_write_b16 v147, v2 offset:9552
	v_cvt_pk_bf16_f32 v2, v14, s0
	ds_write_b16 v147, v2 offset:8768
	v_cvt_pk_bf16_f32 v2, v15, s0
	ds_write_b16 v147, v2 offset:9040
	v_cvt_pk_bf16_f32 v2, v16, s0
	ds_write_b16 v147, v2 offset:9312
	v_cvt_pk_bf16_f32 v2, v17, s0
	ds_write_b16 v147, v2 offset:9584
	v_cvt_pk_bf16_f32 v2, v26, s0
	ds_write_b16 v147, v2 offset:8800
	v_cvt_pk_bf16_f32 v2, v27, s0
	ds_write_b16 v147, v2 offset:9072
	v_cvt_pk_bf16_f32 v2, v28, s0
	ds_write_b16 v147, v2 offset:9344
	v_cvt_pk_bf16_f32 v2, v29, s0
	ds_write_b16 v147, v2 offset:9616
	v_cvt_pk_bf16_f32 v2, v34, s0
	ds_write_b16 v147, v2 offset:13056
	v_cvt_pk_bf16_f32 v2, v35, s0
	ds_write_b16 v147, v2 offset:13328
	v_cvt_pk_bf16_f32 v2, v36, s0
	ds_write_b16 v147, v2 offset:13600
	v_cvt_pk_bf16_f32 v2, v37, s0
	ds_write_b16 v147, v2 offset:13872
	v_cvt_pk_bf16_f32 v2, v30, s0
	ds_write_b16 v147, v2 offset:13088
	v_cvt_pk_bf16_f32 v2, v31, s0
	ds_write_b16 v147, v2 offset:13360
	v_cvt_pk_bf16_f32 v2, v32, s0
	ds_write_b16 v147, v2 offset:13632
	v_cvt_pk_bf16_f32 v2, v33, s0
	ds_write_b16 v147, v2 offset:13904
	v_cvt_pk_bf16_f32 v2, v22, s0
	ds_write_b16 v147, v2 offset:13120
	v_cvt_pk_bf16_f32 v2, v23, s0
	ds_write_b16 v147, v2 offset:13392
	v_cvt_pk_bf16_f32 v2, v24, s0
	ds_write_b16 v147, v2 offset:13664
	v_cvt_pk_bf16_f32 v2, v25, s0
	v_cvt_pk_bf16_f32 v6, v6, s0
	ds_write_b16 v147, v2 offset:13936
	v_cvt_pk_bf16_f32 v2, v18, s0
	ds_write_b16 v147, v6 offset:4448
	v_cvt_pk_bf16_f32 v6, v7, s0
	ds_write_b16 v147, v2 offset:13152
	v_cvt_pk_bf16_f32 v2, v19, s0
	ds_write_b16 v147, v6 offset:4720
	v_cvt_pk_bf16_f32 v6, v8, s0
	ds_write_b16 v147, v2 offset:13424
	v_cvt_pk_bf16_f32 v2, v20, s0
	ds_write_b16 v147, v6 offset:4992
	v_cvt_pk_bf16_f32 v6, v9, s0
	ds_write_b16 v147, v2 offset:13696
	v_cvt_pk_bf16_f32 v2, v21, s0
	ds_write_b16 v147, v6 offset:5264
	ds_write_b16 v147, v2 offset:13968
	s_waitcnt vmcnt(7)
	ds_write_b128 v148, v[38:41]
	s_waitcnt vmcnt(6)
	ds_write_b128 v149, v[42:45]
	s_waitcnt vmcnt(5)
	ds_write_b128 v150, v[46:49]
	s_waitcnt vmcnt(4)
	ds_write_b128 v151, v[50:53]
	s_waitcnt vmcnt(3)
	ds_write_b128 v152, v[54:57]
	s_waitcnt vmcnt(2)
	ds_write_b128 v153, v[58:61]
	s_waitcnt vmcnt(1)
	ds_write_b128 v154, v[62:65]
	s_waitcnt vmcnt(0)
	ds_write_b128 v155, v[66:69]
	s_waitcnt lgkmcnt(0)
	s_barrier
	ds_read_b128 v[2:5], v176
	ds_read_b128 v[6:9], v177 offset:34816
	ds_read_b128 v[34:37], v176 offset:4352
	ds_read_b128 v[70:73], v176 offset:64
	ds_read_b128 v[50:53], v176 offset:8704
	ds_read_b128 v[66:69], v176 offset:13056
	ds_read_b128 v[14:17], v177 offset:39168
	ds_read_b128 v[22:25], v177 offset:43520
	ds_read_b128 v[30:33], v177 offset:47872
	ds_read_b128 v[78:81], v177 offset:43584
	s_waitcnt lgkmcnt(8)
	v_mfma_f32_16x16x32_bf16 v[10:13], v[2:5], v[6:9], 0
	ds_read_b128 v[74:77], v177 offset:39232
	ds_read_b128 v[82:85], v177 offset:47936
	s_lshl_b64 s[48:49], s[48:49], 6
	s_waitcnt lgkmcnt(5)
	v_mfma_f32_16x16x32_bf16 v[18:21], v[2:5], v[14:17], 0
	s_add_u32 s48, s29, s48
	s_addc_u32 s49, s76, s49
	s_mov_b32 s10, 0
	s_waitcnt lgkmcnt(4)
	v_mfma_f32_16x16x32_bf16 v[26:29], v[2:5], v[22:25], 0
	s_waitcnt lgkmcnt(3)
	v_mfma_f32_16x16x32_bf16 v[2:5], v[2:5], v[30:33], 0
	v_mfma_f32_16x16x32_bf16 v[38:41], v[34:37], v[6:9], 0
	v_mfma_f32_16x16x32_bf16 v[42:45], v[34:37], v[14:17], 0
	v_mfma_f32_16x16x32_bf16 v[46:49], v[34:37], v[22:25], 0
	v_mfma_f32_16x16x32_bf16 v[34:37], v[34:37], v[30:33], 0
	v_mfma_f32_16x16x32_bf16 v[54:57], v[50:53], v[6:9], 0
	v_mfma_f32_16x16x32_bf16 v[58:61], v[50:53], v[14:17], 0
	v_mfma_f32_16x16x32_bf16 v[62:65], v[50:53], v[22:25], 0
	v_mfma_f32_16x16x32_bf16 v[50:53], v[50:53], v[30:33], 0
	v_mfma_f32_16x16x32_bf16 v[6:9], v[66:69], v[6:9], 0
	v_mfma_f32_16x16x32_bf16 v[14:17], v[66:69], v[14:17], 0
	v_mfma_f32_16x16x32_bf16 v[22:25], v[66:69], v[22:25], 0
	v_mfma_f32_16x16x32_bf16 v[30:33], v[66:69], v[30:33], 0
	ds_read_b128 v[66:69], v177 offset:34880
	s_waitcnt lgkmcnt(0)
	v_mfma_f32_16x16x32_bf16 v[10:13], v[70:73], v[66:69], v[10:13]
	v_mfma_f32_16x16x32_bf16 v[18:21], v[70:73], v[74:77], v[18:21]
	v_mfma_f32_16x16x32_bf16 v[26:29], v[70:73], v[78:81], v[26:29]
	v_mfma_f32_16x16x32_bf16 v[2:5], v[70:73], v[82:85], v[2:5]
	ds_read_b128 v[70:73], v176 offset:4416
	s_waitcnt lgkmcnt(0)
	v_mfma_f32_16x16x32_bf16 v[38:41], v[70:73], v[66:69], v[38:41]
	v_mfma_f32_16x16x32_bf16 v[42:45], v[70:73], v[74:77], v[42:45]
	v_mfma_f32_16x16x32_bf16 v[46:49], v[70:73], v[78:81], v[46:49]
	v_mfma_f32_16x16x32_bf16 v[34:37], v[70:73], v[82:85], v[34:37]
	ds_read_b128 v[70:73], v176 offset:8768
	s_waitcnt lgkmcnt(0)
	v_mfma_f32_16x16x32_bf16 v[54:57], v[70:73], v[66:69], v[54:57]
	v_mfma_f32_16x16x32_bf16 v[58:61], v[70:73], v[74:77], v[58:61]
	v_mfma_f32_16x16x32_bf16 v[62:65], v[70:73], v[78:81], v[62:65]
	v_mfma_f32_16x16x32_bf16 v[50:53], v[70:73], v[82:85], v[50:53]
	ds_read_b128 v[70:73], v176 offset:13120
	s_waitcnt lgkmcnt(0)
	v_mfma_f32_16x16x32_bf16 v[6:9], v[70:73], v[66:69], v[6:9]
	ds_read_b128 v[66:69], v176 offset:128
	v_mfma_f32_16x16x32_bf16 v[14:17], v[70:73], v[74:77], v[14:17]
	ds_read_b128 v[74:77], v177 offset:39296
	v_mfma_f32_16x16x32_bf16 v[22:25], v[70:73], v[78:81], v[22:25]
	ds_read_b128 v[78:81], v177 offset:43648
	v_mfma_f32_16x16x32_bf16 v[30:33], v[70:73], v[82:85], v[30:33]
	ds_read_b128 v[70:73], v177 offset:34944
	ds_read_b128 v[82:85], v177 offset:48000
	s_waitcnt lgkmcnt(1)
	v_mfma_f32_16x16x32_bf16 v[10:13], v[66:69], v[70:73], v[10:13]
	v_mfma_f32_16x16x32_bf16 v[18:21], v[66:69], v[74:77], v[18:21]
	v_mfma_f32_16x16x32_bf16 v[26:29], v[66:69], v[78:81], v[26:29]
	s_waitcnt lgkmcnt(0)
	v_mfma_f32_16x16x32_bf16 v[2:5], v[66:69], v[82:85], v[2:5]
	ds_read_b128 v[66:69], v176 offset:4480
	s_waitcnt lgkmcnt(0)
	v_mfma_f32_16x16x32_bf16 v[38:41], v[66:69], v[70:73], v[38:41]
	v_mfma_f32_16x16x32_bf16 v[42:45], v[66:69], v[74:77], v[42:45]
	v_mfma_f32_16x16x32_bf16 v[46:49], v[66:69], v[78:81], v[46:49]
	v_mfma_f32_16x16x32_bf16 v[34:37], v[66:69], v[82:85], v[34:37]
	ds_read_b128 v[66:69], v176 offset:8832
	s_waitcnt lgkmcnt(0)
	v_mfma_f32_16x16x32_bf16 v[54:57], v[66:69], v[70:73], v[54:57]
	v_mfma_f32_16x16x32_bf16 v[58:61], v[66:69], v[74:77], v[58:61]
	v_mfma_f32_16x16x32_bf16 v[62:65], v[66:69], v[78:81], v[62:65]
	v_mfma_f32_16x16x32_bf16 v[50:53], v[66:69], v[82:85], v[50:53]
	ds_read_b128 v[66:69], v176 offset:13184
	s_waitcnt lgkmcnt(0)
	v_mfma_f32_16x16x32_bf16 v[6:9], v[66:69], v[70:73], v[6:9]
	ds_read_b128 v[70:73], v176 offset:192
	v_mfma_f32_16x16x32_bf16 v[14:17], v[66:69], v[74:77], v[14:17]
	ds_read_b128 v[74:77], v177 offset:39360
	v_mfma_f32_16x16x32_bf16 v[22:25], v[66:69], v[78:81], v[22:25]
	ds_read_b128 v[78:81], v177 offset:43712
	v_mfma_f32_16x16x32_bf16 v[30:33], v[66:69], v[82:85], v[30:33]
	ds_read_b128 v[66:69], v177 offset:35008
	ds_read_b128 v[82:85], v177 offset:48064
	s_waitcnt lgkmcnt(1)
	v_mfma_f32_16x16x32_bf16 v[10:13], v[70:73], v[66:69], v[10:13]
	v_mfma_f32_16x16x32_bf16 v[18:21], v[70:73], v[74:77], v[18:21]
	v_mfma_f32_16x16x32_bf16 v[26:29], v[70:73], v[78:81], v[26:29]
	s_waitcnt lgkmcnt(0)
	v_mfma_f32_16x16x32_bf16 v[2:5], v[70:73], v[82:85], v[2:5]
	ds_read_b128 v[70:73], v176 offset:4544
	s_waitcnt lgkmcnt(0)
	v_mfma_f32_16x16x32_bf16 v[38:41], v[70:73], v[66:69], v[38:41]
	v_mfma_f32_16x16x32_bf16 v[42:45], v[70:73], v[74:77], v[42:45]
	v_mfma_f32_16x16x32_bf16 v[46:49], v[70:73], v[78:81], v[46:49]
	v_mfma_f32_16x16x32_bf16 v[34:37], v[70:73], v[82:85], v[34:37]
	ds_read_b128 v[70:73], v176 offset:8896
	s_waitcnt lgkmcnt(0)
	v_mfma_f32_16x16x32_bf16 v[54:57], v[70:73], v[66:69], v[54:57]
	v_mfma_f32_16x16x32_bf16 v[58:61], v[70:73], v[74:77], v[58:61]
	v_mfma_f32_16x16x32_bf16 v[62:65], v[70:73], v[78:81], v[62:65]
	v_mfma_f32_16x16x32_bf16 v[50:53], v[70:73], v[82:85], v[50:53]
	ds_read_b128 v[70:73], v176 offset:13248
	s_waitcnt lgkmcnt(0)
	s_barrier
	v_mfma_f32_16x16x32_bf16 v[6:9], v[70:73], v[66:69], v[6:9]
	ds_write2_b32 v146, v10, v18 offset1:16
	ds_write2_b32 v146, v11, v19 offset0:132 offset1:148
	v_add_u32_e32 v10, 0x400, v146
	v_mfma_f32_16x16x32_bf16 v[14:17], v[70:73], v[74:77], v[14:17]
	ds_write2_b32 v10, v12, v20 offset0:8 offset1:24
	ds_write2_b32 v10, v13, v21 offset0:140 offset1:156
	ds_write2_b32 v146, v26, v2 offset0:32 offset1:48
	ds_write2_b32 v146, v27, v3 offset0:164 offset1:180
	ds_write2_b32 v10, v28, v4 offset0:40 offset1:56
	ds_write2_b32 v10, v29, v5 offset0:172 offset1:188
	v_add_u32_e32 v2, 0x2000, v146
	v_add_u32_e32 v3, 0x2400, v146
	v_mfma_f32_16x16x32_bf16 v[22:25], v[70:73], v[78:81], v[22:25]
	ds_write2_b32 v2, v38, v42 offset0:64 offset1:80
	ds_write2_b32 v2, v39, v43 offset0:196 offset1:212
	ds_write2_b32 v3, v40, v44 offset0:72 offset1:88
	ds_write2_b32 v3, v41, v45 offset0:204 offset1:220
	ds_write2_b32 v2, v46, v34 offset0:96 offset1:112
	ds_write2_b32 v2, v47, v35 offset0:228 offset1:244
	ds_write2_b32 v3, v48, v36 offset0:104 offset1:120
	ds_write2_b32 v3, v49, v37 offset0:236 offset1:252
	v_add_u32_e32 v2, 0x4000, v146
	v_mfma_f32_16x16x32_bf16 v[30:33], v[70:73], v[82:85], v[30:33]
	v_add_u32_e32 v3, 0x4400, v146
	v_add_u32_e32 v4, 0x4800, v146
	ds_write2_b32 v2, v54, v58 offset0:128 offset1:144
	ds_write2_b32 v3, v55, v59 offset0:4 offset1:20
	ds_write2_b32 v3, v56, v60 offset0:136 offset1:152
	ds_write2_b32 v4, v57, v61 offset0:12 offset1:28
	ds_write2_b32 v2, v62, v50 offset0:160 offset1:176
	ds_write2_b32 v3, v63, v51 offset0:36 offset1:52
	ds_write2_b32 v3, v64, v52 offset0:168 offset1:184
	ds_write2_b32 v4, v65, v53 offset0:44 offset1:60
	v_add_u32_e32 v2, 0x6000, v146
	v_add_u32_e32 v3, 0x6400, v146
	v_add_u32_e32 v4, 0x6800, v146
	ds_write2_b32 v2, v6, v14 offset0:192 offset1:208
	ds_write2_b32 v3, v7, v15 offset0:68 offset1:84
	ds_write2_b32 v3, v8, v16 offset0:200 offset1:216
	ds_write2_b32 v4, v9, v17 offset0:76 offset1:92
	ds_write2_b32 v2, v22, v30 offset0:224 offset1:240
	ds_write2_b32 v3, v23, v31 offset0:100 offset1:116
	ds_write2_b32 v3, v24, v32 offset0:232 offset1:248
	ds_write2_b32 v4, v25, v33 offset0:108 offset1:124
	v_mov_b32_e32 v2, v178
	s_waitcnt lgkmcnt(0)
	s_barrier
	s_branch .LBB0_790

.LBB0_927:
	s_lshl_b32 s28, s66, 7
	s_ashr_i32 s29, s28, 31
	s_lshl_b64 s[26:27], s[28:29], 10
	s_lshl_b64 s[6:7], s[28:29], 11
	s_add_u32 s6, s23, s6
	s_addc_u32 s7, s33, s7
	s_ashr_i32 s25, s24, 31
	s_lshl_b64 s[8:9], s[24:25], 18
	s_add_u32 s8, s54, s8
	s_addc_u32 s9, s55, s9
	v_and_b32_e32 v200, 15, v0
	v_bfe_u32 v201, v0, 4, 2
	v_and_b32_e32 v163, 7, v200
	v_xor_b32_e32 v201, v201, v163
	v_lshlrev_b32_e32 v201, 4, v201
	v_lshl_or_b32 v201, v200, 7, v201
	v_bfe_u32 v200, v0, 7, 1
	v_lshl_or_b32 v132, v200, 13, v201
	v_bfe_u32 v200, v0, 6, 1
	v_lshl_or_b32 v194, v200, 13, v201
	v_or_b32_e32 v194, 0x4000, v194
	v_xor_b32_e32 v163, 64, v132
	v_xor_b32_e32 v195, 64, v194
	v_bfe_u32 v200, v0, 3, 3
	v_and_b32_e32 v201, 7, v0
	v_xor_b32_e32 v201, v201, v200
	v_lshlrev_b32_e32 v201, 4, v201
	v_lshl_or_b32 v201, v200, 11, v201
	v_lshrrev_b32_e32 v200, 6, v0
	v_and_b32_e32 v200, 3, v200
	v_lshl_or_b32 v196, v200, 16, v201
	v_add_u32_e32 v197, 0x3c00, v196
	v_add_u32_e32 v198, 0x7800, v196
	v_add_u32_e32 v199, 0xb400, v196
	v_lshlrev_b32_e32 v200, 12, v200
	s_nop 0
	v_readfirstlane_b32 s14, v200
	s_add_u32 s14, s14, 32
	v_mov_b32_e32 v94, 0
	v_mov_b32_e32 v95, 0
	v_mov_b32_e32 v96, 0
	v_mov_b32_e32 v97, 0
	v_mov_b32_e32 v90, 0
	v_mov_b32_e32 v91, 0
	v_mov_b32_e32 v92, 0
	v_mov_b32_e32 v93, 0
	v_mov_b32_e32 v86, 0
	v_mov_b32_e32 v87, 0
	v_mov_b32_e32 v88, 0
	v_mov_b32_e32 v89, 0
	v_mov_b32_e32 v82, 0
	v_mov_b32_e32 v83, 0
	v_mov_b32_e32 v84, 0
	v_mov_b32_e32 v85, 0
	v_mov_b32_e32 v74, 0
	v_mov_b32_e32 v75, 0
	v_mov_b32_e32 v76, 0
	v_mov_b32_e32 v77, 0
	v_mov_b32_e32 v70, 0
	v_mov_b32_e32 v71, 0
	v_mov_b32_e32 v72, 0
	v_mov_b32_e32 v73, 0
	v_mov_b32_e32 v66, 0
	v_mov_b32_e32 v67, 0
	v_mov_b32_e32 v68, 0
	v_mov_b32_e32 v69, 0
	v_mov_b32_e32 v62, 0
	v_mov_b32_e32 v63, 0
	v_mov_b32_e32 v64, 0
	v_mov_b32_e32 v65, 0
	v_mov_b32_e32 v50, 0
	v_mov_b32_e32 v51, 0
	v_mov_b32_e32 v52, 0
	v_mov_b32_e32 v53, 0
	v_mov_b32_e32 v30, 0
	v_mov_b32_e32 v31, 0
	v_mov_b32_e32 v32, 0
	v_mov_b32_e32 v33, 0
	v_mov_b32_e32 v18, 0
	v_mov_b32_e32 v19, 0
	v_mov_b32_e32 v20, 0
	v_mov_b32_e32 v21, 0
	v_mov_b32_e32 v14, 0
	v_mov_b32_e32 v15, 0
	v_mov_b32_e32 v16, 0
	v_mov_b32_e32 v17, 0
	v_mov_b32_e32 v10, 0
	v_mov_b32_e32 v11, 0
	v_mov_b32_e32 v12, 0
	v_mov_b32_e32 v13, 0
	v_mov_b32_e32 v6, 0
	v_mov_b32_e32 v7, 0
	v_mov_b32_e32 v8, 0
	v_mov_b32_e32 v9, 0
	v_mov_b32_e32 v2, 0
	v_mov_b32_e32 v3, 0
	v_mov_b32_e32 v4, 0
	v_mov_b32_e32 v5, 0
	v_mov_b32_e32 v78, 0
	v_mov_b32_e32 v79, 0
	v_mov_b32_e32 v80, 0
	v_mov_b32_e32 v81, 0
	v_mov_b32_e32 v98, 0
	v_mov_b32_e32 v99, 0
	v_mov_b32_e32 v100, 0
	v_mov_b32_e32 v101, 0
	v_mov_b32_e32 v102, 0
	v_mov_b32_e32 v103, 0
	v_mov_b32_e32 v104, 0
	v_mov_b32_e32 v105, 0
	v_mov_b32_e32 v106, 0
	v_mov_b32_e32 v107, 0
	v_mov_b32_e32 v108, 0
	v_mov_b32_e32 v109, 0
	v_mov_b32_e32 v110, 0
	v_mov_b32_e32 v111, 0
	v_mov_b32_e32 v112, 0
	v_mov_b32_e32 v113, 0
	v_mov_b32_e32 v114, 0
	v_mov_b32_e32 v115, 0
	v_mov_b32_e32 v116, 0
	v_mov_b32_e32 v117, 0
	v_mov_b32_e32 v118, 0
	v_mov_b32_e32 v119, 0
	v_mov_b32_e32 v120, 0
	v_mov_b32_e32 v121, 0
	v_mov_b32_e32 v122, 0
	v_mov_b32_e32 v123, 0
	v_mov_b32_e32 v124, 0
	v_mov_b32_e32 v125, 0
	v_mov_b32_e32 v126, 0
	v_mov_b32_e32 v127, 0
	v_mov_b32_e32 v128, 0
	v_mov_b32_e32 v129, 0
	s_waitcnt lgkmcnt(0)
	s_barrier
	v_readlane_b32 s98, v255, 16
	s_lshr_b32 s98, s98, 3
	s_and_b32 s98, s98, 3
	s_lshl_b32 s98, s98, 2
	s_lshl_b32 s99, s98, 7
	s_add_u32 s6, s6, s99
	s_addc_u32 s7, s7, 0
	s_add_u32 s8, s8, s99
	s_addc_u32 s9, s9, 0
	s_add_u32 m0, s14, 0
	s_nop 0
	global_load_lds_dwordx4 v196, s[6:7] offset:0
	global_load_lds_dwordx4 v197, s[6:7] offset:1024
	global_load_lds_dwordx4 v198, s[6:7] offset:2048
	global_load_lds_dwordx4 v199, s[6:7] offset:3072
	s_add_u32 m0, s14, 16384
	s_nop 0
	global_load_lds_dwordx4 v196, s[8:9] offset:0
	global_load_lds_dwordx4 v197, s[8:9] offset:1024
	global_load_lds_dwordx4 v198, s[8:9] offset:2048
	global_load_lds_dwordx4 v199, s[8:9] offset:3072
	s_add_u32 s98, s98, 1
	s_and_b32 s98, s98, 15
	s_cmp_eq_u32 s98, 0
	s_cselect_b32 s99, 0x800, 0
	s_add_u32 s6, s6, 0x80
	s_addc_u32 s7, s7, 0
	s_sub_u32 s6, s6, s99
	s_subb_u32 s7, s7, 0
	s_add_u32 s8, s8, 0x80
	s_addc_u32 s9, s9, 0
	s_sub_u32 s8, s8, s99
	s_subb_u32 s9, s9, 0
	s_mov_b32 s25, 0
	s_waitcnt vmcnt(0)
.Lk_g1l1_loop:
	s_barrier
	s_add_u32 m0, s14, 32768
	v_mfma_f32_16x16x32_bf16 v[94:97], v[98:101], v[114:117], v[94:97]
	ds_read_b128 v[22:25], v132 offset:32
	global_load_lds_dwordx4 v196, s[6:7] offset:0
	v_mfma_f32_16x16x32_bf16 v[90:93], v[98:101], v[118:121], v[90:93]
	ds_read_b128 v[42:45], v194 offset:32
	global_load_lds_dwordx4 v197, s[6:7] offset:1024
	v_mfma_f32_16x16x32_bf16 v[86:89], v[98:101], v[122:125], v[86:89]
	ds_read_b128 v[46:49], v194 offset:2080
	global_load_lds_dwordx4 v198, s[6:7] offset:2048
	v_mfma_f32_16x16x32_bf16 v[82:85], v[98:101], v[126:129], v[82:85]
	ds_read_b128 v[26:29], v132 offset:2080
	global_load_lds_dwordx4 v199, s[6:7] offset:3072
	s_add_u32 m0, s14, 49152
	v_mfma_f32_16x16x32_bf16 v[74:77], v[102:105], v[114:117], v[74:77]
	ds_read_b128 v[54:57], v194 offset:4128
	global_load_lds_dwordx4 v196, s[8:9] offset:0
	v_mfma_f32_16x16x32_bf16 v[70:73], v[102:105], v[118:121], v[70:73]
	ds_read_b128 v[58:61], v194 offset:6176
	global_load_lds_dwordx4 v197, s[8:9] offset:1024
	v_mfma_f32_16x16x32_bf16 v[66:69], v[102:105], v[122:125], v[66:69]
	ds_read_b128 v[34:37], v132 offset:4128
	global_load_lds_dwordx4 v198, s[8:9] offset:2048
	v_mfma_f32_16x16x32_bf16 v[62:65], v[102:105], v[126:129], v[62:65]
	ds_read_b128 v[38:41], v132 offset:6176
	global_load_lds_dwordx4 v199, s[8:9] offset:3072
	v_mfma_f32_16x16x32_bf16 v[50:53], v[106:109], v[114:117], v[50:53]
	v_mfma_f32_16x16x32_bf16 v[30:33], v[106:109], v[118:121], v[30:33]
	v_mfma_f32_16x16x32_bf16 v[18:21], v[106:109], v[122:125], v[18:21]
	v_mfma_f32_16x16x32_bf16 v[14:17], v[106:109], v[126:129], v[14:17]
	v_mfma_f32_16x16x32_bf16 v[10:13], v[110:113], v[114:117], v[10:13]
	v_mfma_f32_16x16x32_bf16 v[6:9], v[110:113], v[118:121], v[6:9]
	v_mfma_f32_16x16x32_bf16 v[2:5], v[110:113], v[122:125], v[2:5]
	v_mfma_f32_16x16x32_bf16 v[78:81], v[110:113], v[126:129], v[78:81]
	s_add_u32 s98, s98, 1
	s_and_b32 s98, s98, 15
	s_cmp_eq_u32 s98, 0
	s_cselect_b32 s99, 0x800, 0
	s_add_u32 s6, s6, 0x80
	s_addc_u32 s7, s7, 0
	s_sub_u32 s6, s6, s99
	s_subb_u32 s7, s7, 0
	s_add_u32 s8, s8, 0x80
	s_addc_u32 s9, s9, 0
	s_sub_u32 s8, s8, s99
	s_subb_u32 s9, s9, 0
	s_waitcnt lgkmcnt(0)
	v_mfma_f32_16x16x32_bf16 v[94:97], v[22:25], v[42:45], v[94:97]
	ds_read_b128 v[98:101], v163 offset:32
	v_mfma_f32_16x16x32_bf16 v[90:93], v[22:25], v[46:49], v[90:93]
	ds_read_b128 v[114:117], v195 offset:32
	v_mfma_f32_16x16x32_bf16 v[86:89], v[22:25], v[54:57], v[86:89]
	ds_read_b128 v[118:121], v195 offset:2080
	v_mfma_f32_16x16x32_bf16 v[82:85], v[22:25], v[58:61], v[82:85]
	ds_read_b128 v[102:105], v163 offset:2080
	v_mfma_f32_16x16x32_bf16 v[74:77], v[26:29], v[42:45], v[74:77]
	ds_read_b128 v[122:125], v195 offset:4128
	v_mfma_f32_16x16x32_bf16 v[70:73], v[26:29], v[46:49], v[70:73]
	ds_read_b128 v[126:129], v195 offset:6176
	v_mfma_f32_16x16x32_bf16 v[66:69], v[26:29], v[54:57], v[66:69]
	ds_read_b128 v[106:109], v163 offset:4128
	v_mfma_f32_16x16x32_bf16 v[62:65], v[26:29], v[58:61], v[62:65]
	ds_read_b128 v[110:113], v163 offset:6176
	v_mfma_f32_16x16x32_bf16 v[50:53], v[34:37], v[42:45], v[50:53]
	v_mfma_f32_16x16x32_bf16 v[30:33], v[34:37], v[46:49], v[30:33]
	v_mfma_f32_16x16x32_bf16 v[18:21], v[34:37], v[54:57], v[18:21]
	v_mfma_f32_16x16x32_bf16 v[14:17], v[34:37], v[58:61], v[14:17]
	v_mfma_f32_16x16x32_bf16 v[10:13], v[38:41], v[42:45], v[10:13]
	v_mfma_f32_16x16x32_bf16 v[6:9], v[38:41], v[46:49], v[6:9]
	v_mfma_f32_16x16x32_bf16 v[2:5], v[38:41], v[54:57], v[2:5]
	v_mfma_f32_16x16x32_bf16 v[78:81], v[38:41], v[58:61], v[78:81]
	s_waitcnt lgkmcnt(0)
	s_waitcnt vmcnt(0)
	s_barrier
	s_add_u32 m0, s14, 0
	v_mfma_f32_16x16x32_bf16 v[94:97], v[98:101], v[114:117], v[94:97]
	ds_read_b128 v[22:25], v132 offset:32800
	global_load_lds_dwordx4 v196, s[6:7] offset:0
	v_mfma_f32_16x16x32_bf16 v[90:93], v[98:101], v[118:121], v[90:93]
	ds_read_b128 v[42:45], v194 offset:32800
	global_load_lds_dwordx4 v197, s[6:7] offset:1024
	v_mfma_f32_16x16x32_bf16 v[86:89], v[98:101], v[122:125], v[86:89]
	ds_read_b128 v[46:49], v194 offset:34848
	global_load_lds_dwordx4 v198, s[6:7] offset:2048
	v_mfma_f32_16x16x32_bf16 v[82:85], v[98:101], v[126:129], v[82:85]
	ds_read_b128 v[26:29], v132 offset:34848
	global_load_lds_dwordx4 v199, s[6:7] offset:3072
	s_add_u32 m0, s14, 16384
	v_mfma_f32_16x16x32_bf16 v[74:77], v[102:105], v[114:117], v[74:77]
	ds_read_b128 v[54:57], v194 offset:36896
	global_load_lds_dwordx4 v196, s[8:9] offset:0
	v_mfma_f32_16x16x32_bf16 v[70:73], v[102:105], v[118:121], v[70:73]
	ds_read_b128 v[58:61], v194 offset:38944
	global_load_lds_dwordx4 v197, s[8:9] offset:1024
	v_mfma_f32_16x16x32_bf16 v[66:69], v[102:105], v[122:125], v[66:69]
	ds_read_b128 v[34:37], v132 offset:36896
	global_load_lds_dwordx4 v198, s[8:9] offset:2048
	v_mfma_f32_16x16x32_bf16 v[62:65], v[102:105], v[126:129], v[62:65]
	ds_read_b128 v[38:41], v132 offset:38944
	global_load_lds_dwordx4 v199, s[8:9] offset:3072
	v_mfma_f32_16x16x32_bf16 v[50:53], v[106:109], v[114:117], v[50:53]
	v_mfma_f32_16x16x32_bf16 v[30:33], v[106:109], v[118:121], v[30:33]
	v_mfma_f32_16x16x32_bf16 v[18:21], v[106:109], v[122:125], v[18:21]
	v_mfma_f32_16x16x32_bf16 v[14:17], v[106:109], v[126:129], v[14:17]
	v_mfma_f32_16x16x32_bf16 v[10:13], v[110:113], v[114:117], v[10:13]
	v_mfma_f32_16x16x32_bf16 v[6:9], v[110:113], v[118:121], v[6:9]
	v_mfma_f32_16x16x32_bf16 v[2:5], v[110:113], v[122:125], v[2:5]
	v_mfma_f32_16x16x32_bf16 v[78:81], v[110:113], v[126:129], v[78:81]
	s_add_u32 s98, s98, 1
	s_and_b32 s98, s98, 15
	s_cmp_eq_u32 s98, 0
	s_cselect_b32 s99, 0x800, 0
	s_add_u32 s6, s6, 0x80
	s_addc_u32 s7, s7, 0
	s_sub_u32 s6, s6, s99
	s_subb_u32 s7, s7, 0
	s_add_u32 s8, s8, 0x80
	s_addc_u32 s9, s9, 0
	s_sub_u32 s8, s8, s99
	s_subb_u32 s9, s9, 0
	s_waitcnt lgkmcnt(0)
	v_mfma_f32_16x16x32_bf16 v[94:97], v[22:25], v[42:45], v[94:97]
	ds_read_b128 v[98:101], v163 offset:32800
	v_mfma_f32_16x16x32_bf16 v[90:93], v[22:25], v[46:49], v[90:93]
	ds_read_b128 v[114:117], v195 offset:32800
	v_mfma_f32_16x16x32_bf16 v[86:89], v[22:25], v[54:57], v[86:89]
	ds_read_b128 v[118:121], v195 offset:34848
	v_mfma_f32_16x16x32_bf16 v[82:85], v[22:25], v[58:61], v[82:85]
	ds_read_b128 v[102:105], v163 offset:34848
	v_mfma_f32_16x16x32_bf16 v[74:77], v[26:29], v[42:45], v[74:77]
	ds_read_b128 v[122:125], v195 offset:36896
	v_mfma_f32_16x16x32_bf16 v[70:73], v[26:29], v[46:49], v[70:73]
	ds_read_b128 v[126:129], v195 offset:38944
	v_mfma_f32_16x16x32_bf16 v[66:69], v[26:29], v[54:57], v[66:69]
	ds_read_b128 v[106:109], v163 offset:36896
	v_mfma_f32_16x16x32_bf16 v[62:65], v[26:29], v[58:61], v[62:65]
	ds_read_b128 v[110:113], v163 offset:38944
	v_mfma_f32_16x16x32_bf16 v[50:53], v[34:37], v[42:45], v[50:53]
	v_mfma_f32_16x16x32_bf16 v[30:33], v[34:37], v[46:49], v[30:33]
	v_mfma_f32_16x16x32_bf16 v[18:21], v[34:37], v[54:57], v[18:21]
	v_mfma_f32_16x16x32_bf16 v[14:17], v[34:37], v[58:61], v[14:17]
	v_mfma_f32_16x16x32_bf16 v[10:13], v[38:41], v[42:45], v[10:13]
	v_mfma_f32_16x16x32_bf16 v[6:9], v[38:41], v[46:49], v[6:9]
	v_mfma_f32_16x16x32_bf16 v[2:5], v[38:41], v[54:57], v[2:5]
	v_mfma_f32_16x16x32_bf16 v[78:81], v[38:41], v[58:61], v[78:81]
	s_waitcnt lgkmcnt(0)
	s_waitcnt vmcnt(0)
	s_add_u32 s25, s25, 1
	s_cmp_lt_u32 s25, 7
	s_cbranch_scc1 .Lk_g1l1_loop
	s_barrier
	s_add_u32 m0, s14, 32768
	v_mfma_f32_16x16x32_bf16 v[94:97], v[98:101], v[114:117], v[94:97]
	ds_read_b128 v[22:25], v132 offset:32
	global_load_lds_dwordx4 v196, s[6:7] offset:0
	v_mfma_f32_16x16x32_bf16 v[90:93], v[98:101], v[118:121], v[90:93]
	ds_read_b128 v[42:45], v194 offset:32
	global_load_lds_dwordx4 v197, s[6:7] offset:1024
	v_mfma_f32_16x16x32_bf16 v[86:89], v[98:101], v[122:125], v[86:89]
	ds_read_b128 v[46:49], v194 offset:2080
	global_load_lds_dwordx4 v198, s[6:7] offset:2048
	v_mfma_f32_16x16x32_bf16 v[82:85], v[98:101], v[126:129], v[82:85]
	ds_read_b128 v[26:29], v132 offset:2080
	global_load_lds_dwordx4 v199, s[6:7] offset:3072
	s_add_u32 m0, s14, 49152
	v_mfma_f32_16x16x32_bf16 v[74:77], v[102:105], v[114:117], v[74:77]
	ds_read_b128 v[54:57], v194 offset:4128
	global_load_lds_dwordx4 v196, s[8:9] offset:0
	v_mfma_f32_16x16x32_bf16 v[70:73], v[102:105], v[118:121], v[70:73]
	ds_read_b128 v[58:61], v194 offset:6176
	global_load_lds_dwordx4 v197, s[8:9] offset:1024
	v_mfma_f32_16x16x32_bf16 v[66:69], v[102:105], v[122:125], v[66:69]
	ds_read_b128 v[34:37], v132 offset:4128
	global_load_lds_dwordx4 v198, s[8:9] offset:2048
	v_mfma_f32_16x16x32_bf16 v[62:65], v[102:105], v[126:129], v[62:65]
	ds_read_b128 v[38:41], v132 offset:6176
	global_load_lds_dwordx4 v199, s[8:9] offset:3072
	v_mfma_f32_16x16x32_bf16 v[50:53], v[106:109], v[114:117], v[50:53]
	v_mfma_f32_16x16x32_bf16 v[30:33], v[106:109], v[118:121], v[30:33]
	v_mfma_f32_16x16x32_bf16 v[18:21], v[106:109], v[122:125], v[18:21]
	v_mfma_f32_16x16x32_bf16 v[14:17], v[106:109], v[126:129], v[14:17]
	v_mfma_f32_16x16x32_bf16 v[10:13], v[110:113], v[114:117], v[10:13]
	v_mfma_f32_16x16x32_bf16 v[6:9], v[110:113], v[118:121], v[6:9]
	v_mfma_f32_16x16x32_bf16 v[2:5], v[110:113], v[122:125], v[2:5]
	v_mfma_f32_16x16x32_bf16 v[78:81], v[110:113], v[126:129], v[78:81]
	s_add_u32 s98, s98, 1
	s_and_b32 s98, s98, 15
	s_cmp_eq_u32 s98, 0
	s_cselect_b32 s99, 0x800, 0
	s_add_u32 s6, s6, 0x80
	s_addc_u32 s7, s7, 0
	s_sub_u32 s6, s6, s99
	s_subb_u32 s7, s7, 0
	s_add_u32 s8, s8, 0x80
	s_addc_u32 s9, s9, 0
	s_sub_u32 s8, s8, s99
	s_subb_u32 s9, s9, 0
	s_waitcnt lgkmcnt(0)
	v_mfma_f32_16x16x32_bf16 v[94:97], v[22:25], v[42:45], v[94:97]
	ds_read_b128 v[98:101], v163 offset:32
	v_mfma_f32_16x16x32_bf16 v[90:93], v[22:25], v[46:49], v[90:93]
	ds_read_b128 v[114:117], v195 offset:32
	v_mfma_f32_16x16x32_bf16 v[86:89], v[22:25], v[54:57], v[86:89]
	ds_read_b128 v[118:121], v195 offset:2080
	v_mfma_f32_16x16x32_bf16 v[82:85], v[22:25], v[58:61], v[82:85]
	ds_read_b128 v[102:105], v163 offset:2080
	v_mfma_f32_16x16x32_bf16 v[74:77], v[26:29], v[42:45], v[74:77]
	ds_read_b128 v[122:125], v195 offset:4128
	v_mfma_f32_16x16x32_bf16 v[70:73], v[26:29], v[46:49], v[70:73]
	ds_read_b128 v[126:129], v195 offset:6176
	v_mfma_f32_16x16x32_bf16 v[66:69], v[26:29], v[54:57], v[66:69]
	ds_read_b128 v[106:109], v163 offset:4128
	v_mfma_f32_16x16x32_bf16 v[62:65], v[26:29], v[58:61], v[62:65]
	ds_read_b128 v[110:113], v163 offset:6176
	v_mfma_f32_16x16x32_bf16 v[50:53], v[34:37], v[42:45], v[50:53]
	v_mfma_f32_16x16x32_bf16 v[30:33], v[34:37], v[46:49], v[30:33]
	v_mfma_f32_16x16x32_bf16 v[18:21], v[34:37], v[54:57], v[18:21]
	v_mfma_f32_16x16x32_bf16 v[14:17], v[34:37], v[58:61], v[14:17]
	v_mfma_f32_16x16x32_bf16 v[10:13], v[38:41], v[42:45], v[10:13]
	v_mfma_f32_16x16x32_bf16 v[6:9], v[38:41], v[46:49], v[6:9]
	v_mfma_f32_16x16x32_bf16 v[2:5], v[38:41], v[54:57], v[2:5]
	v_mfma_f32_16x16x32_bf16 v[78:81], v[38:41], v[58:61], v[78:81]
	s_waitcnt lgkmcnt(0)
	s_waitcnt vmcnt(0)
	s_barrier
	v_mfma_f32_16x16x32_bf16 v[94:97], v[98:101], v[114:117], v[94:97]
	ds_read_b128 v[22:25], v132 offset:32800
	v_mfma_f32_16x16x32_bf16 v[90:93], v[98:101], v[118:121], v[90:93]
	ds_read_b128 v[42:45], v194 offset:32800
	v_mfma_f32_16x16x32_bf16 v[86:89], v[98:101], v[122:125], v[86:89]
	ds_read_b128 v[46:49], v194 offset:34848
	v_mfma_f32_16x16x32_bf16 v[82:85], v[98:101], v[126:129], v[82:85]
	ds_read_b128 v[26:29], v132 offset:34848
	v_mfma_f32_16x16x32_bf16 v[74:77], v[102:105], v[114:117], v[74:77]
	ds_read_b128 v[54:57], v194 offset:36896
	v_mfma_f32_16x16x32_bf16 v[70:73], v[102:105], v[118:121], v[70:73]
	ds_read_b128 v[58:61], v194 offset:38944
	v_mfma_f32_16x16x32_bf16 v[66:69], v[102:105], v[122:125], v[66:69]
	ds_read_b128 v[34:37], v132 offset:36896
	v_mfma_f32_16x16x32_bf16 v[62:65], v[102:105], v[126:129], v[62:65]
	ds_read_b128 v[38:41], v132 offset:38944
	v_mfma_f32_16x16x32_bf16 v[50:53], v[106:109], v[114:117], v[50:53]
	v_mfma_f32_16x16x32_bf16 v[30:33], v[106:109], v[118:121], v[30:33]
	v_mfma_f32_16x16x32_bf16 v[18:21], v[106:109], v[122:125], v[18:21]
	v_mfma_f32_16x16x32_bf16 v[14:17], v[106:109], v[126:129], v[14:17]
	v_mfma_f32_16x16x32_bf16 v[10:13], v[110:113], v[114:117], v[10:13]
	v_mfma_f32_16x16x32_bf16 v[6:9], v[110:113], v[118:121], v[6:9]
	v_mfma_f32_16x16x32_bf16 v[2:5], v[110:113], v[122:125], v[2:5]
	v_mfma_f32_16x16x32_bf16 v[78:81], v[110:113], v[126:129], v[78:81]
	s_waitcnt lgkmcnt(0)
	v_mfma_f32_16x16x32_bf16 v[94:97], v[22:25], v[42:45], v[94:97]
	ds_read_b128 v[98:101], v163 offset:32800
	v_mfma_f32_16x16x32_bf16 v[90:93], v[22:25], v[46:49], v[90:93]
	ds_read_b128 v[114:117], v195 offset:32800
	v_mfma_f32_16x16x32_bf16 v[86:89], v[22:25], v[54:57], v[86:89]
	ds_read_b128 v[118:121], v195 offset:34848
	v_mfma_f32_16x16x32_bf16 v[82:85], v[22:25], v[58:61], v[82:85]
	ds_read_b128 v[102:105], v163 offset:34848
	v_mfma_f32_16x16x32_bf16 v[74:77], v[26:29], v[42:45], v[74:77]
	ds_read_b128 v[122:125], v195 offset:36896
	v_mfma_f32_16x16x32_bf16 v[70:73], v[26:29], v[46:49], v[70:73]
	ds_read_b128 v[126:129], v195 offset:38944
	v_mfma_f32_16x16x32_bf16 v[66:69], v[26:29], v[54:57], v[66:69]
	ds_read_b128 v[106:109], v163 offset:36896
	v_mfma_f32_16x16x32_bf16 v[62:65], v[26:29], v[58:61], v[62:65]
	ds_read_b128 v[110:113], v163 offset:38944
	v_mfma_f32_16x16x32_bf16 v[50:53], v[34:37], v[42:45], v[50:53]
	v_mfma_f32_16x16x32_bf16 v[30:33], v[34:37], v[46:49], v[30:33]
	v_mfma_f32_16x16x32_bf16 v[18:21], v[34:37], v[54:57], v[18:21]
	v_mfma_f32_16x16x32_bf16 v[14:17], v[34:37], v[58:61], v[14:17]
	v_mfma_f32_16x16x32_bf16 v[10:13], v[38:41], v[42:45], v[10:13]
	v_mfma_f32_16x16x32_bf16 v[6:9], v[38:41], v[46:49], v[6:9]
	v_mfma_f32_16x16x32_bf16 v[2:5], v[38:41], v[54:57], v[2:5]
	v_mfma_f32_16x16x32_bf16 v[78:81], v[38:41], v[58:61], v[78:81]
	s_waitcnt lgkmcnt(0)
	v_mfma_f32_16x16x32_bf16 v[94:97], v[98:101], v[114:117], v[94:97]
	v_mfma_f32_16x16x32_bf16 v[90:93], v[98:101], v[118:121], v[90:93]
	v_mfma_f32_16x16x32_bf16 v[86:89], v[98:101], v[122:125], v[86:89]
	v_mfma_f32_16x16x32_bf16 v[82:85], v[98:101], v[126:129], v[82:85]
	v_mfma_f32_16x16x32_bf16 v[74:77], v[102:105], v[114:117], v[74:77]
	v_mfma_f32_16x16x32_bf16 v[70:73], v[102:105], v[118:121], v[70:73]
	v_mfma_f32_16x16x32_bf16 v[66:69], v[102:105], v[122:125], v[66:69]
	v_mfma_f32_16x16x32_bf16 v[62:65], v[102:105], v[126:129], v[62:65]
	v_mfma_f32_16x16x32_bf16 v[50:53], v[106:109], v[114:117], v[50:53]
	v_mfma_f32_16x16x32_bf16 v[30:33], v[106:109], v[118:121], v[30:33]
	v_mfma_f32_16x16x32_bf16 v[18:21], v[106:109], v[122:125], v[18:21]
	v_mfma_f32_16x16x32_bf16 v[14:17], v[106:109], v[126:129], v[14:17]
	v_mfma_f32_16x16x32_bf16 v[10:13], v[110:113], v[114:117], v[10:13]
	v_mfma_f32_16x16x32_bf16 v[6:9], v[110:113], v[118:121], v[6:9]
	v_mfma_f32_16x16x32_bf16 v[2:5], v[110:113], v[122:125], v[2:5]
	v_mfma_f32_16x16x32_bf16 v[78:81], v[110:113], v[126:129], v[78:81]
	s_waitcnt vmcnt(7)
	v_add_u32_e32 v22, 0x400, v170
	s_barrier
	ds_write2_b32 v170, v94, v90 offset1:16
	ds_write2_b32 v170, v95, v91 offset0:132 offset1:148
	ds_write2_b32 v22, v96, v92 offset0:8 offset1:24
	ds_write2_b32 v22, v97, v93 offset0:140 offset1:156
	ds_write2_b32 v170, v86, v82 offset0:32 offset1:48
	ds_write2_b32 v170, v87, v83 offset0:164 offset1:180
	ds_write2_b32 v22, v88, v84 offset0:40 offset1:56
	ds_write2_b32 v22, v89, v85 offset0:172 offset1:188
	v_add_u32_e32 v22, 0x2000, v170
	v_add_u32_e32 v23, 0x2400, v170
	s_cmp_gt_i32 s66, 63
	ds_write2_b32 v22, v74, v70 offset0:64 offset1:80
	ds_write2_b32 v22, v75, v71 offset0:196 offset1:212
	ds_write2_b32 v23, v76, v72 offset0:72 offset1:88
	ds_write2_b32 v23, v77, v73 offset0:204 offset1:220
	ds_write2_b32 v22, v66, v62 offset0:96 offset1:112
	ds_write2_b32 v22, v67, v63 offset0:228 offset1:244
	ds_write2_b32 v23, v68, v64 offset0:104 offset1:120
	ds_write2_b32 v23, v69, v65 offset0:236 offset1:252
	v_add_u32_e32 v22, 0x4000, v170
	v_add_u32_e32 v23, 0x4400, v170
	v_add_u32_e32 v24, 0x4800, v170
	s_cselect_b64 s[34:35], -1, 0
	s_cmp_lt_i32 s66, 64
	ds_write2_b32 v22, v50, v30 offset0:128 offset1:144
	ds_write2_b32 v23, v51, v31 offset0:4 offset1:20
	ds_write2_b32 v23, v52, v32 offset0:136 offset1:152
	ds_write2_b32 v24, v53, v33 offset0:12 offset1:28
	ds_write2_b32 v22, v18, v14 offset0:160 offset1:176
	ds_write2_b32 v23, v19, v15 offset0:36 offset1:52
	ds_write2_b32 v23, v20, v16 offset0:168 offset1:184
	ds_write2_b32 v24, v21, v17 offset0:44 offset1:60
	v_add_u32_e32 v14, 0x6000, v170
	s_cselect_b64 s[36:37], -1, 0
	s_add_i32 s6, s28, 0xffffe000
	ds_write2_b32 v14, v10, v6 offset0:192 offset1:208
	v_add_u32_e32 v6, 0x6400, v170
	s_lshr_b32 s68, s6, 10
	s_ashr_i32 s30, s66, 1
	s_and_b32 s67, s28, 0x380
	s_and_b32 s25, s28, 0x80
	ds_write2_b32 v6, v11, v7 offset0:68 offset1:84
	ds_write2_b32 v6, v12, v8 offset0:200 offset1:216
	v_add_u32_e32 v7, 0x6800, v170
	v_add_u32_e32 v164, s28, v167
	s_cmp_gt_i32 s24, 9
	s_mov_b64 s[6:7], -1
	ds_write2_b32 v7, v13, v9 offset0:76 offset1:92
	ds_write2_b32 v14, v2, v78 offset0:224 offset1:240
	ds_write2_b32 v6, v3, v79 offset0:100 offset1:116
	ds_write2_b32 v6, v4, v80 offset0:232 offset1:248
	ds_write2_b32 v7, v5, v81 offset0:108 offset1:124
	s_waitcnt lgkmcnt(0)
	s_barrier
	s_cbranch_scc0 .LBB0_979
	s_cmp_gt_u32 s24, 11
	s_cbranch_scc0 .LBB0_964
	s_cmp_lg_u32 s24, 36
	s_cbranch_scc0 .LBB0_959
	s_sub_i32 s6, s24, 20
	s_cmp_gt_u32 s6, 7
	s_mov_b64 s[6:7], -1
	s_cbranch_scc0 .LBB0_955
	s_cmp_lt_u32 s24, 16
	s_cselect_b64 s[46:47], -1, 0
	s_cmp_gt_u32 s24, 15
	s_mov_b64 s[52:53], -1
	s_cbranch_scc0 .LBB0_942
	s_cmp_gt_u32 s24, 19
	s_cbranch_scc0 .LBB0_939
	s_mov_b64 s[48:49], -1
	s_cmp_gt_u32 s24, 35
	s_mov_b64 s[8:9], -1
	s_cbranch_scc0 .LBB0_937
	s_lshl_b64 s[6:7], s[28:29], 12
	s_add_u32 s6, s42, s6
	s_addc_u32 s7, s43, s7
	s_mov_b64 s[8:9], 0

.LBB0_1292:
	s_and_b32 s70, s69, 0xff
	s_mul_i32 s4, s70, 0xab
	s_lshr_b32 s73, s4, 11
	s_mul_i32 s4, s73, 12
	s_sub_i32 s4, s69, s4
	s_and_b32 s4, s4, 0xff
	s_lshl_b32 s4, s4, 10
	s_or_b32 s8, s4, s52
	s_lshl_b32 s71, s8, 10
	s_lshl_b32 s4, s8, 11
	s_add_u32 s4, s53, s4
	s_addc_u32 s5, s54, 0
	s_lshl_b32 s6, s73, 17
	s_add_i32 s72, s6, 0x100000
	s_lshl_b32 s6, s72, 1
	s_add_u32 s6, s55, s6
	s_addc_u32 s7, s56, 0
	v_and_b32_e32 v164, 15, v0
	v_bfe_u32 v165, v0, 4, 2
	v_and_b32_e32 v111, 7, v164
	v_xor_b32_e32 v165, v165, v111
	v_lshlrev_b32_e32 v165, 4, v165
	v_lshl_or_b32 v165, v164, 7, v165
	v_bfe_u32 v164, v0, 7, 1
	v_lshl_or_b32 v100, v164, 13, v165
	v_bfe_u32 v164, v0, 6, 1
	v_lshl_or_b32 v158, v164, 13, v165
	v_or_b32_e32 v158, 0x4000, v158
	v_xor_b32_e32 v111, 64, v100
	v_xor_b32_e32 v159, 64, v158
	v_bfe_u32 v164, v0, 3, 3
	v_and_b32_e32 v165, 7, v0
	v_xor_b32_e32 v165, v165, v164
	v_lshlrev_b32_e32 v165, 4, v165
	v_lshl_or_b32 v165, v164, 11, v165
	v_lshrrev_b32_e32 v164, 6, v0
	v_and_b32_e32 v164, 3, v164
	v_lshl_or_b32 v160, v164, 16, v165
	v_add_u32_e32 v161, 0x3c00, v160
	v_add_u32_e32 v162, 0x7800, v160
	v_add_u32_e32 v163, 0xb400, v160
	v_lshlrev_b32_e32 v164, 12, v164
	s_nop 0
	v_readfirstlane_b32 s10, v164
	s_add_u32 s10, s10, 32
	v_mov_b32_e32 v94, 0
	v_mov_b32_e32 v95, 0
	v_mov_b32_e32 v96, 0
	v_mov_b32_e32 v97, 0
	v_mov_b32_e32 v90, 0
	v_mov_b32_e32 v91, 0
	v_mov_b32_e32 v92, 0
	v_mov_b32_e32 v93, 0
	v_mov_b32_e32 v82, 0
	v_mov_b32_e32 v83, 0
	v_mov_b32_e32 v84, 0
	v_mov_b32_e32 v85, 0
	v_mov_b32_e32 v78, 0
	v_mov_b32_e32 v79, 0
	v_mov_b32_e32 v80, 0
	v_mov_b32_e32 v81, 0
	v_mov_b32_e32 v74, 0
	v_mov_b32_e32 v75, 0
	v_mov_b32_e32 v76, 0
	v_mov_b32_e32 v77, 0
	v_mov_b32_e32 v70, 0
	v_mov_b32_e32 v71, 0
	v_mov_b32_e32 v72, 0
	v_mov_b32_e32 v73, 0
	v_mov_b32_e32 v66, 0
	v_mov_b32_e32 v67, 0
	v_mov_b32_e32 v68, 0
	v_mov_b32_e32 v69, 0
	v_mov_b32_e32 v58, 0
	v_mov_b32_e32 v59, 0
	v_mov_b32_e32 v60, 0
	v_mov_b32_e32 v61, 0
	v_mov_b32_e32 v26, 0
	v_mov_b32_e32 v27, 0
	v_mov_b32_e32 v28, 0
	v_mov_b32_e32 v29, 0
	v_mov_b32_e32 v22, 0
	v_mov_b32_e32 v23, 0
	v_mov_b32_e32 v24, 0
	v_mov_b32_e32 v25, 0
	v_mov_b32_e32 v18, 0
	v_mov_b32_e32 v19, 0
	v_mov_b32_e32 v20, 0
	v_mov_b32_e32 v21, 0
	v_mov_b32_e32 v14, 0
	v_mov_b32_e32 v15, 0
	v_mov_b32_e32 v16, 0
	v_mov_b32_e32 v17, 0
	v_mov_b32_e32 v10, 0
	v_mov_b32_e32 v11, 0
	v_mov_b32_e32 v12, 0
	v_mov_b32_e32 v13, 0
	v_mov_b32_e32 v6, 0
	v_mov_b32_e32 v7, 0
	v_mov_b32_e32 v8, 0
	v_mov_b32_e32 v9, 0
	v_mov_b32_e32 v2, 0
	v_mov_b32_e32 v3, 0
	v_mov_b32_e32 v4, 0
	v_mov_b32_e32 v5, 0
	v_mov_b32_e32 v86, 0
	v_mov_b32_e32 v87, 0
	v_mov_b32_e32 v88, 0
	v_mov_b32_e32 v89, 0
	v_mov_b32_e32 v114, 0
	v_mov_b32_e32 v115, 0
	v_mov_b32_e32 v116, 0
	v_mov_b32_e32 v117, 0
	v_mov_b32_e32 v118, 0
	v_mov_b32_e32 v119, 0
	v_mov_b32_e32 v120, 0
	v_mov_b32_e32 v121, 0
	v_mov_b32_e32 v122, 0
	v_mov_b32_e32 v123, 0
	v_mov_b32_e32 v124, 0
	v_mov_b32_e32 v125, 0
	v_mov_b32_e32 v138, 0
	v_mov_b32_e32 v139, 0
	v_mov_b32_e32 v140, 0
	v_mov_b32_e32 v141, 0
	v_mov_b32_e32 v142, 0
	v_mov_b32_e32 v143, 0
	v_mov_b32_e32 v144, 0
	v_mov_b32_e32 v145, 0
	v_mov_b32_e32 v146, 0
	v_mov_b32_e32 v147, 0
	v_mov_b32_e32 v148, 0
	v_mov_b32_e32 v149, 0
	v_mov_b32_e32 v150, 0
	v_mov_b32_e32 v151, 0
	v_mov_b32_e32 v152, 0
	v_mov_b32_e32 v153, 0
	v_mov_b32_e32 v154, 0
	v_mov_b32_e32 v155, 0
	v_mov_b32_e32 v156, 0
	v_mov_b32_e32 v157, 0
	s_waitcnt lgkmcnt(0)
	s_barrier
	v_readlane_b32 s98, v255, 16
	s_lshr_b32 s98, s98, 3
	s_and_b32 s98, s98, 3
	s_lshl_b32 s98, s98, 2
	s_lshl_b32 s99, s98, 7
	s_add_u32 s4, s4, s99
	s_addc_u32 s5, s5, 0
	s_add_u32 s6, s6, s99
	s_addc_u32 s7, s7, 0
	s_add_u32 m0, s10, 0
	s_nop 0
	global_load_lds_dwordx4 v160, s[4:5] offset:0
	global_load_lds_dwordx4 v161, s[4:5] offset:1024
	global_load_lds_dwordx4 v162, s[4:5] offset:2048
	global_load_lds_dwordx4 v163, s[4:5] offset:3072
	s_add_u32 m0, s10, 16384
	s_nop 0
	global_load_lds_dwordx4 v160, s[6:7] offset:0
	global_load_lds_dwordx4 v161, s[6:7] offset:1024
	global_load_lds_dwordx4 v162, s[6:7] offset:2048
	global_load_lds_dwordx4 v163, s[6:7] offset:3072
	s_add_u32 s98, s98, 1
	s_and_b32 s98, s98, 15
	s_cmp_eq_u32 s98, 0
	s_cselect_b32 s99, 0x800, 0
	s_add_u32 s4, s4, 0x80
	s_addc_u32 s5, s5, 0
	s_sub_u32 s4, s4, s99
	s_subb_u32 s5, s5, 0
	s_add_u32 s6, s6, 0x80
	s_addc_u32 s7, s7, 0
	s_sub_u32 s6, s6, s99
	s_subb_u32 s7, s7, 0
	s_mov_b32 s9, 0
	s_waitcnt vmcnt(0)
.Lk_aol1a_loop:
	s_barrier
	s_add_u32 m0, s10, 32768
	v_mfma_f32_16x16x32_bf16 v[94:97], v[114:117], v[142:145], v[94:97]
	ds_read_b128 v[30:33], v100 offset:32
	global_load_lds_dwordx4 v160, s[4:5] offset:0
	v_mfma_f32_16x16x32_bf16 v[90:93], v[114:117], v[146:149], v[90:93]
	ds_read_b128 v[46:49], v158 offset:32
	global_load_lds_dwordx4 v161, s[4:5] offset:1024
	v_mfma_f32_16x16x32_bf16 v[82:85], v[114:117], v[150:153], v[82:85]
	ds_read_b128 v[50:53], v158 offset:2080
	global_load_lds_dwordx4 v162, s[4:5] offset:2048
	v_mfma_f32_16x16x32_bf16 v[78:81], v[114:117], v[154:157], v[78:81]
	ds_read_b128 v[34:37], v100 offset:2080
	global_load_lds_dwordx4 v163, s[4:5] offset:3072
	s_add_u32 m0, s10, 49152
	v_mfma_f32_16x16x32_bf16 v[74:77], v[118:121], v[142:145], v[74:77]
	ds_read_b128 v[54:57], v158 offset:4128
	global_load_lds_dwordx4 v160, s[6:7] offset:0
	v_mfma_f32_16x16x32_bf16 v[70:73], v[118:121], v[146:149], v[70:73]
	ds_read_b128 v[62:65], v158 offset:6176
	global_load_lds_dwordx4 v161, s[6:7] offset:1024
	v_mfma_f32_16x16x32_bf16 v[66:69], v[118:121], v[150:153], v[66:69]
	ds_read_b128 v[38:41], v100 offset:4128
	global_load_lds_dwordx4 v162, s[6:7] offset:2048
	v_mfma_f32_16x16x32_bf16 v[58:61], v[118:121], v[154:157], v[58:61]
	ds_read_b128 v[42:45], v100 offset:6176
	global_load_lds_dwordx4 v163, s[6:7] offset:3072
	v_mfma_f32_16x16x32_bf16 v[26:29], v[122:125], v[142:145], v[26:29]
	v_mfma_f32_16x16x32_bf16 v[22:25], v[122:125], v[146:149], v[22:25]
	v_mfma_f32_16x16x32_bf16 v[18:21], v[122:125], v[150:153], v[18:21]
	v_mfma_f32_16x16x32_bf16 v[14:17], v[122:125], v[154:157], v[14:17]
	v_mfma_f32_16x16x32_bf16 v[10:13], v[138:141], v[142:145], v[10:13]
	v_mfma_f32_16x16x32_bf16 v[6:9], v[138:141], v[146:149], v[6:9]
	v_mfma_f32_16x16x32_bf16 v[2:5], v[138:141], v[150:153], v[2:5]
	v_mfma_f32_16x16x32_bf16 v[86:89], v[138:141], v[154:157], v[86:89]
	s_add_u32 s98, s98, 1
	s_and_b32 s98, s98, 15
	s_cmp_eq_u32 s98, 0
	s_cselect_b32 s99, 0x800, 0
	s_add_u32 s4, s4, 0x80
	s_addc_u32 s5, s5, 0
	s_sub_u32 s4, s4, s99
	s_subb_u32 s5, s5, 0
	s_add_u32 s6, s6, 0x80
	s_addc_u32 s7, s7, 0
	s_sub_u32 s6, s6, s99
	s_subb_u32 s7, s7, 0
	s_waitcnt lgkmcnt(0)
	v_mfma_f32_16x16x32_bf16 v[94:97], v[30:33], v[46:49], v[94:97]
	ds_read_b128 v[114:117], v111 offset:32
	v_mfma_f32_16x16x32_bf16 v[90:93], v[30:33], v[50:53], v[90:93]
	ds_read_b128 v[142:145], v159 offset:32
	v_mfma_f32_16x16x32_bf16 v[82:85], v[30:33], v[54:57], v[82:85]
	ds_read_b128 v[146:149], v159 offset:2080
	v_mfma_f32_16x16x32_bf16 v[78:81], v[30:33], v[62:65], v[78:81]
	ds_read_b128 v[118:121], v111 offset:2080
	v_mfma_f32_16x16x32_bf16 v[74:77], v[34:37], v[46:49], v[74:77]
	ds_read_b128 v[150:153], v159 offset:4128
	v_mfma_f32_16x16x32_bf16 v[70:73], v[34:37], v[50:53], v[70:73]
	ds_read_b128 v[154:157], v159 offset:6176
	v_mfma_f32_16x16x32_bf16 v[66:69], v[34:37], v[54:57], v[66:69]
	ds_read_b128 v[122:125], v111 offset:4128
	v_mfma_f32_16x16x32_bf16 v[58:61], v[34:37], v[62:65], v[58:61]
	ds_read_b128 v[138:141], v111 offset:6176
	v_mfma_f32_16x16x32_bf16 v[26:29], v[38:41], v[46:49], v[26:29]
	v_mfma_f32_16x16x32_bf16 v[22:25], v[38:41], v[50:53], v[22:25]
	v_mfma_f32_16x16x32_bf16 v[18:21], v[38:41], v[54:57], v[18:21]
	v_mfma_f32_16x16x32_bf16 v[14:17], v[38:41], v[62:65], v[14:17]
	v_mfma_f32_16x16x32_bf16 v[10:13], v[42:45], v[46:49], v[10:13]
	v_mfma_f32_16x16x32_bf16 v[6:9], v[42:45], v[50:53], v[6:9]
	v_mfma_f32_16x16x32_bf16 v[2:5], v[42:45], v[54:57], v[2:5]
	v_mfma_f32_16x16x32_bf16 v[86:89], v[42:45], v[62:65], v[86:89]
	s_waitcnt lgkmcnt(0)
	s_waitcnt vmcnt(0)
	s_barrier
	s_add_u32 m0, s10, 0
	v_mfma_f32_16x16x32_bf16 v[94:97], v[114:117], v[142:145], v[94:97]
	ds_read_b128 v[30:33], v100 offset:32800
	global_load_lds_dwordx4 v160, s[4:5] offset:0
	v_mfma_f32_16x16x32_bf16 v[90:93], v[114:117], v[146:149], v[90:93]
	ds_read_b128 v[46:49], v158 offset:32800
	global_load_lds_dwordx4 v161, s[4:5] offset:1024
	v_mfma_f32_16x16x32_bf16 v[82:85], v[114:117], v[150:153], v[82:85]
	ds_read_b128 v[50:53], v158 offset:34848
	global_load_lds_dwordx4 v162, s[4:5] offset:2048
	v_mfma_f32_16x16x32_bf16 v[78:81], v[114:117], v[154:157], v[78:81]
	ds_read_b128 v[34:37], v100 offset:34848
	global_load_lds_dwordx4 v163, s[4:5] offset:3072
	s_add_u32 m0, s10, 16384
	v_mfma_f32_16x16x32_bf16 v[74:77], v[118:121], v[142:145], v[74:77]
	ds_read_b128 v[54:57], v158 offset:36896
	global_load_lds_dwordx4 v160, s[6:7] offset:0
	v_mfma_f32_16x16x32_bf16 v[70:73], v[118:121], v[146:149], v[70:73]
	ds_read_b128 v[62:65], v158 offset:38944
	global_load_lds_dwordx4 v161, s[6:7] offset:1024
	v_mfma_f32_16x16x32_bf16 v[66:69], v[118:121], v[150:153], v[66:69]
	ds_read_b128 v[38:41], v100 offset:36896
	global_load_lds_dwordx4 v162, s[6:7] offset:2048
	v_mfma_f32_16x16x32_bf16 v[58:61], v[118:121], v[154:157], v[58:61]
	ds_read_b128 v[42:45], v100 offset:38944
	global_load_lds_dwordx4 v163, s[6:7] offset:3072
	v_mfma_f32_16x16x32_bf16 v[26:29], v[122:125], v[142:145], v[26:29]
	v_mfma_f32_16x16x32_bf16 v[22:25], v[122:125], v[146:149], v[22:25]
	v_mfma_f32_16x16x32_bf16 v[18:21], v[122:125], v[150:153], v[18:21]
	v_mfma_f32_16x16x32_bf16 v[14:17], v[122:125], v[154:157], v[14:17]
	v_mfma_f32_16x16x32_bf16 v[10:13], v[138:141], v[142:145], v[10:13]
	v_mfma_f32_16x16x32_bf16 v[6:9], v[138:141], v[146:149], v[6:9]
	v_mfma_f32_16x16x32_bf16 v[2:5], v[138:141], v[150:153], v[2:5]
	v_mfma_f32_16x16x32_bf16 v[86:89], v[138:141], v[154:157], v[86:89]
	s_add_u32 s98, s98, 1
	s_and_b32 s98, s98, 15
	s_cmp_eq_u32 s98, 0
	s_cselect_b32 s99, 0x800, 0
	s_add_u32 s4, s4, 0x80
	s_addc_u32 s5, s5, 0
	s_sub_u32 s4, s4, s99
	s_subb_u32 s5, s5, 0
	s_add_u32 s6, s6, 0x80
	s_addc_u32 s7, s7, 0
	s_sub_u32 s6, s6, s99
	s_subb_u32 s7, s7, 0
	s_waitcnt lgkmcnt(0)
	v_mfma_f32_16x16x32_bf16 v[94:97], v[30:33], v[46:49], v[94:97]
	ds_read_b128 v[114:117], v111 offset:32800
	v_mfma_f32_16x16x32_bf16 v[90:93], v[30:33], v[50:53], v[90:93]
	ds_read_b128 v[142:145], v159 offset:32800
	v_mfma_f32_16x16x32_bf16 v[82:85], v[30:33], v[54:57], v[82:85]
	ds_read_b128 v[146:149], v159 offset:34848
	v_mfma_f32_16x16x32_bf16 v[78:81], v[30:33], v[62:65], v[78:81]
	ds_read_b128 v[118:121], v111 offset:34848
	v_mfma_f32_16x16x32_bf16 v[74:77], v[34:37], v[46:49], v[74:77]
	ds_read_b128 v[150:153], v159 offset:36896
	v_mfma_f32_16x16x32_bf16 v[70:73], v[34:37], v[50:53], v[70:73]
	ds_read_b128 v[154:157], v159 offset:38944
	v_mfma_f32_16x16x32_bf16 v[66:69], v[34:37], v[54:57], v[66:69]
	ds_read_b128 v[122:125], v111 offset:36896
	v_mfma_f32_16x16x32_bf16 v[58:61], v[34:37], v[62:65], v[58:61]
	ds_read_b128 v[138:141], v111 offset:38944
	v_mfma_f32_16x16x32_bf16 v[26:29], v[38:41], v[46:49], v[26:29]
	v_mfma_f32_16x16x32_bf16 v[22:25], v[38:41], v[50:53], v[22:25]
	v_mfma_f32_16x16x32_bf16 v[18:21], v[38:41], v[54:57], v[18:21]
	v_mfma_f32_16x16x32_bf16 v[14:17], v[38:41], v[62:65], v[14:17]
	v_mfma_f32_16x16x32_bf16 v[10:13], v[42:45], v[46:49], v[10:13]
	v_mfma_f32_16x16x32_bf16 v[6:9], v[42:45], v[50:53], v[6:9]
	v_mfma_f32_16x16x32_bf16 v[2:5], v[42:45], v[54:57], v[2:5]
	v_mfma_f32_16x16x32_bf16 v[86:89], v[42:45], v[62:65], v[86:89]
	s_waitcnt lgkmcnt(0)
	s_waitcnt vmcnt(0)
	s_add_u32 s9, s9, 1
	s_cmp_lt_u32 s9, 7
	s_cbranch_scc1 .Lk_aol1a_loop
	s_barrier
	s_add_u32 m0, s10, 32768
	v_mfma_f32_16x16x32_bf16 v[94:97], v[114:117], v[142:145], v[94:97]
	ds_read_b128 v[30:33], v100 offset:32
	global_load_lds_dwordx4 v160, s[4:5] offset:0
	v_mfma_f32_16x16x32_bf16 v[90:93], v[114:117], v[146:149], v[90:93]
	ds_read_b128 v[46:49], v158 offset:32
	global_load_lds_dwordx4 v161, s[4:5] offset:1024
	v_mfma_f32_16x16x32_bf16 v[82:85], v[114:117], v[150:153], v[82:85]
	ds_read_b128 v[50:53], v158 offset:2080
	global_load_lds_dwordx4 v162, s[4:5] offset:2048
	v_mfma_f32_16x16x32_bf16 v[78:81], v[114:117], v[154:157], v[78:81]
	ds_read_b128 v[34:37], v100 offset:2080
	global_load_lds_dwordx4 v163, s[4:5] offset:3072
	s_add_u32 m0, s10, 49152
	v_mfma_f32_16x16x32_bf16 v[74:77], v[118:121], v[142:145], v[74:77]
	ds_read_b128 v[54:57], v158 offset:4128
	global_load_lds_dwordx4 v160, s[6:7] offset:0
	v_mfma_f32_16x16x32_bf16 v[70:73], v[118:121], v[146:149], v[70:73]
	ds_read_b128 v[62:65], v158 offset:6176
	global_load_lds_dwordx4 v161, s[6:7] offset:1024
	v_mfma_f32_16x16x32_bf16 v[66:69], v[118:121], v[150:153], v[66:69]
	ds_read_b128 v[38:41], v100 offset:4128
	global_load_lds_dwordx4 v162, s[6:7] offset:2048
	v_mfma_f32_16x16x32_bf16 v[58:61], v[118:121], v[154:157], v[58:61]
	ds_read_b128 v[42:45], v100 offset:6176
	global_load_lds_dwordx4 v163, s[6:7] offset:3072
	v_mfma_f32_16x16x32_bf16 v[26:29], v[122:125], v[142:145], v[26:29]
	v_mfma_f32_16x16x32_bf16 v[22:25], v[122:125], v[146:149], v[22:25]
	v_mfma_f32_16x16x32_bf16 v[18:21], v[122:125], v[150:153], v[18:21]
	v_mfma_f32_16x16x32_bf16 v[14:17], v[122:125], v[154:157], v[14:17]
	v_mfma_f32_16x16x32_bf16 v[10:13], v[138:141], v[142:145], v[10:13]
	v_mfma_f32_16x16x32_bf16 v[6:9], v[138:141], v[146:149], v[6:9]
	v_mfma_f32_16x16x32_bf16 v[2:5], v[138:141], v[150:153], v[2:5]
	v_mfma_f32_16x16x32_bf16 v[86:89], v[138:141], v[154:157], v[86:89]
	s_add_u32 s98, s98, 1
	s_and_b32 s98, s98, 15
	s_cmp_eq_u32 s98, 0
	s_cselect_b32 s99, 0x800, 0
	s_add_u32 s4, s4, 0x80
	s_addc_u32 s5, s5, 0
	s_sub_u32 s4, s4, s99
	s_subb_u32 s5, s5, 0
	s_add_u32 s6, s6, 0x80
	s_addc_u32 s7, s7, 0
	s_sub_u32 s6, s6, s99
	s_subb_u32 s7, s7, 0
	s_waitcnt lgkmcnt(0)
	v_mfma_f32_16x16x32_bf16 v[94:97], v[30:33], v[46:49], v[94:97]
	ds_read_b128 v[114:117], v111 offset:32
	v_mfma_f32_16x16x32_bf16 v[90:93], v[30:33], v[50:53], v[90:93]
	ds_read_b128 v[142:145], v159 offset:32
	v_mfma_f32_16x16x32_bf16 v[82:85], v[30:33], v[54:57], v[82:85]
	ds_read_b128 v[146:149], v159 offset:2080
	v_mfma_f32_16x16x32_bf16 v[78:81], v[30:33], v[62:65], v[78:81]
	ds_read_b128 v[118:121], v111 offset:2080
	v_mfma_f32_16x16x32_bf16 v[74:77], v[34:37], v[46:49], v[74:77]
	ds_read_b128 v[150:153], v159 offset:4128
	v_mfma_f32_16x16x32_bf16 v[70:73], v[34:37], v[50:53], v[70:73]
	ds_read_b128 v[154:157], v159 offset:6176
	v_mfma_f32_16x16x32_bf16 v[66:69], v[34:37], v[54:57], v[66:69]
	ds_read_b128 v[122:125], v111 offset:4128
	v_mfma_f32_16x16x32_bf16 v[58:61], v[34:37], v[62:65], v[58:61]
	ds_read_b128 v[138:141], v111 offset:6176
	v_mfma_f32_16x16x32_bf16 v[26:29], v[38:41], v[46:49], v[26:29]
	v_mfma_f32_16x16x32_bf16 v[22:25], v[38:41], v[50:53], v[22:25]
	v_mfma_f32_16x16x32_bf16 v[18:21], v[38:41], v[54:57], v[18:21]
	v_mfma_f32_16x16x32_bf16 v[14:17], v[38:41], v[62:65], v[14:17]
	v_mfma_f32_16x16x32_bf16 v[10:13], v[42:45], v[46:49], v[10:13]
	v_mfma_f32_16x16x32_bf16 v[6:9], v[42:45], v[50:53], v[6:9]
	v_mfma_f32_16x16x32_bf16 v[2:5], v[42:45], v[54:57], v[2:5]
	v_mfma_f32_16x16x32_bf16 v[86:89], v[42:45], v[62:65], v[86:89]
	s_waitcnt lgkmcnt(0)
	s_waitcnt vmcnt(0)
	s_barrier
	v_mfma_f32_16x16x32_bf16 v[94:97], v[114:117], v[142:145], v[94:97]
	ds_read_b128 v[30:33], v100 offset:32800
	v_mfma_f32_16x16x32_bf16 v[90:93], v[114:117], v[146:149], v[90:93]
	ds_read_b128 v[46:49], v158 offset:32800
	v_mfma_f32_16x16x32_bf16 v[82:85], v[114:117], v[150:153], v[82:85]
	ds_read_b128 v[50:53], v158 offset:34848
	v_mfma_f32_16x16x32_bf16 v[78:81], v[114:117], v[154:157], v[78:81]
	ds_read_b128 v[34:37], v100 offset:34848
	v_mfma_f32_16x16x32_bf16 v[74:77], v[118:121], v[142:145], v[74:77]
	ds_read_b128 v[54:57], v158 offset:36896
	v_mfma_f32_16x16x32_bf16 v[70:73], v[118:121], v[146:149], v[70:73]
	ds_read_b128 v[62:65], v158 offset:38944
	v_mfma_f32_16x16x32_bf16 v[66:69], v[118:121], v[150:153], v[66:69]
	ds_read_b128 v[38:41], v100 offset:36896
	v_mfma_f32_16x16x32_bf16 v[58:61], v[118:121], v[154:157], v[58:61]
	ds_read_b128 v[42:45], v100 offset:38944
	v_mfma_f32_16x16x32_bf16 v[26:29], v[122:125], v[142:145], v[26:29]
	v_mfma_f32_16x16x32_bf16 v[22:25], v[122:125], v[146:149], v[22:25]
	v_mfma_f32_16x16x32_bf16 v[18:21], v[122:125], v[150:153], v[18:21]
	v_mfma_f32_16x16x32_bf16 v[14:17], v[122:125], v[154:157], v[14:17]
	v_mfma_f32_16x16x32_bf16 v[10:13], v[138:141], v[142:145], v[10:13]
	v_mfma_f32_16x16x32_bf16 v[6:9], v[138:141], v[146:149], v[6:9]
	v_mfma_f32_16x16x32_bf16 v[2:5], v[138:141], v[150:153], v[2:5]
	v_mfma_f32_16x16x32_bf16 v[86:89], v[138:141], v[154:157], v[86:89]
	s_waitcnt lgkmcnt(0)
	v_mfma_f32_16x16x32_bf16 v[94:97], v[30:33], v[46:49], v[94:97]
	ds_read_b128 v[114:117], v111 offset:32800
	v_mfma_f32_16x16x32_bf16 v[90:93], v[30:33], v[50:53], v[90:93]
	ds_read_b128 v[142:145], v159 offset:32800
	v_mfma_f32_16x16x32_bf16 v[82:85], v[30:33], v[54:57], v[82:85]
	ds_read_b128 v[146:149], v159 offset:34848
	v_mfma_f32_16x16x32_bf16 v[78:81], v[30:33], v[62:65], v[78:81]
	ds_read_b128 v[118:121], v111 offset:34848
	v_mfma_f32_16x16x32_bf16 v[74:77], v[34:37], v[46:49], v[74:77]
	ds_read_b128 v[150:153], v159 offset:36896
	v_mfma_f32_16x16x32_bf16 v[70:73], v[34:37], v[50:53], v[70:73]
	ds_read_b128 v[154:157], v159 offset:38944
	v_mfma_f32_16x16x32_bf16 v[66:69], v[34:37], v[54:57], v[66:69]
	ds_read_b128 v[122:125], v111 offset:36896
	v_mfma_f32_16x16x32_bf16 v[58:61], v[34:37], v[62:65], v[58:61]
	ds_read_b128 v[138:141], v111 offset:38944
	v_mfma_f32_16x16x32_bf16 v[26:29], v[38:41], v[46:49], v[26:29]
	v_mfma_f32_16x16x32_bf16 v[22:25], v[38:41], v[50:53], v[22:25]
	v_mfma_f32_16x16x32_bf16 v[18:21], v[38:41], v[54:57], v[18:21]
	v_mfma_f32_16x16x32_bf16 v[14:17], v[38:41], v[62:65], v[14:17]
	v_mfma_f32_16x16x32_bf16 v[10:13], v[42:45], v[46:49], v[10:13]
	v_mfma_f32_16x16x32_bf16 v[6:9], v[42:45], v[50:53], v[6:9]
	v_mfma_f32_16x16x32_bf16 v[2:5], v[42:45], v[54:57], v[2:5]
	v_mfma_f32_16x16x32_bf16 v[86:89], v[42:45], v[62:65], v[86:89]
	s_waitcnt lgkmcnt(0)
	v_mfma_f32_16x16x32_bf16 v[94:97], v[114:117], v[142:145], v[94:97]
	v_mfma_f32_16x16x32_bf16 v[90:93], v[114:117], v[146:149], v[90:93]
	v_mfma_f32_16x16x32_bf16 v[82:85], v[114:117], v[150:153], v[82:85]
	v_mfma_f32_16x16x32_bf16 v[78:81], v[114:117], v[154:157], v[78:81]
	v_mfma_f32_16x16x32_bf16 v[74:77], v[118:121], v[142:145], v[74:77]
	v_mfma_f32_16x16x32_bf16 v[70:73], v[118:121], v[146:149], v[70:73]
	v_mfma_f32_16x16x32_bf16 v[66:69], v[118:121], v[150:153], v[66:69]
	v_mfma_f32_16x16x32_bf16 v[58:61], v[118:121], v[154:157], v[58:61]
	v_mfma_f32_16x16x32_bf16 v[26:29], v[122:125], v[142:145], v[26:29]
	v_mfma_f32_16x16x32_bf16 v[22:25], v[122:125], v[146:149], v[22:25]
	v_mfma_f32_16x16x32_bf16 v[18:21], v[122:125], v[150:153], v[18:21]
	v_mfma_f32_16x16x32_bf16 v[14:17], v[122:125], v[154:157], v[14:17]
	v_mfma_f32_16x16x32_bf16 v[10:13], v[138:141], v[142:145], v[10:13]
	v_mfma_f32_16x16x32_bf16 v[6:9], v[138:141], v[146:149], v[6:9]
	v_mfma_f32_16x16x32_bf16 v[2:5], v[138:141], v[150:153], v[2:5]
	v_mfma_f32_16x16x32_bf16 v[86:89], v[138:141], v[154:157], v[86:89]
	s_mul_i32 s4, s68, s62
	s_add_i32 s4, s4, s67
	s_and_b32 s4, s4, 0xff
	s_waitcnt vmcnt(7)
	v_lshl_or_b32 v30, s4, 10, v132
	s_mul_hi_u32 s4, s4, 0x15555556
	s_mulk_i32 s4, 0xd000
	v_add_u32_e32 v30, s4, v30
	s_lshl_b32 s36, s73, 8
	v_add_u32_e32 v138, 0x400, v129
	v_add_u32_e32 v139, 0x2000, v129
	v_add_u32_e32 v140, 0x2400, v129
	v_add_u32_e32 v141, 0x4000, v129
	v_add_u32_e32 v142, 0x4400, v129
	v_add_u32_e32 v143, 0x4800, v129
	v_add_u32_e32 v144, 0x6000, v129
	v_add_u32_e32 v145, 0x6400, v129
	v_add_u32_e32 v146, 0x6800, v129
	v_lshl_add_u64 v[114:115], v[102:103], 0, s[36:37]
	v_cmp_gt_u32_e32 vcc, s66, v30
	s_barrier
	ds_write2_b32 v129, v94, v90 offset1:16
	ds_write2_b32 v129, v95, v91 offset0:132 offset1:148
	ds_write2_b32 v138, v96, v92 offset0:8 offset1:24
	ds_write2_b32 v138, v97, v93 offset0:140 offset1:156
	ds_write2_b32 v129, v82, v78 offset0:32 offset1:48
	ds_write2_b32 v129, v83, v79 offset0:164 offset1:180
	ds_write2_b32 v138, v84, v80 offset0:40 offset1:56
	ds_write2_b32 v138, v85, v81 offset0:172 offset1:188
	ds_write2_b32 v139, v74, v70 offset0:64 offset1:80
	ds_write2_b32 v139, v75, v71 offset0:196 offset1:212
	ds_write2_b32 v140, v76, v72 offset0:72 offset1:88
	ds_write2_b32 v140, v77, v73 offset0:204 offset1:220
	ds_write2_b32 v139, v66, v58 offset0:96 offset1:112
	ds_write2_b32 v139, v67, v59 offset0:228 offset1:244
	ds_write2_b32 v140, v68, v60 offset0:104 offset1:120
	ds_write2_b32 v140, v69, v61 offset0:236 offset1:252
	ds_write2_b32 v141, v26, v22 offset0:128 offset1:144
	ds_write2_b32 v142, v27, v23 offset0:4 offset1:20
	ds_write2_b32 v142, v28, v24 offset0:136 offset1:152
	ds_write2_b32 v143, v29, v25 offset0:12 offset1:28
	ds_write2_b32 v141, v18, v14 offset0:160 offset1:176
	ds_write2_b32 v142, v19, v15 offset0:36 offset1:52
	ds_write2_b32 v142, v20, v16 offset0:168 offset1:184
	ds_write2_b32 v143, v21, v17 offset0:44 offset1:60
	ds_write2_b32 v144, v10, v6 offset0:192 offset1:208
	ds_write2_b32 v145, v11, v7 offset0:68 offset1:84
	ds_write2_b32 v145, v12, v8 offset0:200 offset1:216
	ds_write2_b32 v146, v13, v9 offset0:76 offset1:92
	ds_write2_b32 v144, v2, v86 offset0:224 offset1:240
	ds_write2_b32 v145, v3, v87 offset0:100 offset1:116
	ds_write2_b32 v145, v4, v88 offset0:232 offset1:248
	ds_write2_b32 v146, v5, v89 offset0:108 offset1:124
	s_waitcnt lgkmcnt(0)
	s_barrier
	s_and_saveexec_b64 s[4:5], vcc
	s_xor_b64 s[4:5], exec, s[4:5]
	s_cbranch_execz .LBB0_1297
	s_mov_b32 s6, s8
	s_mov_b32 s7, 1
	s_mov_b32 s9, 0
	s_mov_b32 s10, 8

.LBB0_1300:
	s_or_b64 exec, exec, s[50:51]
	s_lshl_b32 s4, s73, 7
	s_lshl_b32 s5, s71, 1
	s_add_u32 s6, s58, s5
	s_addc_u32 s7, s59, 0
	s_lshl_b32 s5, s72, 1
	v_mov_b32_e32 v111, v101
	s_add_u32 s8, s60, s5
	s_addc_u32 s9, s61, 0
	s_waitcnt lgkmcnt(0)
	s_barrier
	ds_read2_b32 v[26:27], v129 offset1:16
	ds_read2_b32 v[148:149], v129 offset0:132 offset1:148
	ds_read2_b32 v[28:29], v138 offset0:8 offset1:24
	ds_read2_b32 v[150:151], v138 offset0:140 offset1:156
	ds_read2_b32 v[22:23], v129 offset0:32 offset1:48
	ds_read2_b32 v[152:153], v129 offset0:164 offset1:180
	ds_read2_b32 v[24:25], v138 offset0:40 offset1:56
	ds_read2_b32 v[154:155], v138 offset0:172 offset1:188
	ds_read2_b32 v[18:19], v139 offset0:64 offset1:80
	ds_read2_b32 v[156:157], v139 offset0:196 offset1:212
	ds_read2_b32 v[20:21], v140 offset0:72 offset1:88
	ds_read2_b32 v[158:159], v140 offset0:204 offset1:220
	ds_read2_b32 v[14:15], v139 offset0:96 offset1:112
	ds_read2_b32 v[160:161], v139 offset0:228 offset1:244
	ds_read2_b32 v[16:17], v140 offset0:104 offset1:120
	ds_read2_b32 v[162:163], v140 offset0:236 offset1:252
	ds_read2_b32 v[10:11], v141 offset0:128 offset1:144
	ds_read2_b32 v[164:165], v142 offset0:4 offset1:20
	ds_read2_b32 v[12:13], v142 offset0:136 offset1:152
	ds_read2_b32 v[166:167], v143 offset0:12 offset1:28
	ds_read2_b32 v[6:7], v141 offset0:160 offset1:176
	ds_read2_b32 v[168:169], v142 offset0:36 offset1:52
	ds_read2_b32 v[8:9], v142 offset0:168 offset1:184
	ds_read2_b32 v[170:171], v143 offset0:44 offset1:60
	ds_read2_b32 v[2:3], v144 offset0:192 offset1:208
	ds_read2_b32 v[172:173], v145 offset0:68 offset1:84
	ds_read2_b32 v[4:5], v145 offset0:200 offset1:216
	ds_read2_b32 v[174:175], v146 offset0:76 offset1:92
	ds_read2_b32 v[30:31], v144 offset0:224 offset1:240
	ds_read2_b32 v[176:177], v145 offset0:100 offset1:116
	ds_read2_b32 v[32:33], v145 offset0:232 offset1:248
	ds_read2_b32 v[178:179], v146 offset0:108 offset1:124
	s_waitcnt lgkmcnt(0)
	s_barrier
	v_mov_b32_e32 v94, v31
	v_mov_b32_e32 v95, v177
	v_mov_b32_e32 v96, v33
	v_mov_b32_e32 v97, v179
	v_mov_b32_e32 v31, v176
	v_mov_b32_e32 v33, v178
	v_mov_b32_e32 v66, v3
	v_mov_b32_e32 v67, v173
	v_mov_b32_e32 v68, v5
	v_mov_b32_e32 v69, v175
	v_mov_b32_e32 v3, v172
	v_mov_b32_e32 v5, v174
	v_mov_b32_e32 v70, v7
	v_mov_b32_e32 v71, v169
	v_mov_b32_e32 v72, v9
	v_mov_b32_e32 v73, v171
	v_mov_b32_e32 v7, v168
	v_mov_b32_e32 v9, v170
	v_mov_b32_e32 v74, v11
	v_mov_b32_e32 v75, v165
	v_mov_b32_e32 v76, v13
	v_mov_b32_e32 v77, v167
	v_mov_b32_e32 v11, v164
	v_mov_b32_e32 v13, v166
	v_mov_b32_e32 v78, v15
	v_mov_b32_e32 v79, v161
	v_mov_b32_e32 v80, v17
	v_mov_b32_e32 v81, v163
	v_mov_b32_e32 v15, v160
	v_mov_b32_e32 v17, v162
	v_mov_b32_e32 v82, v19
	v_mov_b32_e32 v83, v157
	v_mov_b32_e32 v84, v21
	v_mov_b32_e32 v85, v159
	v_mov_b32_e32 v19, v156
	v_mov_b32_e32 v21, v158
	v_mov_b32_e32 v86, v23
	v_mov_b32_e32 v87, v153
	v_mov_b32_e32 v88, v25
	v_mov_b32_e32 v89, v155
	v_mov_b32_e32 v23, v152
	v_mov_b32_e32 v25, v154
	v_mov_b32_e32 v90, v27
	v_mov_b32_e32 v91, v149
	v_mov_b32_e32 v92, v29
	v_mov_b32_e32 v93, v151
	v_mov_b32_e32 v27, v148
	v_mov_b32_e32 v29, v150
	s_waitcnt lgkmcnt(0)
	s_barrier
	v_and_b32_e32 v174, 15, v0
	v_bfe_u32 v175, v0, 4, 2
	v_and_b32_e32 v111, 7, v174
	v_xor_b32_e32 v175, v175, v111
	v_lshlrev_b32_e32 v175, 4, v175
	v_lshl_or_b32 v175, v174, 7, v175
	v_bfe_u32 v174, v0, 7, 1
	v_lshl_or_b32 v100, v174, 13, v175
	v_bfe_u32 v174, v0, 6, 1
	v_lshl_or_b32 v168, v174, 13, v175
	v_or_b32_e32 v168, 0x4000, v168
	v_xor_b32_e32 v111, 64, v100
	v_xor_b32_e32 v169, 64, v168
	v_bfe_u32 v174, v0, 3, 3
	v_and_b32_e32 v175, 7, v0
	v_xor_b32_e32 v175, v175, v174
	v_lshlrev_b32_e32 v175, 4, v175
	v_lshl_or_b32 v175, v174, 11, v175
	v_lshrrev_b32_e32 v174, 6, v0
	v_and_b32_e32 v174, 3, v174
	v_lshl_or_b32 v170, v174, 16, v175
	v_add_u32_e32 v171, 0x3c00, v170
	v_add_u32_e32 v172, 0x7800, v170
	v_add_u32_e32 v173, 0xb400, v170
	v_lshlrev_b32_e32 v174, 12, v174
	s_nop 0
	v_readfirstlane_b32 s36, v174
	s_add_u32 s36, s36, 32
	v_mov_b32_e32 v116, 0
	v_mov_b32_e32 v117, 0
	v_mov_b32_e32 v118, 0
	v_mov_b32_e32 v119, 0
	v_mov_b32_e32 v120, 0
	v_mov_b32_e32 v121, 0
	v_mov_b32_e32 v122, 0
	v_mov_b32_e32 v123, 0
	v_mov_b32_e32 v124, 0
	v_mov_b32_e32 v125, 0
	v_mov_b32_e32 v126, 0
	v_mov_b32_e32 v127, 0
	v_mov_b32_e32 v148, 0
	v_mov_b32_e32 v149, 0
	v_mov_b32_e32 v150, 0
	v_mov_b32_e32 v151, 0
	v_mov_b32_e32 v152, 0
	v_mov_b32_e32 v153, 0
	v_mov_b32_e32 v154, 0
	v_mov_b32_e32 v155, 0
	v_mov_b32_e32 v156, 0
	v_mov_b32_e32 v157, 0
	v_mov_b32_e32 v158, 0
	v_mov_b32_e32 v159, 0
	v_mov_b32_e32 v160, 0
	v_mov_b32_e32 v161, 0
	v_mov_b32_e32 v162, 0
	v_mov_b32_e32 v163, 0
	v_mov_b32_e32 v164, 0
	v_mov_b32_e32 v165, 0
	v_mov_b32_e32 v166, 0
	v_mov_b32_e32 v167, 0
	s_waitcnt lgkmcnt(0)
	s_barrier
	v_readlane_b32 s98, v255, 16
	s_lshr_b32 s98, s98, 3
	s_and_b32 s98, s98, 3
	s_lshl_b32 s98, s98, 2
	s_lshl_b32 s99, s98, 7
	s_add_u32 s6, s6, s99
	s_addc_u32 s7, s7, 0
	s_add_u32 s8, s8, s99
	s_addc_u32 s9, s9, 0
	s_add_u32 m0, s36, 0
	s_nop 0
	global_load_lds_dwordx4 v170, s[6:7] offset:0
	global_load_lds_dwordx4 v171, s[6:7] offset:1024
	global_load_lds_dwordx4 v172, s[6:7] offset:2048
	global_load_lds_dwordx4 v173, s[6:7] offset:3072
	s_add_u32 m0, s36, 16384
	s_nop 0
	global_load_lds_dwordx4 v170, s[8:9] offset:0
	global_load_lds_dwordx4 v171, s[8:9] offset:1024
	global_load_lds_dwordx4 v172, s[8:9] offset:2048
	global_load_lds_dwordx4 v173, s[8:9] offset:3072
	s_add_u32 s98, s98, 1
	s_and_b32 s98, s98, 15
	s_cmp_eq_u32 s98, 0
	s_cselect_b32 s99, 0x800, 0
	s_add_u32 s6, s6, 0x80
	s_addc_u32 s7, s7, 0
	s_sub_u32 s6, s6, s99
	s_subb_u32 s7, s7, 0
	s_add_u32 s8, s8, 0x80
	s_addc_u32 s9, s9, 0
	s_sub_u32 s8, s8, s99
	s_subb_u32 s9, s9, 0
	s_mov_b32 s5, 0
	s_waitcnt vmcnt(0)
.Lk_aol1b_loop:
	s_barrier
	s_add_u32 m0, s36, 32768
	v_mfma_f32_16x16x32_bf16 v[26:29], v[116:119], v[152:155], v[26:29]
	ds_read_b128 v[34:37], v100 offset:32
	global_load_lds_dwordx4 v170, s[6:7] offset:0
	v_mfma_f32_16x16x32_bf16 v[90:93], v[116:119], v[156:159], v[90:93]
	ds_read_b128 v[50:53], v168 offset:32
	global_load_lds_dwordx4 v171, s[6:7] offset:1024
	v_mfma_f32_16x16x32_bf16 v[22:25], v[116:119], v[160:163], v[22:25]
	ds_read_b128 v[54:57], v168 offset:2080
	global_load_lds_dwordx4 v172, s[6:7] offset:2048
	v_mfma_f32_16x16x32_bf16 v[86:89], v[116:119], v[164:167], v[86:89]
	ds_read_b128 v[38:41], v100 offset:2080
	global_load_lds_dwordx4 v173, s[6:7] offset:3072
	s_add_u32 m0, s36, 49152
	v_mfma_f32_16x16x32_bf16 v[18:21], v[120:123], v[152:155], v[18:21]
	ds_read_b128 v[58:61], v168 offset:4128
	global_load_lds_dwordx4 v170, s[8:9] offset:0
	v_mfma_f32_16x16x32_bf16 v[82:85], v[120:123], v[156:159], v[82:85]
	ds_read_b128 v[62:65], v168 offset:6176
	global_load_lds_dwordx4 v171, s[8:9] offset:1024
	v_mfma_f32_16x16x32_bf16 v[14:17], v[120:123], v[160:163], v[14:17]
	ds_read_b128 v[42:45], v100 offset:4128
	global_load_lds_dwordx4 v172, s[8:9] offset:2048
	v_mfma_f32_16x16x32_bf16 v[78:81], v[120:123], v[164:167], v[78:81]
	ds_read_b128 v[46:49], v100 offset:6176
	global_load_lds_dwordx4 v173, s[8:9] offset:3072
	v_mfma_f32_16x16x32_bf16 v[10:13], v[124:127], v[152:155], v[10:13]
	v_mfma_f32_16x16x32_bf16 v[74:77], v[124:127], v[156:159], v[74:77]
	v_mfma_f32_16x16x32_bf16 v[6:9], v[124:127], v[160:163], v[6:9]
	v_mfma_f32_16x16x32_bf16 v[70:73], v[124:127], v[164:167], v[70:73]
	v_mfma_f32_16x16x32_bf16 v[2:5], v[148:151], v[152:155], v[2:5]
	v_mfma_f32_16x16x32_bf16 v[66:69], v[148:151], v[156:159], v[66:69]
	v_mfma_f32_16x16x32_bf16 v[30:33], v[148:151], v[160:163], v[30:33]
	v_mfma_f32_16x16x32_bf16 v[94:97], v[148:151], v[164:167], v[94:97]
	s_add_u32 s98, s98, 1
	s_and_b32 s98, s98, 15
	s_cmp_eq_u32 s98, 0
	s_cselect_b32 s99, 0x800, 0
	s_add_u32 s6, s6, 0x80
	s_addc_u32 s7, s7, 0
	s_sub_u32 s6, s6, s99
	s_subb_u32 s7, s7, 0
	s_add_u32 s8, s8, 0x80
	s_addc_u32 s9, s9, 0
	s_sub_u32 s8, s8, s99
	s_subb_u32 s9, s9, 0
	s_waitcnt lgkmcnt(0)
	v_mfma_f32_16x16x32_bf16 v[26:29], v[34:37], v[50:53], v[26:29]
	ds_read_b128 v[116:119], v111 offset:32
	v_mfma_f32_16x16x32_bf16 v[90:93], v[34:37], v[54:57], v[90:93]
	ds_read_b128 v[152:155], v169 offset:32
	v_mfma_f32_16x16x32_bf16 v[22:25], v[34:37], v[58:61], v[22:25]
	ds_read_b128 v[156:159], v169 offset:2080
	v_mfma_f32_16x16x32_bf16 v[86:89], v[34:37], v[62:65], v[86:89]
	ds_read_b128 v[120:123], v111 offset:2080
	v_mfma_f32_16x16x32_bf16 v[18:21], v[38:41], v[50:53], v[18:21]
	ds_read_b128 v[160:163], v169 offset:4128
	v_mfma_f32_16x16x32_bf16 v[82:85], v[38:41], v[54:57], v[82:85]
	ds_read_b128 v[164:167], v169 offset:6176
	v_mfma_f32_16x16x32_bf16 v[14:17], v[38:41], v[58:61], v[14:17]
	ds_read_b128 v[124:127], v111 offset:4128
	v_mfma_f32_16x16x32_bf16 v[78:81], v[38:41], v[62:65], v[78:81]
	ds_read_b128 v[148:151], v111 offset:6176
	v_mfma_f32_16x16x32_bf16 v[10:13], v[42:45], v[50:53], v[10:13]
	v_mfma_f32_16x16x32_bf16 v[74:77], v[42:45], v[54:57], v[74:77]
	v_mfma_f32_16x16x32_bf16 v[6:9], v[42:45], v[58:61], v[6:9]
	v_mfma_f32_16x16x32_bf16 v[70:73], v[42:45], v[62:65], v[70:73]
	v_mfma_f32_16x16x32_bf16 v[2:5], v[46:49], v[50:53], v[2:5]
	v_mfma_f32_16x16x32_bf16 v[66:69], v[46:49], v[54:57], v[66:69]
	v_mfma_f32_16x16x32_bf16 v[30:33], v[46:49], v[58:61], v[30:33]
	v_mfma_f32_16x16x32_bf16 v[94:97], v[46:49], v[62:65], v[94:97]
	s_waitcnt lgkmcnt(0)
	s_waitcnt vmcnt(0)
	s_barrier
	s_add_u32 m0, s36, 0
	v_mfma_f32_16x16x32_bf16 v[26:29], v[116:119], v[152:155], v[26:29]
	ds_read_b128 v[34:37], v100 offset:32800
	global_load_lds_dwordx4 v170, s[6:7] offset:0
	v_mfma_f32_16x16x32_bf16 v[90:93], v[116:119], v[156:159], v[90:93]
	ds_read_b128 v[50:53], v168 offset:32800
	global_load_lds_dwordx4 v171, s[6:7] offset:1024
	v_mfma_f32_16x16x32_bf16 v[22:25], v[116:119], v[160:163], v[22:25]
	ds_read_b128 v[54:57], v168 offset:34848
	global_load_lds_dwordx4 v172, s[6:7] offset:2048
	v_mfma_f32_16x16x32_bf16 v[86:89], v[116:119], v[164:167], v[86:89]
	ds_read_b128 v[38:41], v100 offset:34848
	global_load_lds_dwordx4 v173, s[6:7] offset:3072
	s_add_u32 m0, s36, 16384
	v_mfma_f32_16x16x32_bf16 v[18:21], v[120:123], v[152:155], v[18:21]
	ds_read_b128 v[58:61], v168 offset:36896
	global_load_lds_dwordx4 v170, s[8:9] offset:0
	v_mfma_f32_16x16x32_bf16 v[82:85], v[120:123], v[156:159], v[82:85]
	ds_read_b128 v[62:65], v168 offset:38944
	global_load_lds_dwordx4 v171, s[8:9] offset:1024
	v_mfma_f32_16x16x32_bf16 v[14:17], v[120:123], v[160:163], v[14:17]
	ds_read_b128 v[42:45], v100 offset:36896
	global_load_lds_dwordx4 v172, s[8:9] offset:2048
	v_mfma_f32_16x16x32_bf16 v[78:81], v[120:123], v[164:167], v[78:81]
	ds_read_b128 v[46:49], v100 offset:38944
	global_load_lds_dwordx4 v173, s[8:9] offset:3072
	v_mfma_f32_16x16x32_bf16 v[10:13], v[124:127], v[152:155], v[10:13]
	v_mfma_f32_16x16x32_bf16 v[74:77], v[124:127], v[156:159], v[74:77]
	v_mfma_f32_16x16x32_bf16 v[6:9], v[124:127], v[160:163], v[6:9]
	v_mfma_f32_16x16x32_bf16 v[70:73], v[124:127], v[164:167], v[70:73]
	v_mfma_f32_16x16x32_bf16 v[2:5], v[148:151], v[152:155], v[2:5]
	v_mfma_f32_16x16x32_bf16 v[66:69], v[148:151], v[156:159], v[66:69]
	v_mfma_f32_16x16x32_bf16 v[30:33], v[148:151], v[160:163], v[30:33]
	v_mfma_f32_16x16x32_bf16 v[94:97], v[148:151], v[164:167], v[94:97]
	s_add_u32 s98, s98, 1
	s_and_b32 s98, s98, 15
	s_cmp_eq_u32 s98, 0
	s_cselect_b32 s99, 0x800, 0
	s_add_u32 s6, s6, 0x80
	s_addc_u32 s7, s7, 0
	s_sub_u32 s6, s6, s99
	s_subb_u32 s7, s7, 0
	s_add_u32 s8, s8, 0x80
	s_addc_u32 s9, s9, 0
	s_sub_u32 s8, s8, s99
	s_subb_u32 s9, s9, 0
	s_waitcnt lgkmcnt(0)
	v_mfma_f32_16x16x32_bf16 v[26:29], v[34:37], v[50:53], v[26:29]
	ds_read_b128 v[116:119], v111 offset:32800
	v_mfma_f32_16x16x32_bf16 v[90:93], v[34:37], v[54:57], v[90:93]
	ds_read_b128 v[152:155], v169 offset:32800
	v_mfma_f32_16x16x32_bf16 v[22:25], v[34:37], v[58:61], v[22:25]
	ds_read_b128 v[156:159], v169 offset:34848
	v_mfma_f32_16x16x32_bf16 v[86:89], v[34:37], v[62:65], v[86:89]
	ds_read_b128 v[120:123], v111 offset:34848
	v_mfma_f32_16x16x32_bf16 v[18:21], v[38:41], v[50:53], v[18:21]
	ds_read_b128 v[160:163], v169 offset:36896
	v_mfma_f32_16x16x32_bf16 v[82:85], v[38:41], v[54:57], v[82:85]
	ds_read_b128 v[164:167], v169 offset:38944
	v_mfma_f32_16x16x32_bf16 v[14:17], v[38:41], v[58:61], v[14:17]
	ds_read_b128 v[124:127], v111 offset:36896
	v_mfma_f32_16x16x32_bf16 v[78:81], v[38:41], v[62:65], v[78:81]
	ds_read_b128 v[148:151], v111 offset:38944
	v_mfma_f32_16x16x32_bf16 v[10:13], v[42:45], v[50:53], v[10:13]
	v_mfma_f32_16x16x32_bf16 v[74:77], v[42:45], v[54:57], v[74:77]
	v_mfma_f32_16x16x32_bf16 v[6:9], v[42:45], v[58:61], v[6:9]
	v_mfma_f32_16x16x32_bf16 v[70:73], v[42:45], v[62:65], v[70:73]
	v_mfma_f32_16x16x32_bf16 v[2:5], v[46:49], v[50:53], v[2:5]
	v_mfma_f32_16x16x32_bf16 v[66:69], v[46:49], v[54:57], v[66:69]
	v_mfma_f32_16x16x32_bf16 v[30:33], v[46:49], v[58:61], v[30:33]
	v_mfma_f32_16x16x32_bf16 v[94:97], v[46:49], v[62:65], v[94:97]
	s_waitcnt lgkmcnt(0)
	s_waitcnt vmcnt(0)
	s_add_u32 s5, s5, 1
	s_cmp_lt_u32 s5, 7
	s_cbranch_scc1 .Lk_aol1b_loop
	s_barrier
	s_add_u32 m0, s36, 32768
	v_mfma_f32_16x16x32_bf16 v[26:29], v[116:119], v[152:155], v[26:29]
	ds_read_b128 v[34:37], v100 offset:32
	global_load_lds_dwordx4 v170, s[6:7] offset:0
	v_mfma_f32_16x16x32_bf16 v[90:93], v[116:119], v[156:159], v[90:93]
	ds_read_b128 v[50:53], v168 offset:32
	global_load_lds_dwordx4 v171, s[6:7] offset:1024
	v_mfma_f32_16x16x32_bf16 v[22:25], v[116:119], v[160:163], v[22:25]
	ds_read_b128 v[54:57], v168 offset:2080
	global_load_lds_dwordx4 v172, s[6:7] offset:2048
	v_mfma_f32_16x16x32_bf16 v[86:89], v[116:119], v[164:167], v[86:89]
	ds_read_b128 v[38:41], v100 offset:2080
	global_load_lds_dwordx4 v173, s[6:7] offset:3072
	s_add_u32 m0, s36, 49152
	v_mfma_f32_16x16x32_bf16 v[18:21], v[120:123], v[152:155], v[18:21]
	ds_read_b128 v[58:61], v168 offset:4128
	global_load_lds_dwordx4 v170, s[8:9] offset:0
	v_mfma_f32_16x16x32_bf16 v[82:85], v[120:123], v[156:159], v[82:85]
	ds_read_b128 v[62:65], v168 offset:6176
	global_load_lds_dwordx4 v171, s[8:9] offset:1024
	v_mfma_f32_16x16x32_bf16 v[14:17], v[120:123], v[160:163], v[14:17]
	ds_read_b128 v[42:45], v100 offset:4128
	global_load_lds_dwordx4 v172, s[8:9] offset:2048
	v_mfma_f32_16x16x32_bf16 v[78:81], v[120:123], v[164:167], v[78:81]
	ds_read_b128 v[46:49], v100 offset:6176
	global_load_lds_dwordx4 v173, s[8:9] offset:3072
	v_mfma_f32_16x16x32_bf16 v[10:13], v[124:127], v[152:155], v[10:13]
	v_mfma_f32_16x16x32_bf16 v[74:77], v[124:127], v[156:159], v[74:77]
	v_mfma_f32_16x16x32_bf16 v[6:9], v[124:127], v[160:163], v[6:9]
	v_mfma_f32_16x16x32_bf16 v[70:73], v[124:127], v[164:167], v[70:73]
	v_mfma_f32_16x16x32_bf16 v[2:5], v[148:151], v[152:155], v[2:5]
	v_mfma_f32_16x16x32_bf16 v[66:69], v[148:151], v[156:159], v[66:69]
	v_mfma_f32_16x16x32_bf16 v[30:33], v[148:151], v[160:163], v[30:33]
	v_mfma_f32_16x16x32_bf16 v[94:97], v[148:151], v[164:167], v[94:97]
	s_add_u32 s98, s98, 1
	s_and_b32 s98, s98, 15
	s_cmp_eq_u32 s98, 0
	s_cselect_b32 s99, 0x800, 0
	s_add_u32 s6, s6, 0x80
	s_addc_u32 s7, s7, 0
	s_sub_u32 s6, s6, s99
	s_subb_u32 s7, s7, 0
	s_add_u32 s8, s8, 0x80
	s_addc_u32 s9, s9, 0
	s_sub_u32 s8, s8, s99
	s_subb_u32 s9, s9, 0
	s_waitcnt lgkmcnt(0)
	v_mfma_f32_16x16x32_bf16 v[26:29], v[34:37], v[50:53], v[26:29]
	ds_read_b128 v[116:119], v111 offset:32
	v_mfma_f32_16x16x32_bf16 v[90:93], v[34:37], v[54:57], v[90:93]
	ds_read_b128 v[152:155], v169 offset:32
	v_mfma_f32_16x16x32_bf16 v[22:25], v[34:37], v[58:61], v[22:25]
	ds_read_b128 v[156:159], v169 offset:2080
	v_mfma_f32_16x16x32_bf16 v[86:89], v[34:37], v[62:65], v[86:89]
	ds_read_b128 v[120:123], v111 offset:2080
	v_mfma_f32_16x16x32_bf16 v[18:21], v[38:41], v[50:53], v[18:21]
	ds_read_b128 v[160:163], v169 offset:4128
	v_mfma_f32_16x16x32_bf16 v[82:85], v[38:41], v[54:57], v[82:85]
	ds_read_b128 v[164:167], v169 offset:6176
	v_mfma_f32_16x16x32_bf16 v[14:17], v[38:41], v[58:61], v[14:17]
	ds_read_b128 v[124:127], v111 offset:4128
	v_mfma_f32_16x16x32_bf16 v[78:81], v[38:41], v[62:65], v[78:81]
	ds_read_b128 v[148:151], v111 offset:6176
	v_mfma_f32_16x16x32_bf16 v[10:13], v[42:45], v[50:53], v[10:13]
	v_mfma_f32_16x16x32_bf16 v[74:77], v[42:45], v[54:57], v[74:77]
	v_mfma_f32_16x16x32_bf16 v[6:9], v[42:45], v[58:61], v[6:9]
	v_mfma_f32_16x16x32_bf16 v[70:73], v[42:45], v[62:65], v[70:73]
	v_mfma_f32_16x16x32_bf16 v[2:5], v[46:49], v[50:53], v[2:5]
	v_mfma_f32_16x16x32_bf16 v[66:69], v[46:49], v[54:57], v[66:69]
	v_mfma_f32_16x16x32_bf16 v[30:33], v[46:49], v[58:61], v[30:33]
	v_mfma_f32_16x16x32_bf16 v[94:97], v[46:49], v[62:65], v[94:97]
	s_waitcnt lgkmcnt(0)
	s_waitcnt vmcnt(0)
	s_barrier
	v_mfma_f32_16x16x32_bf16 v[26:29], v[116:119], v[152:155], v[26:29]
	ds_read_b128 v[34:37], v100 offset:32800
	v_mfma_f32_16x16x32_bf16 v[90:93], v[116:119], v[156:159], v[90:93]
	ds_read_b128 v[50:53], v168 offset:32800
	v_mfma_f32_16x16x32_bf16 v[22:25], v[116:119], v[160:163], v[22:25]
	ds_read_b128 v[54:57], v168 offset:34848
	v_mfma_f32_16x16x32_bf16 v[86:89], v[116:119], v[164:167], v[86:89]
	ds_read_b128 v[38:41], v100 offset:34848
	v_mfma_f32_16x16x32_bf16 v[18:21], v[120:123], v[152:155], v[18:21]
	ds_read_b128 v[58:61], v168 offset:36896
	v_mfma_f32_16x16x32_bf16 v[82:85], v[120:123], v[156:159], v[82:85]
	ds_read_b128 v[62:65], v168 offset:38944
	v_mfma_f32_16x16x32_bf16 v[14:17], v[120:123], v[160:163], v[14:17]
	ds_read_b128 v[42:45], v100 offset:36896
	v_mfma_f32_16x16x32_bf16 v[78:81], v[120:123], v[164:167], v[78:81]
	ds_read_b128 v[46:49], v100 offset:38944
	v_mfma_f32_16x16x32_bf16 v[10:13], v[124:127], v[152:155], v[10:13]
	v_mfma_f32_16x16x32_bf16 v[74:77], v[124:127], v[156:159], v[74:77]
	v_mfma_f32_16x16x32_bf16 v[6:9], v[124:127], v[160:163], v[6:9]
	v_mfma_f32_16x16x32_bf16 v[70:73], v[124:127], v[164:167], v[70:73]
	v_mfma_f32_16x16x32_bf16 v[2:5], v[148:151], v[152:155], v[2:5]
	v_mfma_f32_16x16x32_bf16 v[66:69], v[148:151], v[156:159], v[66:69]
	v_mfma_f32_16x16x32_bf16 v[30:33], v[148:151], v[160:163], v[30:33]
	v_mfma_f32_16x16x32_bf16 v[94:97], v[148:151], v[164:167], v[94:97]
	s_waitcnt lgkmcnt(0)
	v_mfma_f32_16x16x32_bf16 v[26:29], v[34:37], v[50:53], v[26:29]
	ds_read_b128 v[116:119], v111 offset:32800
	v_mfma_f32_16x16x32_bf16 v[90:93], v[34:37], v[54:57], v[90:93]
	ds_read_b128 v[152:155], v169 offset:32800
	v_mfma_f32_16x16x32_bf16 v[22:25], v[34:37], v[58:61], v[22:25]
	ds_read_b128 v[156:159], v169 offset:34848
	v_mfma_f32_16x16x32_bf16 v[86:89], v[34:37], v[62:65], v[86:89]
	ds_read_b128 v[120:123], v111 offset:34848
	v_mfma_f32_16x16x32_bf16 v[18:21], v[38:41], v[50:53], v[18:21]
	ds_read_b128 v[160:163], v169 offset:36896
	v_mfma_f32_16x16x32_bf16 v[82:85], v[38:41], v[54:57], v[82:85]
	ds_read_b128 v[164:167], v169 offset:38944
	v_mfma_f32_16x16x32_bf16 v[14:17], v[38:41], v[58:61], v[14:17]
	ds_read_b128 v[124:127], v111 offset:36896
	v_mfma_f32_16x16x32_bf16 v[78:81], v[38:41], v[62:65], v[78:81]
	ds_read_b128 v[148:151], v111 offset:38944
	v_mfma_f32_16x16x32_bf16 v[10:13], v[42:45], v[50:53], v[10:13]
	v_mfma_f32_16x16x32_bf16 v[74:77], v[42:45], v[54:57], v[74:77]
	v_mfma_f32_16x16x32_bf16 v[6:9], v[42:45], v[58:61], v[6:9]
	v_mfma_f32_16x16x32_bf16 v[70:73], v[42:45], v[62:65], v[70:73]
	v_mfma_f32_16x16x32_bf16 v[2:5], v[46:49], v[50:53], v[2:5]
	v_mfma_f32_16x16x32_bf16 v[66:69], v[46:49], v[54:57], v[66:69]
	v_mfma_f32_16x16x32_bf16 v[30:33], v[46:49], v[58:61], v[30:33]
	v_mfma_f32_16x16x32_bf16 v[94:97], v[46:49], v[62:65], v[94:97]
	s_waitcnt lgkmcnt(0)
	v_mfma_f32_16x16x32_bf16 v[26:29], v[116:119], v[152:155], v[26:29]
	v_mfma_f32_16x16x32_bf16 v[90:93], v[116:119], v[156:159], v[90:93]
	v_mfma_f32_16x16x32_bf16 v[22:25], v[116:119], v[160:163], v[22:25]
	v_mfma_f32_16x16x32_bf16 v[86:89], v[116:119], v[164:167], v[86:89]
	v_mfma_f32_16x16x32_bf16 v[18:21], v[120:123], v[152:155], v[18:21]
	v_mfma_f32_16x16x32_bf16 v[82:85], v[120:123], v[156:159], v[82:85]
	v_mfma_f32_16x16x32_bf16 v[14:17], v[120:123], v[160:163], v[14:17]
	v_mfma_f32_16x16x32_bf16 v[78:81], v[120:123], v[164:167], v[78:81]
	v_mfma_f32_16x16x32_bf16 v[10:13], v[124:127], v[152:155], v[10:13]
	v_mfma_f32_16x16x32_bf16 v[74:77], v[124:127], v[156:159], v[74:77]
	v_mfma_f32_16x16x32_bf16 v[6:9], v[124:127], v[160:163], v[6:9]
	v_mfma_f32_16x16x32_bf16 v[70:73], v[124:127], v[164:167], v[70:73]
	v_mfma_f32_16x16x32_bf16 v[2:5], v[148:151], v[152:155], v[2:5]
	v_mfma_f32_16x16x32_bf16 v[66:69], v[148:151], v[156:159], v[66:69]
	v_mfma_f32_16x16x32_bf16 v[30:33], v[148:151], v[160:163], v[30:33]
	v_mfma_f32_16x16x32_bf16 v[94:97], v[148:151], v[164:167], v[94:97]
	s_lshl_b32 s36, s4, 1
	s_lshl_b32 s4, s70, 10
	s_mul_hi_u32 s5, s70, 0x15555556
	s_barrier
	ds_write2_b32 v129, v26, v90 offset1:16
	ds_write2_b32 v129, v27, v91 offset0:132 offset1:148
	ds_write2_b32 v138, v28, v92 offset0:8 offset1:24
	ds_write2_b32 v138, v29, v93 offset0:140 offset1:156
	ds_write2_b32 v129, v22, v86 offset0:32 offset1:48
	ds_write2_b32 v129, v23, v87 offset0:164 offset1:180
	ds_write2_b32 v138, v24, v88 offset0:40 offset1:56
	ds_write2_b32 v138, v25, v89 offset0:172 offset1:188
	ds_write2_b32 v139, v18, v82 offset0:64 offset1:80
	ds_write2_b32 v139, v19, v83 offset0:196 offset1:212
	ds_write2_b32 v140, v20, v84 offset0:72 offset1:88
	ds_write2_b32 v140, v21, v85 offset0:204 offset1:220
	ds_write2_b32 v139, v14, v78 offset0:96 offset1:112
	ds_write2_b32 v139, v15, v79 offset0:228 offset1:244
	ds_write2_b32 v140, v16, v80 offset0:104 offset1:120
	ds_write2_b32 v140, v17, v81 offset0:236 offset1:252
	ds_write2_b32 v141, v10, v74 offset0:128 offset1:144
	ds_write2_b32 v142, v11, v75 offset0:4 offset1:20
	ds_write2_b32 v142, v12, v76 offset0:136 offset1:152
	ds_write2_b32 v143, v13, v77 offset0:12 offset1:28
	ds_write2_b32 v141, v6, v70 offset0:160 offset1:176
	ds_write2_b32 v142, v7, v71 offset0:36 offset1:52
	ds_write2_b32 v142, v8, v72 offset0:168 offset1:184
	ds_write2_b32 v143, v9, v73 offset0:44 offset1:60
	ds_write2_b32 v144, v2, v66 offset0:192 offset1:208
	ds_write2_b32 v145, v3, v67 offset0:68 offset1:84
	ds_write2_b32 v145, v4, v68 offset0:200 offset1:216
	ds_write2_b32 v146, v5, v69 offset0:76 offset1:92
	ds_write2_b32 v144, v30, v94 offset0:224 offset1:240
	ds_write2_b32 v145, v31, v95 offset0:100 offset1:116
	ds_write2_b32 v145, v32, v96 offset0:232 offset1:248
	ds_write2_b32 v146, v33, v97 offset0:108 offset1:124
	v_or_b32_e32 v4, s4, v134
	s_mulk_i32 s5, 0x3000
	v_or_b32_e32 v5, s4, v132
	v_lshl_add_u64 v[2:3], v[106:107], 0, s[36:37]
	v_subrev_u32_e32 v4, s5, v4
	v_subrev_u32_e32 v100, s5, v5
	s_mov_b32 s4, 0
	s_waitcnt lgkmcnt(0)
	s_barrier

.LBB0_1372:
	s_and_b32 s28, s11, 0xff
	s_mul_i32 s2, s28, 0xab
	s_lshr_b32 s29, s2, 11
	s_mul_i32 s2, s29, 12
	s_sub_i32 s2, s11, s2
	s_and_b32 s2, s2, 0xff
	s_lshl_b32 s2, s2, 21
	s_or_b32 s2, s2, s21
	s_add_u32 s14, s16, s2
	s_addc_u32 s15, s17, 0
	s_lshl_b32 s2, s29, 18
	s_add_u32 s12, s18, s2
	s_addc_u32 s13, s19, 0
	v_and_b32_e32 v162, 15, v0
	v_bfe_u32 v163, v0, 4, 2
	v_and_b32_e32 v107, 7, v162
	v_xor_b32_e32 v163, v163, v107
	v_lshlrev_b32_e32 v163, 4, v163
	v_lshl_or_b32 v163, v162, 7, v163
	v_bfe_u32 v162, v0, 7, 1
	v_lshl_or_b32 v98, v162, 13, v163
	v_bfe_u32 v162, v0, 6, 1
	v_lshl_or_b32 v156, v162, 13, v163
	v_or_b32_e32 v156, 0x4000, v156
	v_xor_b32_e32 v107, 64, v98
	v_xor_b32_e32 v157, 64, v156
	v_bfe_u32 v162, v0, 3, 3
	v_and_b32_e32 v163, 7, v0
	v_xor_b32_e32 v163, v163, v162
	v_lshlrev_b32_e32 v163, 4, v163
	v_lshl_or_b32 v163, v162, 11, v163
	v_lshrrev_b32_e32 v162, 6, v0
	v_and_b32_e32 v162, 3, v162
	v_lshl_or_b32 v158, v162, 16, v163
	v_add_u32_e32 v159, 0x3c00, v158
	v_add_u32_e32 v160, 0x7800, v158
	v_add_u32_e32 v161, 0xb400, v158
	v_lshlrev_b32_e32 v162, 12, v162
	s_nop 0
	v_readfirstlane_b32 s31, v162
	s_add_u32 s31, s31, 32
	v_mov_b32_e32 v94, 0
	v_mov_b32_e32 v95, 0
	v_mov_b32_e32 v96, 0
	v_mov_b32_e32 v97, 0
	v_mov_b32_e32 v90, 0
	v_mov_b32_e32 v91, 0
	v_mov_b32_e32 v92, 0
	v_mov_b32_e32 v93, 0
	v_mov_b32_e32 v82, 0
	v_mov_b32_e32 v83, 0
	v_mov_b32_e32 v84, 0
	v_mov_b32_e32 v85, 0
	v_mov_b32_e32 v78, 0
	v_mov_b32_e32 v79, 0
	v_mov_b32_e32 v80, 0
	v_mov_b32_e32 v81, 0
	v_mov_b32_e32 v74, 0
	v_mov_b32_e32 v75, 0
	v_mov_b32_e32 v76, 0
	v_mov_b32_e32 v77, 0
	v_mov_b32_e32 v70, 0
	v_mov_b32_e32 v71, 0
	v_mov_b32_e32 v72, 0
	v_mov_b32_e32 v73, 0
	v_mov_b32_e32 v66, 0
	v_mov_b32_e32 v67, 0
	v_mov_b32_e32 v68, 0
	v_mov_b32_e32 v69, 0
	v_mov_b32_e32 v62, 0
	v_mov_b32_e32 v63, 0
	v_mov_b32_e32 v64, 0
	v_mov_b32_e32 v65, 0
	v_mov_b32_e32 v58, 0
	v_mov_b32_e32 v59, 0
	v_mov_b32_e32 v60, 0
	v_mov_b32_e32 v61, 0
	v_mov_b32_e32 v42, 0
	v_mov_b32_e32 v43, 0
	v_mov_b32_e32 v44, 0
	v_mov_b32_e32 v45, 0
	v_mov_b32_e32 v22, 0
	v_mov_b32_e32 v23, 0
	v_mov_b32_e32 v24, 0
	v_mov_b32_e32 v25, 0
	v_mov_b32_e32 v14, 0
	v_mov_b32_e32 v15, 0
	v_mov_b32_e32 v16, 0
	v_mov_b32_e32 v17, 0
	v_mov_b32_e32 v10, 0
	v_mov_b32_e32 v11, 0
	v_mov_b32_e32 v12, 0
	v_mov_b32_e32 v13, 0
	v_mov_b32_e32 v6, 0
	v_mov_b32_e32 v7, 0
	v_mov_b32_e32 v8, 0
	v_mov_b32_e32 v9, 0
	v_mov_b32_e32 v2, 0
	v_mov_b32_e32 v3, 0
	v_mov_b32_e32 v4, 0
	v_mov_b32_e32 v5, 0
	v_mov_b32_e32 v86, 0
	v_mov_b32_e32 v87, 0
	v_mov_b32_e32 v88, 0
	v_mov_b32_e32 v89, 0
	v_mov_b32_e32 v108, 0
	v_mov_b32_e32 v109, 0
	v_mov_b32_e32 v110, 0
	v_mov_b32_e32 v111, 0
	v_mov_b32_e32 v112, 0
	v_mov_b32_e32 v113, 0
	v_mov_b32_e32 v114, 0
	v_mov_b32_e32 v115, 0
	v_mov_b32_e32 v116, 0
	v_mov_b32_e32 v117, 0
	v_mov_b32_e32 v118, 0
	v_mov_b32_e32 v119, 0
	v_mov_b32_e32 v136, 0
	v_mov_b32_e32 v137, 0
	v_mov_b32_e32 v138, 0
	v_mov_b32_e32 v139, 0
	v_mov_b32_e32 v140, 0
	v_mov_b32_e32 v141, 0
	v_mov_b32_e32 v142, 0
	v_mov_b32_e32 v143, 0
	v_mov_b32_e32 v144, 0
	v_mov_b32_e32 v145, 0
	v_mov_b32_e32 v146, 0
	v_mov_b32_e32 v147, 0
	v_mov_b32_e32 v148, 0
	v_mov_b32_e32 v149, 0
	v_mov_b32_e32 v150, 0
	v_mov_b32_e32 v151, 0
	v_mov_b32_e32 v152, 0
	v_mov_b32_e32 v153, 0
	v_mov_b32_e32 v154, 0
	v_mov_b32_e32 v155, 0
	s_waitcnt lgkmcnt(0)
	s_barrier
	v_readlane_b32 s98, v255, 16
	s_lshr_b32 s98, s98, 3
	s_and_b32 s98, s98, 3
	s_lshl_b32 s98, s98, 2
	s_lshl_b32 s99, s98, 7
	s_add_u32 s14, s14, s99
	s_addc_u32 s15, s15, 0
	s_add_u32 s12, s12, s99
	s_addc_u32 s13, s13, 0
	s_add_u32 m0, s31, 0
	s_nop 0
	global_load_lds_dwordx4 v158, s[14:15] offset:0
	global_load_lds_dwordx4 v159, s[14:15] offset:1024
	global_load_lds_dwordx4 v160, s[14:15] offset:2048
	global_load_lds_dwordx4 v161, s[14:15] offset:3072
	s_add_u32 m0, s31, 16384
	s_nop 0
	global_load_lds_dwordx4 v158, s[12:13] offset:0
	global_load_lds_dwordx4 v159, s[12:13] offset:1024
	global_load_lds_dwordx4 v160, s[12:13] offset:2048
	global_load_lds_dwordx4 v161, s[12:13] offset:3072
	s_add_u32 s98, s98, 1
	s_and_b32 s98, s98, 15
	s_cmp_eq_u32 s98, 0
	s_cselect_b32 s99, 0x800, 0
	s_add_u32 s14, s14, 0x80
	s_addc_u32 s15, s15, 0
	s_sub_u32 s14, s14, s99
	s_subb_u32 s15, s15, 0
	s_add_u32 s12, s12, 0x80
	s_addc_u32 s13, s13, 0
	s_sub_u32 s12, s12, s99
	s_subb_u32 s13, s13, 0
	s_mov_b32 s30, 0
	s_waitcnt vmcnt(0)
.Lk_outl1_loop:
	s_barrier
	s_add_u32 m0, s31, 32768
	v_mfma_f32_16x16x32_bf16 v[94:97], v[108:111], v[140:143], v[94:97]
	ds_read_b128 v[18:21], v98 offset:32
	global_load_lds_dwordx4 v158, s[14:15] offset:0
	v_mfma_f32_16x16x32_bf16 v[90:93], v[108:111], v[144:147], v[90:93]
	ds_read_b128 v[38:41], v156 offset:32
	global_load_lds_dwordx4 v159, s[14:15] offset:1024
	v_mfma_f32_16x16x32_bf16 v[82:85], v[108:111], v[148:151], v[82:85]
	ds_read_b128 v[46:49], v156 offset:2080
	global_load_lds_dwordx4 v160, s[14:15] offset:2048
	v_mfma_f32_16x16x32_bf16 v[78:81], v[108:111], v[152:155], v[78:81]
	ds_read_b128 v[26:29], v98 offset:2080
	global_load_lds_dwordx4 v161, s[14:15] offset:3072
	s_add_u32 m0, s31, 49152
	v_mfma_f32_16x16x32_bf16 v[74:77], v[112:115], v[140:143], v[74:77]
	ds_read_b128 v[50:53], v156 offset:4128
	global_load_lds_dwordx4 v158, s[12:13] offset:0
	v_mfma_f32_16x16x32_bf16 v[70:73], v[112:115], v[144:147], v[70:73]
	ds_read_b128 v[54:57], v156 offset:6176
	global_load_lds_dwordx4 v159, s[12:13] offset:1024
	v_mfma_f32_16x16x32_bf16 v[66:69], v[112:115], v[148:151], v[66:69]
	ds_read_b128 v[30:33], v98 offset:4128
	global_load_lds_dwordx4 v160, s[12:13] offset:2048
	v_mfma_f32_16x16x32_bf16 v[62:65], v[112:115], v[152:155], v[62:65]
	ds_read_b128 v[34:37], v98 offset:6176
	global_load_lds_dwordx4 v161, s[12:13] offset:3072
	v_mfma_f32_16x16x32_bf16 v[58:61], v[116:119], v[140:143], v[58:61]
	v_mfma_f32_16x16x32_bf16 v[42:45], v[116:119], v[144:147], v[42:45]
	v_mfma_f32_16x16x32_bf16 v[22:25], v[116:119], v[148:151], v[22:25]
	v_mfma_f32_16x16x32_bf16 v[14:17], v[116:119], v[152:155], v[14:17]
	v_mfma_f32_16x16x32_bf16 v[10:13], v[136:139], v[140:143], v[10:13]
	v_mfma_f32_16x16x32_bf16 v[6:9], v[136:139], v[144:147], v[6:9]
	v_mfma_f32_16x16x32_bf16 v[2:5], v[136:139], v[148:151], v[2:5]
	v_mfma_f32_16x16x32_bf16 v[86:89], v[136:139], v[152:155], v[86:89]
	s_add_u32 s98, s98, 1
	s_and_b32 s98, s98, 15
	s_cmp_eq_u32 s98, 0
	s_cselect_b32 s99, 0x800, 0
	s_add_u32 s14, s14, 0x80
	s_addc_u32 s15, s15, 0
	s_sub_u32 s14, s14, s99
	s_subb_u32 s15, s15, 0
	s_add_u32 s12, s12, 0x80
	s_addc_u32 s13, s13, 0
	s_sub_u32 s12, s12, s99
	s_subb_u32 s13, s13, 0
	s_waitcnt lgkmcnt(0)
	v_mfma_f32_16x16x32_bf16 v[94:97], v[18:21], v[38:41], v[94:97]
	ds_read_b128 v[108:111], v107 offset:32
	v_mfma_f32_16x16x32_bf16 v[90:93], v[18:21], v[46:49], v[90:93]
	ds_read_b128 v[140:143], v157 offset:32
	v_mfma_f32_16x16x32_bf16 v[82:85], v[18:21], v[50:53], v[82:85]
	ds_read_b128 v[144:147], v157 offset:2080
	v_mfma_f32_16x16x32_bf16 v[78:81], v[18:21], v[54:57], v[78:81]
	ds_read_b128 v[112:115], v107 offset:2080
	v_mfma_f32_16x16x32_bf16 v[74:77], v[26:29], v[38:41], v[74:77]
	ds_read_b128 v[148:151], v157 offset:4128
	v_mfma_f32_16x16x32_bf16 v[70:73], v[26:29], v[46:49], v[70:73]
	ds_read_b128 v[152:155], v157 offset:6176
	v_mfma_f32_16x16x32_bf16 v[66:69], v[26:29], v[50:53], v[66:69]
	ds_read_b128 v[116:119], v107 offset:4128
	v_mfma_f32_16x16x32_bf16 v[62:65], v[26:29], v[54:57], v[62:65]
	ds_read_b128 v[136:139], v107 offset:6176
	v_mfma_f32_16x16x32_bf16 v[58:61], v[30:33], v[38:41], v[58:61]
	v_mfma_f32_16x16x32_bf16 v[42:45], v[30:33], v[46:49], v[42:45]
	v_mfma_f32_16x16x32_bf16 v[22:25], v[30:33], v[50:53], v[22:25]
	v_mfma_f32_16x16x32_bf16 v[14:17], v[30:33], v[54:57], v[14:17]
	v_mfma_f32_16x16x32_bf16 v[10:13], v[34:37], v[38:41], v[10:13]
	v_mfma_f32_16x16x32_bf16 v[6:9], v[34:37], v[46:49], v[6:9]
	v_mfma_f32_16x16x32_bf16 v[2:5], v[34:37], v[50:53], v[2:5]
	v_mfma_f32_16x16x32_bf16 v[86:89], v[34:37], v[54:57], v[86:89]
	s_waitcnt lgkmcnt(0)
	s_waitcnt vmcnt(0)
	s_barrier
	s_add_u32 m0, s31, 0
	v_mfma_f32_16x16x32_bf16 v[94:97], v[108:111], v[140:143], v[94:97]
	ds_read_b128 v[18:21], v98 offset:32800
	global_load_lds_dwordx4 v158, s[14:15] offset:0
	v_mfma_f32_16x16x32_bf16 v[90:93], v[108:111], v[144:147], v[90:93]
	ds_read_b128 v[38:41], v156 offset:32800
	global_load_lds_dwordx4 v159, s[14:15] offset:1024
	v_mfma_f32_16x16x32_bf16 v[82:85], v[108:111], v[148:151], v[82:85]
	ds_read_b128 v[46:49], v156 offset:34848
	global_load_lds_dwordx4 v160, s[14:15] offset:2048
	v_mfma_f32_16x16x32_bf16 v[78:81], v[108:111], v[152:155], v[78:81]
	ds_read_b128 v[26:29], v98 offset:34848
	global_load_lds_dwordx4 v161, s[14:15] offset:3072
	s_add_u32 m0, s31, 16384
	v_mfma_f32_16x16x32_bf16 v[74:77], v[112:115], v[140:143], v[74:77]
	ds_read_b128 v[50:53], v156 offset:36896
	global_load_lds_dwordx4 v158, s[12:13] offset:0
	v_mfma_f32_16x16x32_bf16 v[70:73], v[112:115], v[144:147], v[70:73]
	ds_read_b128 v[54:57], v156 offset:38944
	global_load_lds_dwordx4 v159, s[12:13] offset:1024
	v_mfma_f32_16x16x32_bf16 v[66:69], v[112:115], v[148:151], v[66:69]
	ds_read_b128 v[30:33], v98 offset:36896
	global_load_lds_dwordx4 v160, s[12:13] offset:2048
	v_mfma_f32_16x16x32_bf16 v[62:65], v[112:115], v[152:155], v[62:65]
	ds_read_b128 v[34:37], v98 offset:38944
	global_load_lds_dwordx4 v161, s[12:13] offset:3072
	v_mfma_f32_16x16x32_bf16 v[58:61], v[116:119], v[140:143], v[58:61]
	v_mfma_f32_16x16x32_bf16 v[42:45], v[116:119], v[144:147], v[42:45]
	v_mfma_f32_16x16x32_bf16 v[22:25], v[116:119], v[148:151], v[22:25]
	v_mfma_f32_16x16x32_bf16 v[14:17], v[116:119], v[152:155], v[14:17]
	v_mfma_f32_16x16x32_bf16 v[10:13], v[136:139], v[140:143], v[10:13]
	v_mfma_f32_16x16x32_bf16 v[6:9], v[136:139], v[144:147], v[6:9]
	v_mfma_f32_16x16x32_bf16 v[2:5], v[136:139], v[148:151], v[2:5]
	v_mfma_f32_16x16x32_bf16 v[86:89], v[136:139], v[152:155], v[86:89]
	s_add_u32 s98, s98, 1
	s_and_b32 s98, s98, 15
	s_cmp_eq_u32 s98, 0
	s_cselect_b32 s99, 0x800, 0
	s_add_u32 s14, s14, 0x80
	s_addc_u32 s15, s15, 0
	s_sub_u32 s14, s14, s99
	s_subb_u32 s15, s15, 0
	s_add_u32 s12, s12, 0x80
	s_addc_u32 s13, s13, 0
	s_sub_u32 s12, s12, s99
	s_subb_u32 s13, s13, 0
	s_waitcnt lgkmcnt(0)
	v_mfma_f32_16x16x32_bf16 v[94:97], v[18:21], v[38:41], v[94:97]
	ds_read_b128 v[108:111], v107 offset:32800
	v_mfma_f32_16x16x32_bf16 v[90:93], v[18:21], v[46:49], v[90:93]
	ds_read_b128 v[140:143], v157 offset:32800
	v_mfma_f32_16x16x32_bf16 v[82:85], v[18:21], v[50:53], v[82:85]
	ds_read_b128 v[144:147], v157 offset:34848
	v_mfma_f32_16x16x32_bf16 v[78:81], v[18:21], v[54:57], v[78:81]
	ds_read_b128 v[112:115], v107 offset:34848
	v_mfma_f32_16x16x32_bf16 v[74:77], v[26:29], v[38:41], v[74:77]
	ds_read_b128 v[148:151], v157 offset:36896
	v_mfma_f32_16x16x32_bf16 v[70:73], v[26:29], v[46:49], v[70:73]
	ds_read_b128 v[152:155], v157 offset:38944
	v_mfma_f32_16x16x32_bf16 v[66:69], v[26:29], v[50:53], v[66:69]
	ds_read_b128 v[116:119], v107 offset:36896
	v_mfma_f32_16x16x32_bf16 v[62:65], v[26:29], v[54:57], v[62:65]
	ds_read_b128 v[136:139], v107 offset:38944
	v_mfma_f32_16x16x32_bf16 v[58:61], v[30:33], v[38:41], v[58:61]
	v_mfma_f32_16x16x32_bf16 v[42:45], v[30:33], v[46:49], v[42:45]
	v_mfma_f32_16x16x32_bf16 v[22:25], v[30:33], v[50:53], v[22:25]
	v_mfma_f32_16x16x32_bf16 v[14:17], v[30:33], v[54:57], v[14:17]
	v_mfma_f32_16x16x32_bf16 v[10:13], v[34:37], v[38:41], v[10:13]
	v_mfma_f32_16x16x32_bf16 v[6:9], v[34:37], v[46:49], v[6:9]
	v_mfma_f32_16x16x32_bf16 v[2:5], v[34:37], v[50:53], v[2:5]
	v_mfma_f32_16x16x32_bf16 v[86:89], v[34:37], v[54:57], v[86:89]
	s_waitcnt lgkmcnt(0)
	s_waitcnt vmcnt(0)
	s_add_u32 s30, s30, 1
	s_cmp_lt_u32 s30, 7
	s_cbranch_scc1 .Lk_outl1_loop
	s_barrier
	s_add_u32 m0, s31, 32768
	v_mfma_f32_16x16x32_bf16 v[94:97], v[108:111], v[140:143], v[94:97]
	ds_read_b128 v[18:21], v98 offset:32
	global_load_lds_dwordx4 v158, s[14:15] offset:0
	v_mfma_f32_16x16x32_bf16 v[90:93], v[108:111], v[144:147], v[90:93]
	ds_read_b128 v[38:41], v156 offset:32
	global_load_lds_dwordx4 v159, s[14:15] offset:1024
	v_mfma_f32_16x16x32_bf16 v[82:85], v[108:111], v[148:151], v[82:85]
	ds_read_b128 v[46:49], v156 offset:2080
	global_load_lds_dwordx4 v160, s[14:15] offset:2048
	v_mfma_f32_16x16x32_bf16 v[78:81], v[108:111], v[152:155], v[78:81]
	ds_read_b128 v[26:29], v98 offset:2080
	global_load_lds_dwordx4 v161, s[14:15] offset:3072
	s_add_u32 m0, s31, 49152
	v_mfma_f32_16x16x32_bf16 v[74:77], v[112:115], v[140:143], v[74:77]
	ds_read_b128 v[50:53], v156 offset:4128
	global_load_lds_dwordx4 v158, s[12:13] offset:0
	v_mfma_f32_16x16x32_bf16 v[70:73], v[112:115], v[144:147], v[70:73]
	ds_read_b128 v[54:57], v156 offset:6176
	global_load_lds_dwordx4 v159, s[12:13] offset:1024
	v_mfma_f32_16x16x32_bf16 v[66:69], v[112:115], v[148:151], v[66:69]
	ds_read_b128 v[30:33], v98 offset:4128
	global_load_lds_dwordx4 v160, s[12:13] offset:2048
	v_mfma_f32_16x16x32_bf16 v[62:65], v[112:115], v[152:155], v[62:65]
	ds_read_b128 v[34:37], v98 offset:6176
	global_load_lds_dwordx4 v161, s[12:13] offset:3072
	v_mfma_f32_16x16x32_bf16 v[58:61], v[116:119], v[140:143], v[58:61]
	v_mfma_f32_16x16x32_bf16 v[42:45], v[116:119], v[144:147], v[42:45]
	v_mfma_f32_16x16x32_bf16 v[22:25], v[116:119], v[148:151], v[22:25]
	v_mfma_f32_16x16x32_bf16 v[14:17], v[116:119], v[152:155], v[14:17]
	v_mfma_f32_16x16x32_bf16 v[10:13], v[136:139], v[140:143], v[10:13]
	v_mfma_f32_16x16x32_bf16 v[6:9], v[136:139], v[144:147], v[6:9]
	v_mfma_f32_16x16x32_bf16 v[2:5], v[136:139], v[148:151], v[2:5]
	v_mfma_f32_16x16x32_bf16 v[86:89], v[136:139], v[152:155], v[86:89]
	s_add_u32 s98, s98, 1
	s_and_b32 s98, s98, 15
	s_cmp_eq_u32 s98, 0
	s_cselect_b32 s99, 0x800, 0
	s_add_u32 s14, s14, 0x80
	s_addc_u32 s15, s15, 0
	s_sub_u32 s14, s14, s99
	s_subb_u32 s15, s15, 0
	s_add_u32 s12, s12, 0x80
	s_addc_u32 s13, s13, 0
	s_sub_u32 s12, s12, s99
	s_subb_u32 s13, s13, 0
	s_waitcnt lgkmcnt(0)
	v_mfma_f32_16x16x32_bf16 v[94:97], v[18:21], v[38:41], v[94:97]
	ds_read_b128 v[108:111], v107 offset:32
	v_mfma_f32_16x16x32_bf16 v[90:93], v[18:21], v[46:49], v[90:93]
	ds_read_b128 v[140:143], v157 offset:32
	v_mfma_f32_16x16x32_bf16 v[82:85], v[18:21], v[50:53], v[82:85]
	ds_read_b128 v[144:147], v157 offset:2080
	v_mfma_f32_16x16x32_bf16 v[78:81], v[18:21], v[54:57], v[78:81]
	ds_read_b128 v[112:115], v107 offset:2080
	v_mfma_f32_16x16x32_bf16 v[74:77], v[26:29], v[38:41], v[74:77]
	ds_read_b128 v[148:151], v157 offset:4128
	v_mfma_f32_16x16x32_bf16 v[70:73], v[26:29], v[46:49], v[70:73]
	ds_read_b128 v[152:155], v157 offset:6176
	v_mfma_f32_16x16x32_bf16 v[66:69], v[26:29], v[50:53], v[66:69]
	ds_read_b128 v[116:119], v107 offset:4128
	v_mfma_f32_16x16x32_bf16 v[62:65], v[26:29], v[54:57], v[62:65]
	ds_read_b128 v[136:139], v107 offset:6176
	v_mfma_f32_16x16x32_bf16 v[58:61], v[30:33], v[38:41], v[58:61]
	v_mfma_f32_16x16x32_bf16 v[42:45], v[30:33], v[46:49], v[42:45]
	v_mfma_f32_16x16x32_bf16 v[22:25], v[30:33], v[50:53], v[22:25]
	v_mfma_f32_16x16x32_bf16 v[14:17], v[30:33], v[54:57], v[14:17]
	v_mfma_f32_16x16x32_bf16 v[10:13], v[34:37], v[38:41], v[10:13]
	v_mfma_f32_16x16x32_bf16 v[6:9], v[34:37], v[46:49], v[6:9]
	v_mfma_f32_16x16x32_bf16 v[2:5], v[34:37], v[50:53], v[2:5]
	v_mfma_f32_16x16x32_bf16 v[86:89], v[34:37], v[54:57], v[86:89]
	s_waitcnt lgkmcnt(0)
	s_waitcnt vmcnt(0)
	s_barrier
	v_mfma_f32_16x16x32_bf16 v[94:97], v[108:111], v[140:143], v[94:97]
	ds_read_b128 v[18:21], v98 offset:32800
	v_mfma_f32_16x16x32_bf16 v[90:93], v[108:111], v[144:147], v[90:93]
	ds_read_b128 v[38:41], v156 offset:32800
	v_mfma_f32_16x16x32_bf16 v[82:85], v[108:111], v[148:151], v[82:85]
	ds_read_b128 v[46:49], v156 offset:34848
	v_mfma_f32_16x16x32_bf16 v[78:81], v[108:111], v[152:155], v[78:81]
	ds_read_b128 v[26:29], v98 offset:34848
	v_mfma_f32_16x16x32_bf16 v[74:77], v[112:115], v[140:143], v[74:77]
	ds_read_b128 v[50:53], v156 offset:36896
	v_mfma_f32_16x16x32_bf16 v[70:73], v[112:115], v[144:147], v[70:73]
	ds_read_b128 v[54:57], v156 offset:38944
	v_mfma_f32_16x16x32_bf16 v[66:69], v[112:115], v[148:151], v[66:69]
	ds_read_b128 v[30:33], v98 offset:36896
	v_mfma_f32_16x16x32_bf16 v[62:65], v[112:115], v[152:155], v[62:65]
	ds_read_b128 v[34:37], v98 offset:38944
	v_mfma_f32_16x16x32_bf16 v[58:61], v[116:119], v[140:143], v[58:61]
	v_mfma_f32_16x16x32_bf16 v[42:45], v[116:119], v[144:147], v[42:45]
	v_mfma_f32_16x16x32_bf16 v[22:25], v[116:119], v[148:151], v[22:25]
	v_mfma_f32_16x16x32_bf16 v[14:17], v[116:119], v[152:155], v[14:17]
	v_mfma_f32_16x16x32_bf16 v[10:13], v[136:139], v[140:143], v[10:13]
	v_mfma_f32_16x16x32_bf16 v[6:9], v[136:139], v[144:147], v[6:9]
	v_mfma_f32_16x16x32_bf16 v[2:5], v[136:139], v[148:151], v[2:5]
	v_mfma_f32_16x16x32_bf16 v[86:89], v[136:139], v[152:155], v[86:89]
	s_waitcnt lgkmcnt(0)
	v_mfma_f32_16x16x32_bf16 v[94:97], v[18:21], v[38:41], v[94:97]
	ds_read_b128 v[108:111], v107 offset:32800
	v_mfma_f32_16x16x32_bf16 v[90:93], v[18:21], v[46:49], v[90:93]
	ds_read_b128 v[140:143], v157 offset:32800
	v_mfma_f32_16x16x32_bf16 v[82:85], v[18:21], v[50:53], v[82:85]
	ds_read_b128 v[144:147], v157 offset:34848
	v_mfma_f32_16x16x32_bf16 v[78:81], v[18:21], v[54:57], v[78:81]
	ds_read_b128 v[112:115], v107 offset:34848
	v_mfma_f32_16x16x32_bf16 v[74:77], v[26:29], v[38:41], v[74:77]
	ds_read_b128 v[148:151], v157 offset:36896
	v_mfma_f32_16x16x32_bf16 v[70:73], v[26:29], v[46:49], v[70:73]
	ds_read_b128 v[152:155], v157 offset:38944
	v_mfma_f32_16x16x32_bf16 v[66:69], v[26:29], v[50:53], v[66:69]
	ds_read_b128 v[116:119], v107 offset:36896
	v_mfma_f32_16x16x32_bf16 v[62:65], v[26:29], v[54:57], v[62:65]
	ds_read_b128 v[136:139], v107 offset:38944
	v_mfma_f32_16x16x32_bf16 v[58:61], v[30:33], v[38:41], v[58:61]
	v_mfma_f32_16x16x32_bf16 v[42:45], v[30:33], v[46:49], v[42:45]
	v_mfma_f32_16x16x32_bf16 v[22:25], v[30:33], v[50:53], v[22:25]
	v_mfma_f32_16x16x32_bf16 v[14:17], v[30:33], v[54:57], v[14:17]
	v_mfma_f32_16x16x32_bf16 v[10:13], v[34:37], v[38:41], v[10:13]
	v_mfma_f32_16x16x32_bf16 v[6:9], v[34:37], v[46:49], v[6:9]
	v_mfma_f32_16x16x32_bf16 v[2:5], v[34:37], v[50:53], v[2:5]
	v_mfma_f32_16x16x32_bf16 v[86:89], v[34:37], v[54:57], v[86:89]
	s_waitcnt lgkmcnt(0)
	v_mfma_f32_16x16x32_bf16 v[94:97], v[108:111], v[140:143], v[94:97]
	v_mfma_f32_16x16x32_bf16 v[90:93], v[108:111], v[144:147], v[90:93]
	v_mfma_f32_16x16x32_bf16 v[82:85], v[108:111], v[148:151], v[82:85]
	v_mfma_f32_16x16x32_bf16 v[78:81], v[108:111], v[152:155], v[78:81]
	v_mfma_f32_16x16x32_bf16 v[74:77], v[112:115], v[140:143], v[74:77]
	v_mfma_f32_16x16x32_bf16 v[70:73], v[112:115], v[144:147], v[70:73]
	v_mfma_f32_16x16x32_bf16 v[66:69], v[112:115], v[148:151], v[66:69]
	v_mfma_f32_16x16x32_bf16 v[62:65], v[112:115], v[152:155], v[62:65]
	v_mfma_f32_16x16x32_bf16 v[58:61], v[116:119], v[140:143], v[58:61]
	v_mfma_f32_16x16x32_bf16 v[42:45], v[116:119], v[144:147], v[42:45]
	v_mfma_f32_16x16x32_bf16 v[22:25], v[116:119], v[148:151], v[22:25]
	v_mfma_f32_16x16x32_bf16 v[14:17], v[116:119], v[152:155], v[14:17]
	v_mfma_f32_16x16x32_bf16 v[10:13], v[136:139], v[140:143], v[10:13]
	v_mfma_f32_16x16x32_bf16 v[6:9], v[136:139], v[144:147], v[6:9]
	v_mfma_f32_16x16x32_bf16 v[2:5], v[136:139], v[148:151], v[2:5]
	v_mfma_f32_16x16x32_bf16 v[86:89], v[136:139], v[152:155], v[86:89]
	s_waitcnt vmcnt(7)
	v_add_u32_e32 v18, 0x400, v123
	s_barrier
	ds_write2_b32 v123, v94, v90 offset1:16
	ds_write2_b32 v123, v95, v91 offset0:132 offset1:148
	ds_write2_b32 v18, v96, v92 offset0:8 offset1:24
	ds_write2_b32 v18, v97, v93 offset0:140 offset1:156
	ds_write2_b32 v123, v82, v78 offset0:32 offset1:48
	ds_write2_b32 v123, v83, v79 offset0:164 offset1:180
	ds_write2_b32 v18, v84, v80 offset0:40 offset1:56
	ds_write2_b32 v18, v85, v81 offset0:172 offset1:188
	v_add_u32_e32 v18, 0x2000, v123
	v_add_u32_e32 v19, 0x2400, v123
	ds_write2_b32 v18, v74, v70 offset0:64 offset1:80
	ds_write2_b32 v18, v75, v71 offset0:196 offset1:212
	ds_write2_b32 v19, v76, v72 offset0:72 offset1:88
	ds_write2_b32 v19, v77, v73 offset0:204 offset1:220
	ds_write2_b32 v18, v66, v62 offset0:96 offset1:112
	ds_write2_b32 v18, v67, v63 offset0:228 offset1:244
	ds_write2_b32 v19, v68, v64 offset0:104 offset1:120
	ds_write2_b32 v19, v69, v65 offset0:236 offset1:252
	v_add_u32_e32 v18, 0x4000, v123
	v_add_u32_e32 v19, 0x4400, v123
	v_add_u32_e32 v20, 0x4800, v123
	ds_write2_b32 v18, v58, v42 offset0:128 offset1:144
	ds_write2_b32 v19, v59, v43 offset0:4 offset1:20
	ds_write2_b32 v19, v60, v44 offset0:136 offset1:152
	ds_write2_b32 v20, v61, v45 offset0:12 offset1:28
	ds_write2_b32 v18, v22, v14 offset0:160 offset1:176
	ds_write2_b32 v19, v23, v15 offset0:36 offset1:52
	ds_write2_b32 v19, v24, v16 offset0:168 offset1:184
	ds_write2_b32 v20, v25, v17 offset0:44 offset1:60
	v_add_u32_e32 v14, 0x6000, v123
	ds_write2_b32 v14, v10, v6 offset0:192 offset1:208
	v_add_u32_e32 v6, 0x6400, v123
	ds_write2_b32 v6, v11, v7 offset0:68 offset1:84
	ds_write2_b32 v6, v12, v8 offset0:200 offset1:216
	v_add_u32_e32 v7, 0x6800, v123
	s_lshl_b32 s2, s29, 9
	ds_write2_b32 v7, v13, v9 offset0:76 offset1:92
	ds_write2_b32 v14, v2, v86 offset0:224 offset1:240
	ds_write2_b32 v6, v3, v87 offset0:100 offset1:116
	ds_write2_b32 v6, v4, v88 offset0:232 offset1:248
	ds_write2_b32 v7, v5, v89 offset0:108 offset1:124
	v_lshl_add_u64 v[2:3], v[100:101], 0, s[2:3]
	v_lshl_add_u64 v[4:5], v[102:103], 0, s[2:3]
	s_lshl_b32 s2, s28, 10
	s_mul_hi_u32 s12, s28, 0x15555556
	s_lshl_b32 s13, s29, 7
	v_or_b32_e32 v6, s2, v125
	s_mulk_i32 s12, 0x3000
	v_or_b32_e32 v7, s2, v127
	v_or_b32_e32 v8, s2, v129
	v_or_b32_e32 v9, s2, v133
	v_subrev_u32_e32 v6, s12, v6
	v_subrev_u32_e32 v7, s12, v7
	v_subrev_u32_e32 v8, s12, v8
	v_subrev_u32_e32 v9, s12, v9
	s_mov_b32 s12, 0
	s_lshl_b32 s2, s13, 2
	v_mov_b32_e32 v10, v132
	v_mov_b32_e32 v11, v128
	v_mov_b32_e32 v12, v126
	v_mov_b32_e32 v13, v124
	s_waitcnt lgkmcnt(0)
	s_barrier

.LBB0_1496:
	s_lshl_b32 s10, s50, 7
	s_or_b32 s46, s37, s10
	s_xor_b64 s[48:49], s[52:53], -1
	s_lshl_b64 s[52:53], s[46:47], 11
	s_add_u32 s52, s55, s52
	s_addc_u32 s53, s56, s53
	s_waitcnt lgkmcnt(0)
	s_lshl_b32 s98, s36, 11
	s_add_u32 s98, s33, s98
	s_addc_u32 s99, s54, 0
	v_and_b32_e32 v212, 15, v0
	v_bfe_u32 v213, v0, 4, 2
	v_and_b32_e32 v139, 7, v212
	v_xor_b32_e32 v213, v213, v139
	v_lshlrev_b32_e32 v213, 4, v213
	v_lshl_or_b32 v213, v212, 7, v213
	v_bfe_u32 v212, v0, 7, 1
	v_lshl_or_b32 v138, v212, 13, v213
	v_bfe_u32 v212, v0, 6, 1
	v_lshl_or_b32 v206, v212, 13, v213
	v_or_b32_e32 v206, 0x4000, v206
	v_xor_b32_e32 v139, 64, v138
	v_xor_b32_e32 v207, 64, v206
	v_bfe_u32 v212, v0, 3, 3
	v_and_b32_e32 v213, 7, v0
	v_xor_b32_e32 v213, v213, v212
	v_lshlrev_b32_e32 v213, 4, v213
	v_lshl_or_b32 v213, v212, 11, v213
	v_lshrrev_b32_e32 v212, 6, v0
	v_and_b32_e32 v212, 3, v212
	v_lshl_or_b32 v208, v212, 16, v213
	v_add_u32_e32 v209, 0x3c00, v208
	v_add_u32_e32 v210, 0x7800, v208
	v_add_u32_e32 v211, 0xb400, v208
	v_lshlrev_b32_e32 v212, 12, v212
	s_nop 0
	v_readfirstlane_b32 s101, v212
	s_add_u32 s101, s101, 32
	v_mov_b32_e32 v66, 0
	v_mov_b32_e32 v67, 0
	v_mov_b32_e32 v68, 0
	v_mov_b32_e32 v69, 0
	v_mov_b32_e32 v58, 0
	v_mov_b32_e32 v59, 0
	v_mov_b32_e32 v60, 0
	v_mov_b32_e32 v61, 0
	v_mov_b32_e32 v54, 0
	v_mov_b32_e32 v55, 0
	v_mov_b32_e32 v56, 0
	v_mov_b32_e32 v57, 0
	v_mov_b32_e32 v50, 0
	v_mov_b32_e32 v51, 0
	v_mov_b32_e32 v52, 0
	v_mov_b32_e32 v53, 0
	v_mov_b32_e32 v46, 0
	v_mov_b32_e32 v47, 0
	v_mov_b32_e32 v48, 0
	v_mov_b32_e32 v49, 0
	v_mov_b32_e32 v42, 0
	v_mov_b32_e32 v43, 0
	v_mov_b32_e32 v44, 0
	v_mov_b32_e32 v45, 0
	v_mov_b32_e32 v38, 0
	v_mov_b32_e32 v39, 0
	v_mov_b32_e32 v40, 0
	v_mov_b32_e32 v41, 0
	v_mov_b32_e32 v6, 0
	v_mov_b32_e32 v7, 0
	v_mov_b32_e32 v8, 0
	v_mov_b32_e32 v9, 0
	v_mov_b32_e32 v2, 0
	v_mov_b32_e32 v3, 0
	v_mov_b32_e32 v4, 0
	v_mov_b32_e32 v5, 0
	v_mov_b32_e32 v22, 0
	v_mov_b32_e32 v23, 0
	v_mov_b32_e32 v24, 0
	v_mov_b32_e32 v25, 0
	v_mov_b32_e32 v18, 0
	v_mov_b32_e32 v19, 0
	v_mov_b32_e32 v20, 0
	v_mov_b32_e32 v21, 0
	v_mov_b32_e32 v14, 0
	v_mov_b32_e32 v15, 0
	v_mov_b32_e32 v16, 0
	v_mov_b32_e32 v17, 0
	v_mov_b32_e32 v10, 0
	v_mov_b32_e32 v11, 0
	v_mov_b32_e32 v12, 0
	v_mov_b32_e32 v13, 0
	v_mov_b32_e32 v34, 0
	v_mov_b32_e32 v35, 0
	v_mov_b32_e32 v36, 0
	v_mov_b32_e32 v37, 0
	v_mov_b32_e32 v30, 0
	v_mov_b32_e32 v31, 0
	v_mov_b32_e32 v32, 0
	v_mov_b32_e32 v33, 0
	v_mov_b32_e32 v26, 0
	v_mov_b32_e32 v27, 0
	v_mov_b32_e32 v28, 0
	v_mov_b32_e32 v29, 0
	v_mov_b32_e32 v134, 0
	v_mov_b32_e32 v135, 0
	v_mov_b32_e32 v136, 0
	v_mov_b32_e32 v137, 0
	v_mov_b32_e32 v178, 0
	v_mov_b32_e32 v179, 0
	v_mov_b32_e32 v180, 0
	v_mov_b32_e32 v181, 0
	v_mov_b32_e32 v182, 0
	v_mov_b32_e32 v183, 0
	v_mov_b32_e32 v184, 0
	v_mov_b32_e32 v185, 0
	v_mov_b32_e32 v186, 0
	v_mov_b32_e32 v187, 0
	v_mov_b32_e32 v188, 0
	v_mov_b32_e32 v189, 0
	v_mov_b32_e32 v190, 0
	v_mov_b32_e32 v191, 0
	v_mov_b32_e32 v192, 0
	v_mov_b32_e32 v193, 0
	v_mov_b32_e32 v194, 0
	v_mov_b32_e32 v195, 0
	v_mov_b32_e32 v196, 0
	v_mov_b32_e32 v197, 0
	v_mov_b32_e32 v198, 0
	v_mov_b32_e32 v199, 0
	v_mov_b32_e32 v200, 0
	v_mov_b32_e32 v201, 0
	v_mov_b32_e32 v202, 0
	v_mov_b32_e32 v203, 0
	v_mov_b32_e32 v204, 0
	v_mov_b32_e32 v205, 0
	s_waitcnt lgkmcnt(0)
	s_barrier
	v_readlane_b32 s46, v255, 16
	s_lshr_b32 s46, s46, 3
	s_and_b32 s46, s46, 3
	s_lshl_b32 s46, s46, 2
	s_lshl_b32 s51, s46, 7
	s_add_u32 s98, s98, s51
	s_addc_u32 s99, s99, 0
	s_add_u32 s52, s52, s51
	s_addc_u32 s53, s53, 0
	s_add_u32 m0, s101, 0
	s_nop 0
	global_load_lds_dwordx4 v208, s[98:99] offset:0
	global_load_lds_dwordx4 v209, s[98:99] offset:1024
	global_load_lds_dwordx4 v210, s[98:99] offset:2048
	global_load_lds_dwordx4 v211, s[98:99] offset:3072
	s_add_u32 m0, s101, 16384
	s_nop 0
	global_load_lds_dwordx4 v208, s[52:53] offset:0
	global_load_lds_dwordx4 v209, s[52:53] offset:1024
	global_load_lds_dwordx4 v210, s[52:53] offset:2048
	global_load_lds_dwordx4 v211, s[52:53] offset:3072
	s_add_u32 s46, s46, 1
	s_and_b32 s46, s46, 15
	s_cmp_eq_u32 s46, 0
	s_cselect_b32 s51, 0x800, 0
	s_add_u32 s98, s98, 0x80
	s_addc_u32 s99, s99, 0
	s_sub_u32 s98, s98, s51
	s_subb_u32 s99, s99, 0
	s_add_u32 s52, s52, 0x80
	s_addc_u32 s53, s53, 0
	s_sub_u32 s52, s52, s51
	s_subb_u32 s53, s53, 0
	s_mov_b32 s100, 0
	s_waitcnt vmcnt(0)
.Lk_pq1_loop:
	s_barrier
	s_add_u32 m0, s101, 32768
	v_mfma_f32_16x16x32_bf16 v[66:69], v[134:137], v[190:193], v[66:69]
	ds_read_b128 v[62:65], v138 offset:32
	global_load_lds_dwordx4 v208, s[98:99] offset:0
	v_mfma_f32_16x16x32_bf16 v[58:61], v[134:137], v[194:197], v[58:61]
	ds_read_b128 v[82:85], v206 offset:32
	global_load_lds_dwordx4 v209, s[98:99] offset:1024
	v_mfma_f32_16x16x32_bf16 v[54:57], v[134:137], v[198:201], v[54:57]
	ds_read_b128 v[86:89], v206 offset:2080
	global_load_lds_dwordx4 v210, s[98:99] offset:2048
	v_mfma_f32_16x16x32_bf16 v[50:53], v[134:137], v[202:205], v[50:53]
	ds_read_b128 v[70:73], v138 offset:2080
	global_load_lds_dwordx4 v211, s[98:99] offset:3072
	s_add_u32 m0, s101, 49152
	v_mfma_f32_16x16x32_bf16 v[46:49], v[178:181], v[190:193], v[46:49]
	ds_read_b128 v[90:93], v206 offset:4128
	global_load_lds_dwordx4 v208, s[52:53] offset:0
	v_mfma_f32_16x16x32_bf16 v[42:45], v[178:181], v[194:197], v[42:45]
	ds_read_b128 v[94:97], v206 offset:6176
	global_load_lds_dwordx4 v209, s[52:53] offset:1024
	v_mfma_f32_16x16x32_bf16 v[38:41], v[178:181], v[198:201], v[38:41]
	ds_read_b128 v[74:77], v138 offset:4128
	global_load_lds_dwordx4 v210, s[52:53] offset:2048
	v_mfma_f32_16x16x32_bf16 v[6:9], v[178:181], v[202:205], v[6:9]
	ds_read_b128 v[78:81], v138 offset:6176
	global_load_lds_dwordx4 v211, s[52:53] offset:3072
	v_mfma_f32_16x16x32_bf16 v[2:5], v[182:185], v[190:193], v[2:5]
	v_mfma_f32_16x16x32_bf16 v[22:25], v[182:185], v[194:197], v[22:25]
	v_mfma_f32_16x16x32_bf16 v[18:21], v[182:185], v[198:201], v[18:21]
	v_mfma_f32_16x16x32_bf16 v[14:17], v[182:185], v[202:205], v[14:17]
	v_mfma_f32_16x16x32_bf16 v[10:13], v[186:189], v[190:193], v[10:13]
	v_mfma_f32_16x16x32_bf16 v[34:37], v[186:189], v[194:197], v[34:37]
	v_mfma_f32_16x16x32_bf16 v[30:33], v[186:189], v[198:201], v[30:33]
	v_mfma_f32_16x16x32_bf16 v[26:29], v[186:189], v[202:205], v[26:29]
	s_add_u32 s46, s46, 1
	s_and_b32 s46, s46, 15
	s_cmp_eq_u32 s46, 0
	s_cselect_b32 s51, 0x800, 0
	s_add_u32 s98, s98, 0x80
	s_addc_u32 s99, s99, 0
	s_sub_u32 s98, s98, s51
	s_subb_u32 s99, s99, 0
	s_add_u32 s52, s52, 0x80
	s_addc_u32 s53, s53, 0
	s_sub_u32 s52, s52, s51
	s_subb_u32 s53, s53, 0
	s_waitcnt lgkmcnt(0)
	v_mfma_f32_16x16x32_bf16 v[66:69], v[62:65], v[82:85], v[66:69]
	ds_read_b128 v[134:137], v139 offset:32
	v_mfma_f32_16x16x32_bf16 v[58:61], v[62:65], v[86:89], v[58:61]
	ds_read_b128 v[190:193], v207 offset:32
	v_mfma_f32_16x16x32_bf16 v[54:57], v[62:65], v[90:93], v[54:57]
	ds_read_b128 v[194:197], v207 offset:2080
	v_mfma_f32_16x16x32_bf16 v[50:53], v[62:65], v[94:97], v[50:53]
	ds_read_b128 v[178:181], v139 offset:2080
	v_mfma_f32_16x16x32_bf16 v[46:49], v[70:73], v[82:85], v[46:49]
	ds_read_b128 v[198:201], v207 offset:4128
	v_mfma_f32_16x16x32_bf16 v[42:45], v[70:73], v[86:89], v[42:45]
	ds_read_b128 v[202:205], v207 offset:6176
	v_mfma_f32_16x16x32_bf16 v[38:41], v[70:73], v[90:93], v[38:41]
	ds_read_b128 v[182:185], v139 offset:4128
	v_mfma_f32_16x16x32_bf16 v[6:9], v[70:73], v[94:97], v[6:9]
	ds_read_b128 v[186:189], v139 offset:6176
	v_mfma_f32_16x16x32_bf16 v[2:5], v[74:77], v[82:85], v[2:5]
	v_mfma_f32_16x16x32_bf16 v[22:25], v[74:77], v[86:89], v[22:25]
	v_mfma_f32_16x16x32_bf16 v[18:21], v[74:77], v[90:93], v[18:21]
	v_mfma_f32_16x16x32_bf16 v[14:17], v[74:77], v[94:97], v[14:17]
	v_mfma_f32_16x16x32_bf16 v[10:13], v[78:81], v[82:85], v[10:13]
	v_mfma_f32_16x16x32_bf16 v[34:37], v[78:81], v[86:89], v[34:37]
	v_mfma_f32_16x16x32_bf16 v[30:33], v[78:81], v[90:93], v[30:33]
	v_mfma_f32_16x16x32_bf16 v[26:29], v[78:81], v[94:97], v[26:29]
	s_waitcnt lgkmcnt(0)
	s_waitcnt vmcnt(0)
	s_barrier
	s_add_u32 m0, s101, 0
	v_mfma_f32_16x16x32_bf16 v[66:69], v[134:137], v[190:193], v[66:69]
	ds_read_b128 v[62:65], v138 offset:32800
	global_load_lds_dwordx4 v208, s[98:99] offset:0
	v_mfma_f32_16x16x32_bf16 v[58:61], v[134:137], v[194:197], v[58:61]
	ds_read_b128 v[82:85], v206 offset:32800
	global_load_lds_dwordx4 v209, s[98:99] offset:1024
	v_mfma_f32_16x16x32_bf16 v[54:57], v[134:137], v[198:201], v[54:57]
	ds_read_b128 v[86:89], v206 offset:34848
	global_load_lds_dwordx4 v210, s[98:99] offset:2048
	v_mfma_f32_16x16x32_bf16 v[50:53], v[134:137], v[202:205], v[50:53]
	ds_read_b128 v[70:73], v138 offset:34848
	global_load_lds_dwordx4 v211, s[98:99] offset:3072
	s_add_u32 m0, s101, 16384
	v_mfma_f32_16x16x32_bf16 v[46:49], v[178:181], v[190:193], v[46:49]
	ds_read_b128 v[90:93], v206 offset:36896
	global_load_lds_dwordx4 v208, s[52:53] offset:0
	v_mfma_f32_16x16x32_bf16 v[42:45], v[178:181], v[194:197], v[42:45]
	ds_read_b128 v[94:97], v206 offset:38944
	global_load_lds_dwordx4 v209, s[52:53] offset:1024
	v_mfma_f32_16x16x32_bf16 v[38:41], v[178:181], v[198:201], v[38:41]
	ds_read_b128 v[74:77], v138 offset:36896
	global_load_lds_dwordx4 v210, s[52:53] offset:2048
	v_mfma_f32_16x16x32_bf16 v[6:9], v[178:181], v[202:205], v[6:9]
	ds_read_b128 v[78:81], v138 offset:38944
	global_load_lds_dwordx4 v211, s[52:53] offset:3072
	v_mfma_f32_16x16x32_bf16 v[2:5], v[182:185], v[190:193], v[2:5]
	v_mfma_f32_16x16x32_bf16 v[22:25], v[182:185], v[194:197], v[22:25]
	v_mfma_f32_16x16x32_bf16 v[18:21], v[182:185], v[198:201], v[18:21]
	v_mfma_f32_16x16x32_bf16 v[14:17], v[182:185], v[202:205], v[14:17]
	v_mfma_f32_16x16x32_bf16 v[10:13], v[186:189], v[190:193], v[10:13]
	v_mfma_f32_16x16x32_bf16 v[34:37], v[186:189], v[194:197], v[34:37]
	v_mfma_f32_16x16x32_bf16 v[30:33], v[186:189], v[198:201], v[30:33]
	v_mfma_f32_16x16x32_bf16 v[26:29], v[186:189], v[202:205], v[26:29]
	s_add_u32 s46, s46, 1
	s_and_b32 s46, s46, 15
	s_cmp_eq_u32 s46, 0
	s_cselect_b32 s51, 0x800, 0
	s_add_u32 s98, s98, 0x80
	s_addc_u32 s99, s99, 0
	s_sub_u32 s98, s98, s51
	s_subb_u32 s99, s99, 0
	s_add_u32 s52, s52, 0x80
	s_addc_u32 s53, s53, 0
	s_sub_u32 s52, s52, s51
	s_subb_u32 s53, s53, 0
	s_waitcnt lgkmcnt(0)
	v_mfma_f32_16x16x32_bf16 v[66:69], v[62:65], v[82:85], v[66:69]
	ds_read_b128 v[134:137], v139 offset:32800
	v_mfma_f32_16x16x32_bf16 v[58:61], v[62:65], v[86:89], v[58:61]
	ds_read_b128 v[190:193], v207 offset:32800
	v_mfma_f32_16x16x32_bf16 v[54:57], v[62:65], v[90:93], v[54:57]
	ds_read_b128 v[194:197], v207 offset:34848
	v_mfma_f32_16x16x32_bf16 v[50:53], v[62:65], v[94:97], v[50:53]
	ds_read_b128 v[178:181], v139 offset:34848
	v_mfma_f32_16x16x32_bf16 v[46:49], v[70:73], v[82:85], v[46:49]
	ds_read_b128 v[198:201], v207 offset:36896
	v_mfma_f32_16x16x32_bf16 v[42:45], v[70:73], v[86:89], v[42:45]
	ds_read_b128 v[202:205], v207 offset:38944
	v_mfma_f32_16x16x32_bf16 v[38:41], v[70:73], v[90:93], v[38:41]
	ds_read_b128 v[182:185], v139 offset:36896
	v_mfma_f32_16x16x32_bf16 v[6:9], v[70:73], v[94:97], v[6:9]
	ds_read_b128 v[186:189], v139 offset:38944
	v_mfma_f32_16x16x32_bf16 v[2:5], v[74:77], v[82:85], v[2:5]
	v_mfma_f32_16x16x32_bf16 v[22:25], v[74:77], v[86:89], v[22:25]
	v_mfma_f32_16x16x32_bf16 v[18:21], v[74:77], v[90:93], v[18:21]
	v_mfma_f32_16x16x32_bf16 v[14:17], v[74:77], v[94:97], v[14:17]
	v_mfma_f32_16x16x32_bf16 v[10:13], v[78:81], v[82:85], v[10:13]
	v_mfma_f32_16x16x32_bf16 v[34:37], v[78:81], v[86:89], v[34:37]
	v_mfma_f32_16x16x32_bf16 v[30:33], v[78:81], v[90:93], v[30:33]
	v_mfma_f32_16x16x32_bf16 v[26:29], v[78:81], v[94:97], v[26:29]
	s_waitcnt lgkmcnt(0)
	s_waitcnt vmcnt(0)
	s_add_u32 s100, s100, 1
	s_cmp_lt_u32 s100, 7
	s_cbranch_scc1 .Lk_pq1_loop
	s_barrier
	s_add_u32 m0, s101, 32768
	v_mfma_f32_16x16x32_bf16 v[66:69], v[134:137], v[190:193], v[66:69]
	ds_read_b128 v[62:65], v138 offset:32
	global_load_lds_dwordx4 v208, s[98:99] offset:0
	v_mfma_f32_16x16x32_bf16 v[58:61], v[134:137], v[194:197], v[58:61]
	ds_read_b128 v[82:85], v206 offset:32
	global_load_lds_dwordx4 v209, s[98:99] offset:1024
	v_mfma_f32_16x16x32_bf16 v[54:57], v[134:137], v[198:201], v[54:57]
	ds_read_b128 v[86:89], v206 offset:2080
	global_load_lds_dwordx4 v210, s[98:99] offset:2048
	v_mfma_f32_16x16x32_bf16 v[50:53], v[134:137], v[202:205], v[50:53]
	ds_read_b128 v[70:73], v138 offset:2080
	global_load_lds_dwordx4 v211, s[98:99] offset:3072
	s_add_u32 m0, s101, 49152
	v_mfma_f32_16x16x32_bf16 v[46:49], v[178:181], v[190:193], v[46:49]
	ds_read_b128 v[90:93], v206 offset:4128
	global_load_lds_dwordx4 v208, s[52:53] offset:0
	v_mfma_f32_16x16x32_bf16 v[42:45], v[178:181], v[194:197], v[42:45]
	ds_read_b128 v[94:97], v206 offset:6176
	global_load_lds_dwordx4 v209, s[52:53] offset:1024
	v_mfma_f32_16x16x32_bf16 v[38:41], v[178:181], v[198:201], v[38:41]
	ds_read_b128 v[74:77], v138 offset:4128
	global_load_lds_dwordx4 v210, s[52:53] offset:2048
	v_mfma_f32_16x16x32_bf16 v[6:9], v[178:181], v[202:205], v[6:9]
	ds_read_b128 v[78:81], v138 offset:6176
	global_load_lds_dwordx4 v211, s[52:53] offset:3072
	v_mfma_f32_16x16x32_bf16 v[2:5], v[182:185], v[190:193], v[2:5]
	v_mfma_f32_16x16x32_bf16 v[22:25], v[182:185], v[194:197], v[22:25]
	v_mfma_f32_16x16x32_bf16 v[18:21], v[182:185], v[198:201], v[18:21]
	v_mfma_f32_16x16x32_bf16 v[14:17], v[182:185], v[202:205], v[14:17]
	v_mfma_f32_16x16x32_bf16 v[10:13], v[186:189], v[190:193], v[10:13]
	v_mfma_f32_16x16x32_bf16 v[34:37], v[186:189], v[194:197], v[34:37]
	v_mfma_f32_16x16x32_bf16 v[30:33], v[186:189], v[198:201], v[30:33]
	v_mfma_f32_16x16x32_bf16 v[26:29], v[186:189], v[202:205], v[26:29]
	s_add_u32 s46, s46, 1
	s_and_b32 s46, s46, 15
	s_cmp_eq_u32 s46, 0
	s_cselect_b32 s51, 0x800, 0
	s_add_u32 s98, s98, 0x80
	s_addc_u32 s99, s99, 0
	s_sub_u32 s98, s98, s51
	s_subb_u32 s99, s99, 0
	s_add_u32 s52, s52, 0x80
	s_addc_u32 s53, s53, 0
	s_sub_u32 s52, s52, s51
	s_subb_u32 s53, s53, 0
	s_waitcnt lgkmcnt(0)
	v_mfma_f32_16x16x32_bf16 v[66:69], v[62:65], v[82:85], v[66:69]
	ds_read_b128 v[134:137], v139 offset:32
	v_mfma_f32_16x16x32_bf16 v[58:61], v[62:65], v[86:89], v[58:61]
	ds_read_b128 v[190:193], v207 offset:32
	v_mfma_f32_16x16x32_bf16 v[54:57], v[62:65], v[90:93], v[54:57]
	ds_read_b128 v[194:197], v207 offset:2080
	v_mfma_f32_16x16x32_bf16 v[50:53], v[62:65], v[94:97], v[50:53]
	ds_read_b128 v[178:181], v139 offset:2080
	v_mfma_f32_16x16x32_bf16 v[46:49], v[70:73], v[82:85], v[46:49]
	ds_read_b128 v[198:201], v207 offset:4128
	v_mfma_f32_16x16x32_bf16 v[42:45], v[70:73], v[86:89], v[42:45]
	ds_read_b128 v[202:205], v207 offset:6176
	v_mfma_f32_16x16x32_bf16 v[38:41], v[70:73], v[90:93], v[38:41]
	ds_read_b128 v[182:185], v139 offset:4128
	v_mfma_f32_16x16x32_bf16 v[6:9], v[70:73], v[94:97], v[6:9]
	ds_read_b128 v[186:189], v139 offset:6176
	v_mfma_f32_16x16x32_bf16 v[2:5], v[74:77], v[82:85], v[2:5]
	v_mfma_f32_16x16x32_bf16 v[22:25], v[74:77], v[86:89], v[22:25]
	v_mfma_f32_16x16x32_bf16 v[18:21], v[74:77], v[90:93], v[18:21]
	v_mfma_f32_16x16x32_bf16 v[14:17], v[74:77], v[94:97], v[14:17]
	v_mfma_f32_16x16x32_bf16 v[10:13], v[78:81], v[82:85], v[10:13]
	v_mfma_f32_16x16x32_bf16 v[34:37], v[78:81], v[86:89], v[34:37]
	v_mfma_f32_16x16x32_bf16 v[30:33], v[78:81], v[90:93], v[30:33]
	v_mfma_f32_16x16x32_bf16 v[26:29], v[78:81], v[94:97], v[26:29]
	s_waitcnt lgkmcnt(0)
	s_waitcnt vmcnt(0)
	s_barrier
	v_mfma_f32_16x16x32_bf16 v[66:69], v[134:137], v[190:193], v[66:69]
	ds_read_b128 v[62:65], v138 offset:32800
	v_mfma_f32_16x16x32_bf16 v[58:61], v[134:137], v[194:197], v[58:61]
	ds_read_b128 v[82:85], v206 offset:32800
	v_mfma_f32_16x16x32_bf16 v[54:57], v[134:137], v[198:201], v[54:57]
	ds_read_b128 v[86:89], v206 offset:34848
	v_mfma_f32_16x16x32_bf16 v[50:53], v[134:137], v[202:205], v[50:53]
	ds_read_b128 v[70:73], v138 offset:34848
	v_mfma_f32_16x16x32_bf16 v[46:49], v[178:181], v[190:193], v[46:49]
	ds_read_b128 v[90:93], v206 offset:36896
	v_mfma_f32_16x16x32_bf16 v[42:45], v[178:181], v[194:197], v[42:45]
	ds_read_b128 v[94:97], v206 offset:38944
	v_mfma_f32_16x16x32_bf16 v[38:41], v[178:181], v[198:201], v[38:41]
	ds_read_b128 v[74:77], v138 offset:36896
	v_mfma_f32_16x16x32_bf16 v[6:9], v[178:181], v[202:205], v[6:9]
	ds_read_b128 v[78:81], v138 offset:38944
	v_mfma_f32_16x16x32_bf16 v[2:5], v[182:185], v[190:193], v[2:5]
	v_mfma_f32_16x16x32_bf16 v[22:25], v[182:185], v[194:197], v[22:25]
	v_mfma_f32_16x16x32_bf16 v[18:21], v[182:185], v[198:201], v[18:21]
	v_mfma_f32_16x16x32_bf16 v[14:17], v[182:185], v[202:205], v[14:17]
	v_mfma_f32_16x16x32_bf16 v[10:13], v[186:189], v[190:193], v[10:13]
	v_mfma_f32_16x16x32_bf16 v[34:37], v[186:189], v[194:197], v[34:37]
	v_mfma_f32_16x16x32_bf16 v[30:33], v[186:189], v[198:201], v[30:33]
	v_mfma_f32_16x16x32_bf16 v[26:29], v[186:189], v[202:205], v[26:29]
	s_waitcnt lgkmcnt(0)
	v_mfma_f32_16x16x32_bf16 v[66:69], v[62:65], v[82:85], v[66:69]
	ds_read_b128 v[134:137], v139 offset:32800
	v_mfma_f32_16x16x32_bf16 v[58:61], v[62:65], v[86:89], v[58:61]
	ds_read_b128 v[190:193], v207 offset:32800
	v_mfma_f32_16x16x32_bf16 v[54:57], v[62:65], v[90:93], v[54:57]
	ds_read_b128 v[194:197], v207 offset:34848
	v_mfma_f32_16x16x32_bf16 v[50:53], v[62:65], v[94:97], v[50:53]
	ds_read_b128 v[178:181], v139 offset:34848
	v_mfma_f32_16x16x32_bf16 v[46:49], v[70:73], v[82:85], v[46:49]
	ds_read_b128 v[198:201], v207 offset:36896
	v_mfma_f32_16x16x32_bf16 v[42:45], v[70:73], v[86:89], v[42:45]
	ds_read_b128 v[202:205], v207 offset:38944
	v_mfma_f32_16x16x32_bf16 v[38:41], v[70:73], v[90:93], v[38:41]
	ds_read_b128 v[182:185], v139 offset:36896
	v_mfma_f32_16x16x32_bf16 v[6:9], v[70:73], v[94:97], v[6:9]
	ds_read_b128 v[186:189], v139 offset:38944
	v_mfma_f32_16x16x32_bf16 v[2:5], v[74:77], v[82:85], v[2:5]
	v_mfma_f32_16x16x32_bf16 v[22:25], v[74:77], v[86:89], v[22:25]
	v_mfma_f32_16x16x32_bf16 v[18:21], v[74:77], v[90:93], v[18:21]
	v_mfma_f32_16x16x32_bf16 v[14:17], v[74:77], v[94:97], v[14:17]
	v_mfma_f32_16x16x32_bf16 v[10:13], v[78:81], v[82:85], v[10:13]
	v_mfma_f32_16x16x32_bf16 v[34:37], v[78:81], v[86:89], v[34:37]
	v_mfma_f32_16x16x32_bf16 v[30:33], v[78:81], v[90:93], v[30:33]
	v_mfma_f32_16x16x32_bf16 v[26:29], v[78:81], v[94:97], v[26:29]
	s_waitcnt lgkmcnt(0)
	v_mfma_f32_16x16x32_bf16 v[66:69], v[134:137], v[190:193], v[66:69]
	v_mfma_f32_16x16x32_bf16 v[58:61], v[134:137], v[194:197], v[58:61]
	v_mfma_f32_16x16x32_bf16 v[54:57], v[134:137], v[198:201], v[54:57]
	v_mfma_f32_16x16x32_bf16 v[50:53], v[134:137], v[202:205], v[50:53]
	v_mfma_f32_16x16x32_bf16 v[46:49], v[178:181], v[190:193], v[46:49]
	v_mfma_f32_16x16x32_bf16 v[42:45], v[178:181], v[194:197], v[42:45]
	v_mfma_f32_16x16x32_bf16 v[38:41], v[178:181], v[198:201], v[38:41]
	v_mfma_f32_16x16x32_bf16 v[6:9], v[178:181], v[202:205], v[6:9]
	v_mfma_f32_16x16x32_bf16 v[2:5], v[182:185], v[190:193], v[2:5]
	v_mfma_f32_16x16x32_bf16 v[22:25], v[182:185], v[194:197], v[22:25]
	v_mfma_f32_16x16x32_bf16 v[18:21], v[182:185], v[198:201], v[18:21]
	v_mfma_f32_16x16x32_bf16 v[14:17], v[182:185], v[202:205], v[14:17]
	v_mfma_f32_16x16x32_bf16 v[10:13], v[186:189], v[190:193], v[10:13]
	v_mfma_f32_16x16x32_bf16 v[34:37], v[186:189], v[194:197], v[34:37]
	v_mfma_f32_16x16x32_bf16 v[30:33], v[186:189], v[198:201], v[30:33]
	v_mfma_f32_16x16x32_bf16 v[26:29], v[186:189], v[202:205], v[26:29]
	s_waitcnt vmcnt(2)
	v_cvt_pk_bf16_f32 v62, v66, s0
	s_barrier
	ds_write_b16 v146, v62
	v_cvt_pk_bf16_f32 v62, v67, s0
	v_cvt_pk_bf16_f32 v58, v58, s0
	v_cvt_pk_bf16_f32 v54, v54, s0
	v_cvt_pk_bf16_f32 v50, v50, s0
	v_cvt_pk_bf16_f32 v46, v46, s0
	v_cvt_pk_bf16_f32 v42, v42, s0
	v_cvt_pk_bf16_f32 v38, v38, s0
	ds_write_b16 v146, v62 offset:272
	v_cvt_pk_bf16_f32 v62, v68, s0
	ds_write_b16 v146, v58 offset:32
	v_cvt_pk_bf16_f32 v58, v59, s0
	ds_write_b16 v146, v54 offset:64
	v_cvt_pk_bf16_f32 v54, v55, s0
	ds_write_b16 v146, v50 offset:96
	v_cvt_pk_bf16_f32 v50, v51, s0
	ds_write_b16 v146, v46 offset:4352
	v_cvt_pk_bf16_f32 v46, v47, s0
	ds_write_b16 v146, v42 offset:4384
	v_cvt_pk_bf16_f32 v42, v43, s0
	ds_write_b16 v146, v38 offset:4416
	v_cvt_pk_bf16_f32 v38, v39, s0
	s_mov_b32 s51, s11
	ds_write_b16 v146, v62 offset:544
	v_cvt_pk_bf16_f32 v62, v69, s0
	ds_write_b16 v146, v58 offset:304
	v_cvt_pk_bf16_f32 v58, v60, s0
	ds_write_b16 v146, v54 offset:336
	v_cvt_pk_bf16_f32 v54, v56, s0
	ds_write_b16 v146, v50 offset:368
	v_cvt_pk_bf16_f32 v50, v52, s0
	ds_write_b16 v146, v46 offset:4624
	v_cvt_pk_bf16_f32 v46, v48, s0
	ds_write_b16 v146, v42 offset:4656
	v_cvt_pk_bf16_f32 v42, v44, s0
	ds_write_b16 v146, v38 offset:4688
	v_cvt_pk_bf16_f32 v38, v40, s0
	s_lshl_b64 s[52:53], s[50:51], 15
	ds_write_b16 v146, v62 offset:816
	ds_write_b16 v146, v58 offset:576
	v_cvt_pk_bf16_f32 v58, v61, s0
	ds_write_b16 v146, v54 offset:608
	v_cvt_pk_bf16_f32 v54, v57, s0
	ds_write_b16 v146, v50 offset:640
	v_cvt_pk_bf16_f32 v50, v53, s0
	ds_write_b16 v146, v46 offset:4896
	v_cvt_pk_bf16_f32 v46, v49, s0
	ds_write_b16 v146, v42 offset:4928
	v_cvt_pk_bf16_f32 v42, v45, s0
	ds_write_b16 v146, v38 offset:4960
	v_cvt_pk_bf16_f32 v38, v41, s0
	v_lshl_add_u64 v[62:63], v[100:101], 0, s[52:53]
	v_mov_b32_e32 v105, v99
	v_mov_b32_e32 v107, v99
	v_mov_b32_e32 v109, v99
	v_mov_b32_e32 v111, v99
	v_mov_b32_e32 v113, v99
	v_mov_b32_e32 v115, v99
	v_mov_b32_e32 v117, v99
	ds_write_b16 v146, v58 offset:848
	ds_write_b16 v146, v54 offset:880
	ds_write_b16 v146, v50 offset:912
	ds_write_b16 v146, v46 offset:5168
	ds_write_b16 v146, v42 offset:5200
	ds_write_b16 v146, v38 offset:5232
	v_lshl_add_u64 v[38:39], v[62:63], 0, v[98:99]
	v_lshl_add_u64 v[42:43], v[62:63], 0, v[104:105]
	v_lshl_add_u64 v[46:47], v[62:63], 0, v[106:107]
	v_lshl_add_u64 v[50:51], v[62:63], 0, v[108:109]
	v_lshl_add_u64 v[54:55], v[62:63], 0, v[110:111]
	v_lshl_add_u64 v[58:59], v[62:63], 0, v[112:113]
	v_lshl_add_u64 v[64:65], v[62:63], 0, v[114:115]
	v_lshl_add_u64 v[66:67], v[62:63], 0, v[116:117]
	global_load_dwordx4 v[38:41], v[38:39], off
	s_nop 0
	global_load_dwordx4 v[42:45], v[42:43], off
	s_nop 0
	global_load_dwordx4 v[46:49], v[46:47], off
	s_nop 0
	global_load_dwordx4 v[50:53], v[50:51], off
	s_nop 0
	global_load_dwordx4 v[54:57], v[54:55], off
	s_nop 0
	global_load_dwordx4 v[58:61], v[58:59], off
	s_nop 0
	global_load_dwordx4 v[62:65], v[64:65], off
	s_nop 0
	global_load_dwordx4 v[66:69], v[66:67], off
	v_cvt_pk_bf16_f32 v2, v2, s0
	ds_write_b16 v146, v2 offset:8704
	v_cvt_pk_bf16_f32 v2, v3, s0
	ds_write_b16 v146, v2 offset:8976
	v_cvt_pk_bf16_f32 v2, v4, s0
	ds_write_b16 v146, v2 offset:9248
	v_cvt_pk_bf16_f32 v2, v5, s0
	ds_write_b16 v146, v2 offset:9520
	v_cvt_pk_bf16_f32 v2, v22, s0
	ds_write_b16 v146, v2 offset:8736
	v_cvt_pk_bf16_f32 v2, v23, s0
	ds_write_b16 v146, v2 offset:9008
	v_cvt_pk_bf16_f32 v2, v24, s0
	ds_write_b16 v146, v2 offset:9280
	v_cvt_pk_bf16_f32 v2, v25, s0
	ds_write_b16 v146, v2 offset:9552
	v_cvt_pk_bf16_f32 v2, v18, s0
	ds_write_b16 v146, v2 offset:8768
	v_cvt_pk_bf16_f32 v2, v19, s0
	ds_write_b16 v146, v2 offset:9040
	v_cvt_pk_bf16_f32 v2, v20, s0
	ds_write_b16 v146, v2 offset:9312
	v_cvt_pk_bf16_f32 v2, v21, s0
	ds_write_b16 v146, v2 offset:9584
	v_cvt_pk_bf16_f32 v2, v14, s0
	ds_write_b16 v146, v2 offset:8800
	v_cvt_pk_bf16_f32 v2, v15, s0
	ds_write_b16 v146, v2 offset:9072
	v_cvt_pk_bf16_f32 v2, v16, s0
	ds_write_b16 v146, v2 offset:9344
	v_cvt_pk_bf16_f32 v2, v17, s0
	ds_write_b16 v146, v2 offset:9616
	v_cvt_pk_bf16_f32 v2, v10, s0
	ds_write_b16 v146, v2 offset:13056
	v_cvt_pk_bf16_f32 v2, v11, s0
	ds_write_b16 v146, v2 offset:13328
	v_cvt_pk_bf16_f32 v2, v12, s0
	ds_write_b16 v146, v2 offset:13600
	v_cvt_pk_bf16_f32 v2, v13, s0
	ds_write_b16 v146, v2 offset:13872
	v_cvt_pk_bf16_f32 v2, v34, s0
	ds_write_b16 v146, v2 offset:13088
	v_cvt_pk_bf16_f32 v2, v35, s0
	ds_write_b16 v146, v2 offset:13360
	v_cvt_pk_bf16_f32 v2, v36, s0
	ds_write_b16 v146, v2 offset:13632
	v_cvt_pk_bf16_f32 v2, v37, s0
	ds_write_b16 v146, v2 offset:13904
	v_cvt_pk_bf16_f32 v2, v30, s0
	ds_write_b16 v146, v2 offset:13120
	v_cvt_pk_bf16_f32 v2, v31, s0
	ds_write_b16 v146, v2 offset:13392
	v_cvt_pk_bf16_f32 v2, v32, s0
	ds_write_b16 v146, v2 offset:13664
	v_cvt_pk_bf16_f32 v2, v33, s0
	v_cvt_pk_bf16_f32 v6, v6, s0
	ds_write_b16 v146, v2 offset:13936
	v_cvt_pk_bf16_f32 v2, v26, s0
	ds_write_b16 v146, v6 offset:4448
	v_cvt_pk_bf16_f32 v6, v7, s0
	ds_write_b16 v146, v2 offset:13152
	v_cvt_pk_bf16_f32 v2, v27, s0
	ds_write_b16 v146, v6 offset:4720
	v_cvt_pk_bf16_f32 v6, v8, s0
	ds_write_b16 v146, v2 offset:13424
	v_cvt_pk_bf16_f32 v2, v28, s0
	ds_write_b16 v146, v6 offset:4992
	v_cvt_pk_bf16_f32 v6, v9, s0
	ds_write_b16 v146, v2 offset:13696
	v_cvt_pk_bf16_f32 v2, v29, s0
	ds_write_b16 v146, v6 offset:5264
	ds_write_b16 v146, v2 offset:13968
	s_waitcnt vmcnt(7)
	ds_write_b128 v147, v[38:41]
	s_waitcnt vmcnt(6)
	ds_write_b128 v148, v[42:45]
	s_waitcnt vmcnt(5)
	ds_write_b128 v149, v[46:49]
	s_waitcnt vmcnt(4)
	ds_write_b128 v150, v[50:53]
	s_waitcnt vmcnt(3)
	ds_write_b128 v151, v[54:57]
	s_waitcnt vmcnt(2)
	ds_write_b128 v152, v[58:61]
	s_waitcnt vmcnt(1)
	ds_write_b128 v153, v[62:65]
	s_waitcnt vmcnt(0)
	ds_write_b128 v154, v[66:69]
	s_waitcnt lgkmcnt(0)
	s_barrier
	ds_read_b128 v[2:5], v175
	ds_read_b128 v[6:9], v176 offset:34816
	ds_read_b128 v[10:13], v175 offset:64
	ds_read_b128 v[14:17], v176 offset:34880
	ds_read_b128 v[22:25], v176 offset:39168
	ds_read_b128 v[26:29], v176 offset:39232
	ds_read_b128 v[34:37], v176 offset:43520
	ds_read_b128 v[38:41], v176 offset:43584
	ds_read_b128 v[46:49], v176 offset:47872
	ds_read_b128 v[50:53], v176 offset:47936
	ds_read_b128 v[54:57], v175 offset:4352
	ds_read_b128 v[58:61], v175 offset:4416
	ds_read_b128 v[74:77], v175 offset:8704
	ds_read_b128 v[78:81], v175 offset:8768
	ds_read_b128 v[94:97], v175 offset:13056
	ds_read_b128 v[134:137], v175 offset:13120
	s_waitcnt lgkmcnt(14)
	v_mfma_f32_16x16x32_bf16 v[18:21], v[2:5], v[6:9], 0
	s_lshl_b64 s[50:51], s[50:51], 6
	s_add_u32 s50, s35, s50
	s_addc_u32 s51, s79, s51
	s_waitcnt lgkmcnt(11)
	v_mfma_f32_16x16x32_bf16 v[30:33], v[2:5], v[22:25], 0
	s_mov_b32 s10, 0
	s_waitcnt lgkmcnt(9)
	v_mfma_f32_16x16x32_bf16 v[42:45], v[2:5], v[34:37], 0
	s_waitcnt lgkmcnt(7)
	v_mfma_f32_16x16x32_bf16 v[2:5], v[2:5], v[46:49], 0
	s_waitcnt lgkmcnt(5)
	v_mfma_f32_16x16x32_bf16 v[62:65], v[54:57], v[6:9], 0
	v_mfma_f32_16x16x32_bf16 v[66:69], v[54:57], v[22:25], 0
	v_mfma_f32_16x16x32_bf16 v[70:73], v[54:57], v[34:37], 0
	v_mfma_f32_16x16x32_bf16 v[54:57], v[54:57], v[46:49], 0
	s_waitcnt lgkmcnt(3)
	v_mfma_f32_16x16x32_bf16 v[82:85], v[74:77], v[6:9], 0
	v_mfma_f32_16x16x32_bf16 v[86:89], v[74:77], v[22:25], 0
	s_waitcnt lgkmcnt(1)
	v_mfma_f32_16x16x32_bf16 v[6:9], v[94:97], v[6:9], 0
	v_mfma_f32_16x16x32_bf16 v[22:25], v[94:97], v[22:25], 0
	v_mfma_f32_16x16x32_bf16 v[18:21], v[10:13], v[14:17], v[18:21]
	v_mfma_f32_16x16x32_bf16 v[30:33], v[10:13], v[26:29], v[30:33]
	v_mfma_f32_16x16x32_bf16 v[42:45], v[10:13], v[38:41], v[42:45]
	v_mfma_f32_16x16x32_bf16 v[2:5], v[10:13], v[50:53], v[2:5]
	v_mfma_f32_16x16x32_bf16 v[10:13], v[58:61], v[14:17], v[62:65]
	v_mfma_f32_16x16x32_bf16 v[62:65], v[58:61], v[26:29], v[66:69]
	v_mfma_f32_16x16x32_bf16 v[66:69], v[58:61], v[38:41], v[70:73]
	v_mfma_f32_16x16x32_bf16 v[54:57], v[58:61], v[50:53], v[54:57]
	v_mfma_f32_16x16x32_bf16 v[58:61], v[78:81], v[14:17], v[82:85]
	v_mfma_f32_16x16x32_bf16 v[70:73], v[78:81], v[26:29], v[86:89]
	s_waitcnt lgkmcnt(0)
	v_mfma_f32_16x16x32_bf16 v[6:9], v[134:137], v[14:17], v[6:9]
	v_mfma_f32_16x16x32_bf16 v[14:17], v[134:137], v[26:29], v[22:25]
	ds_read_b128 v[26:29], v175 offset:128
	v_mfma_f32_16x16x32_bf16 v[90:93], v[74:77], v[34:37], 0
	v_mfma_f32_16x16x32_bf16 v[74:77], v[74:77], v[46:49], 0
	v_mfma_f32_16x16x32_bf16 v[34:37], v[94:97], v[34:37], 0
	v_mfma_f32_16x16x32_bf16 v[46:49], v[94:97], v[46:49], 0
	v_mfma_f32_16x16x32_bf16 v[82:85], v[78:81], v[38:41], v[90:93]
	v_mfma_f32_16x16x32_bf16 v[74:77], v[78:81], v[50:53], v[74:77]
	v_mfma_f32_16x16x32_bf16 v[22:25], v[134:137], v[38:41], v[34:37]
	v_mfma_f32_16x16x32_bf16 v[34:37], v[134:137], v[50:53], v[46:49]
	ds_read_b128 v[38:41], v176 offset:34944
	s_nop 2
	ds_read_b128 v[46:49], v175 offset:192
	ds_read_b128 v[50:53], v176 offset:35008
	ds_read_b128 v[78:81], v176 offset:39296
	ds_read_b128 v[86:89], v176 offset:39360
	ds_read_b128 v[90:93], v176 offset:43648
	ds_read_b128 v[94:97], v176 offset:43712
	ds_read_b128 v[134:137], v176 offset:48000
	ds_read_b128 v[178:181], v176 offset:48064
	s_waitcnt lgkmcnt(8)
	v_mfma_f32_16x16x32_bf16 v[18:21], v[26:29], v[38:41], v[18:21]
	s_waitcnt lgkmcnt(5)
	v_mfma_f32_16x16x32_bf16 v[30:33], v[26:29], v[78:81], v[30:33]
	s_waitcnt lgkmcnt(3)
	v_mfma_f32_16x16x32_bf16 v[42:45], v[26:29], v[90:93], v[42:45]
	s_waitcnt lgkmcnt(1)
	v_mfma_f32_16x16x32_bf16 v[2:5], v[26:29], v[134:137], v[2:5]
	ds_read_b128 v[26:29], v175 offset:4480
	ds_read_b128 v[182:185], v175 offset:4544
	s_waitcnt lgkmcnt(1)
	v_mfma_f32_16x16x32_bf16 v[10:13], v[26:29], v[38:41], v[10:13]
	v_mfma_f32_16x16x32_bf16 v[62:65], v[26:29], v[78:81], v[62:65]
	v_mfma_f32_16x16x32_bf16 v[66:69], v[26:29], v[90:93], v[66:69]
	v_mfma_f32_16x16x32_bf16 v[26:29], v[26:29], v[134:137], v[54:57]
	s_nop 2
	ds_read_b128 v[54:57], v175 offset:8832
	ds_read_b128 v[186:189], v175 offset:8896
	s_waitcnt lgkmcnt(1)
	v_mfma_f32_16x16x32_bf16 v[58:61], v[54:57], v[38:41], v[58:61]
	v_mfma_f32_16x16x32_bf16 v[70:73], v[54:57], v[78:81], v[70:73]
	v_mfma_f32_16x16x32_bf16 v[82:85], v[54:57], v[90:93], v[82:85]
	v_mfma_f32_16x16x32_bf16 v[54:57], v[54:57], v[134:137], v[74:77]
	s_nop 2
	ds_read_b128 v[74:77], v175 offset:13184
	ds_read_b128 v[190:193], v175 offset:13248
	s_waitcnt lgkmcnt(0)
	s_barrier
	v_mfma_f32_16x16x32_bf16 v[6:9], v[74:77], v[38:41], v[6:9]
	v_mfma_f32_16x16x32_bf16 v[14:17], v[74:77], v[78:81], v[14:17]
	v_mfma_f32_16x16x32_bf16 v[18:21], v[46:49], v[50:53], v[18:21]
	v_mfma_f32_16x16x32_bf16 v[30:33], v[46:49], v[86:89], v[30:33]
	s_nop 7
	ds_write2_b32 v145, v18, v30 offset1:16
	ds_write2_b32 v145, v19, v31 offset0:132 offset1:148
	v_mfma_f32_16x16x32_bf16 v[22:25], v[74:77], v[90:93], v[22:25]
	v_add_u32_e32 v18, 0x400, v145
	v_mfma_f32_16x16x32_bf16 v[34:37], v[74:77], v[134:137], v[34:37]
	v_mfma_f32_16x16x32_bf16 v[38:41], v[46:49], v[94:97], v[42:45]
	v_mfma_f32_16x16x32_bf16 v[10:13], v[182:185], v[50:53], v[10:13]
	v_mfma_f32_16x16x32_bf16 v[42:45], v[182:185], v[86:89], v[62:65]
	v_mfma_f32_16x16x32_bf16 v[2:5], v[46:49], v[178:181], v[2:5]
	ds_write2_b32 v18, v20, v32 offset0:8 offset1:24
	ds_write2_b32 v18, v21, v33 offset0:140 offset1:156
	s_nop 5
	ds_write2_b32 v145, v38, v2 offset0:32 offset1:48
	ds_write2_b32 v145, v39, v3 offset0:164 offset1:180
	ds_write2_b32 v18, v40, v4 offset0:40 offset1:56
	ds_write2_b32 v18, v41, v5 offset0:172 offset1:188
	v_add_u32_e32 v2, 0x2000, v145
	v_mfma_f32_16x16x32_bf16 v[58:61], v[186:189], v[50:53], v[58:61]
	v_add_u32_e32 v3, 0x2400, v145
	ds_write2_b32 v2, v10, v42 offset0:64 offset1:80
	ds_write2_b32 v2, v11, v43 offset0:196 offset1:212
	v_add_u32_e32 v4, 0x4800, v145
	v_mfma_f32_16x16x32_bf16 v[62:65], v[186:189], v[86:89], v[70:73]
	v_mfma_f32_16x16x32_bf16 v[46:49], v[182:185], v[94:97], v[66:69]
	v_mfma_f32_16x16x32_bf16 v[26:29], v[182:185], v[178:181], v[26:29]
	ds_write2_b32 v3, v12, v44 offset0:72 offset1:88
	ds_write2_b32 v3, v13, v45 offset0:204 offset1:220
	s_nop 5
	ds_write2_b32 v2, v46, v26 offset0:96 offset1:112
	ds_write2_b32 v2, v47, v27 offset0:228 offset1:244
	ds_write2_b32 v3, v48, v28 offset0:104 offset1:120
	ds_write2_b32 v3, v49, v29 offset0:236 offset1:252
	v_add_u32_e32 v2, 0x4000, v145
	v_mfma_f32_16x16x32_bf16 v[66:69], v[186:189], v[94:97], v[82:85]
	v_add_u32_e32 v3, 0x4400, v145
	ds_write2_b32 v2, v58, v62 offset0:128 offset1:144
	ds_write2_b32 v3, v59, v63 offset0:4 offset1:20
	ds_write2_b32 v3, v60, v64 offset0:136 offset1:152
	v_mfma_f32_16x16x32_bf16 v[54:57], v[186:189], v[178:181], v[54:57]
	ds_write2_b32 v4, v61, v65 offset0:12 offset1:28
	s_nop 6
	ds_write2_b32 v2, v66, v54 offset0:160 offset1:176
	ds_write2_b32 v3, v67, v55 offset0:36 offset1:52
	ds_write2_b32 v3, v68, v56 offset0:168 offset1:184
	ds_write2_b32 v4, v69, v57 offset0:44 offset1:60
	v_mfma_f32_16x16x32_bf16 v[6:9], v[190:193], v[50:53], v[6:9]
	v_add_u32_e32 v2, 0x6000, v145
	v_add_u32_e32 v3, 0x6400, v145
	v_add_u32_e32 v4, 0x6800, v145
	v_mfma_f32_16x16x32_bf16 v[14:17], v[190:193], v[86:89], v[14:17]
	v_mfma_f32_16x16x32_bf16 v[22:25], v[190:193], v[94:97], v[22:25]
	v_mfma_f32_16x16x32_bf16 v[34:37], v[190:193], v[178:181], v[34:37]
	s_nop 5
	ds_write2_b32 v2, v6, v14 offset0:192 offset1:208
	ds_write2_b32 v3, v7, v15 offset0:68 offset1:84
	ds_write2_b32 v3, v8, v16 offset0:200 offset1:216
	ds_write2_b32 v4, v9, v17 offset0:76 offset1:92
	ds_write2_b32 v2, v22, v34 offset0:224 offset1:240
	ds_write2_b32 v3, v23, v35 offset0:100 offset1:116
	ds_write2_b32 v3, v24, v36 offset0:232 offset1:248
	ds_write2_b32 v4, v25, v37 offset0:108 offset1:124
	v_mov_b32_e32 v2, v177
	s_waitcnt lgkmcnt(0)
	s_barrier
	s_branch .LBB0_1500
